# P1 column-tile rotation (spreads expensive nt>=42 tiles over all workgroups), hand-written P1 main loop (3-deep register prefetch), next-job L2 prefetch in top-k, scans with 16-B LDS reads
# speedup vs baseline: 1.0939x; 1.0212x over previous
; DI void inproj_tile(const Params& p, int l, int mt, int nt, char* lds) {
;     ...
;   const int m0 = mt * 256;
;   const u16* A = p.Xb + (size_t)m0 * DM;
;   const u16* Bw = p.Wt_in + (size_t)(l & 1) * NIN * DM + (size_t)nt * 128 * DM;
; __global__ void __launch_bounds__(NTHREADS) mega(Params p) {
;     ...
;     for (int rep = 0; rep < REP_P1; ++rep) {
;       for (int j = blockIdx.x; j < 66 * 48; j += gridDim.x) inproj_tile(p, l, j / 48, j % 48, lds);
.LBB0_320:
	v_readlane_b32 s0, v240, 17
	v_readlane_b32 s1, v240, 18
	s_andn2_b64 vcc, exec, s[0:1]
	s_lshl_b32 s0, s38, 4
	s_lshl_b32 s50, s38, 3
	v_writelane_b32 v238, s0, 45
	s_nop 1
	v_writelane_b32 v238, s1, 46
	s_cbranch_vccnz .LBB0_370
	s_bitcmp1_b32 s38, 0
	v_readlane_b32 s4, v241, 16
	s_cselect_b32 s0, 0xc00000, 0
	s_add_u32 s18, s4, s0
	v_readlane_b32 s0, v238, 45
	v_readlane_b32 s5, v241, 17
	s_addc_u32 s19, s5, 0
	s_mov_b32 s1, s61
	s_mov_b32 s2, s0
	v_writelane_b32 v238, s2, 45
	s_lshl_b64 s[0:1], s[0:1], 2
	v_readlane_b32 s6, v241, 42
	v_writelane_b32 v238, s3, 46
	v_readlane_b32 s7, v241, 43
	v_readlane_b32 s10, v241, 46
	s_add_u32 s20, s6, s0
	s_addc_u32 s21, s7, s1
	s_lshl_b32 s22, s10, 7
	v_readlane_b32 s25, v238, 16
	s_branch .LBB0_324

; template <bool SWAP, class Epi>
; DI void gemm_tile(const u16* __restrict__ A, int lda, const u16* __restrict__ Bw, int ldb, int K, char* lds, Epi epi) {
;     ...
;   gload(0, ra0, rb0);
;   lstore(0, ra0, rb0);
;   gload(1, ra1, rb1);
;   __syncthreads();
;   for (int kt = 0; kt < nk; kt += 2) {
;     if (kt + 2 < nk) gload(kt + 2, ra0, rb0);
;     compute(0);
;     lstore(1, ra1, rb1);
;     __syncthreads();
;     if (kt + 3 < nk) gload(kt + 3, ra1, rb1);
;     compute(1);
; __global__ void __launch_bounds__(NTHREADS) mega(Params p) {
;     ...
;       for (int j = blockIdx.x; j < 66 * 48; j += gridDim.x) inproj_tile(p, l, j / 48, j % 48, lds);
.LBB0_323:
	s_mov_b32 s25, s101
	v_readlane_b32 s6, v241, 46
	v_readlane_b32 s0, v238, 18
	s_add_i32 s25, s25, s6
	s_add_i32 s24, s24, s0
	s_add_i32 s23, s23, s22
	s_cmpk_gt_i32 s25, 0xc5f
	s_cbranch_scc1 .LBB0_370
.LBB0_324:
	s_mul_hi_u32 s0, s25, 0x5555556
	s_mul_i32 s1, s0, 48
	s_sub_i32 s1, s25, s1
	s_mul_i32 s2, s0, 43
	s_lshr_b32 s2, s2, 8
	s_add_i32 s3, s0, s2
	s_add_i32 s3, s3, 4
	s_mul_i32 s4, s3, 43
	s_lshr_b32 s4, s4, 8
	s_mul_i32 s4, s4, 6
	s_sub_i32 s3, s3, s4
	s_lshl_b32 s3, s3, 3
	s_add_i32 s3, s1, s3
	s_cmp_ge_u32 s3, 48
	s_cselect_b32 s4, 48, 0
	s_sub_i32 s3, s3, s4
	s_mov_b32 s101, s25
	s_sub_i32 s25, s25, s1
	s_add_i32 s25, s25, s3
	s_lshl_b32 s24, s25, 1
	s_lshl_b32 s23, s25, 7
	s_mul_hi_i32 s0, s25, 0x2aaaaaab
	s_lshr_b32 s1, s0, 31
	s_ashr_i32 s26, s0, 3
	s_add_i32 s26, s26, s1
	s_lshl_b32 s4, s26, 8
	s_mul_i32 s0, s26, 0xffffffd0
	s_ashr_i32 s5, s4, 31
	s_add_i32 s2, s25, s0
	s_lshl_b64 s[0:1], s[4:5], 11
	v_readlane_b32 s78, v241, 26
	v_readlane_b32 s79, v241, 27
	s_add_u32 s6, s78, s0
	s_addc_u32 s7, s79, s1
	s_ashr_i32 s3, s2, 31
	s_lshl_b64 s[0:1], s[2:3], 18
	s_add_u32 s8, s18, s0
	v_mov_b32_e32 v1, v152
	s_addc_u32 s9, s19, s1
	s_cmp_gt_i32 s2, 41
	v_and_b32_e32 v107, 31, v1
	v_bfe_u32 v106, v1, 5, 1
	v_bfe_u32 v108, v1, 6, 2
	v_ashrrev_i32_e32 v0, 8, v1
	s_mov_b64 s[0:1], -1
	s_cbranch_scc0 .LBB0_358
	s_cmp_lg_u32 s2, 42
	s_cbranch_scc0 .LBB0_327
	v_mov_b32_e32 v30, v152
	s_mov_b32 s0, 0x40000
	v_ashrrev_i32_e32 v28, 3, v30
	v_ashrrev_i32_e32 v29, 31, v28
	s_waitcnt vmcnt(3)
	v_lshlrev_b64 v[4:5], 11, v[28:29]
	v_lshlrev_b32_e32 v2, 4, v30
	v_lshl_add_u64 v[6:7], s[6:7], 0, v[4:5]
	v_and_b32_e32 v2, 0x70, v2
	v_lshl_add_u64 v[70:71], v[6:7], 0, v[2:3]
	v_add_co_u32_e32 v72, vcc, s60, v70
	v_lshl_add_u64 v[4:5], s[8:9], 0, v[4:5]
	s_nop 0
	v_addc_co_u32_e32 v73, vcc, 0, v71, vcc
	v_add_co_u32_e32 v74, vcc, s0, v70
	s_mov_b32 s0, 0x60000
	s_nop 0
	v_addc_co_u32_e32 v75, vcc, 0, v71, vcc
	v_add_co_u32_e32 v76, vcc, s0, v70
	v_lshl_add_u64 v[68:69], v[4:5], 0, v[2:3]
	s_nop 0
	v_addc_co_u32_e32 v77, vcc, 0, v71, vcc
	global_load_dwordx4 v[4:7], v[70:71], off
	global_load_dwordx4 v[8:11], v[72:73], off
	global_load_dwordx4 v[12:15], v[74:75], off
	global_load_dwordx4 v[16:19], v[76:77], off
	global_load_dwordx4 v[20:23], v[68:69], off
	v_add_co_u32_e32 v78, vcc, s60, v68
	v_and_b32_e32 v29, 31, v30
	s_nop 0
	v_addc_co_u32_e32 v79, vcc, 0, v69, vcc
	global_load_dwordx4 v[24:27], v[78:79], off
	global_load_dwordx4 v[94:97], v[70:71], off offset:128
	global_load_dwordx4 v[98:101], v[68:69], off offset:128
	global_load_dwordx4 v[102:105], v[72:73], off offset:128
	global_load_dwordx4 v[110:113], v[74:75], off offset:128
	global_load_dwordx4 v[114:117], v[76:77], off offset:128
	global_load_dwordx4 v[118:121], v[78:79], off offset:128
	v_and_b32_e32 v31, 0xdf, v30
	v_lshrrev_b32_e32 v32, 1, v30
	v_lshrrev_b32_e32 v30, 2, v30
	s_mov_b32 s0, 0xfffffc0
	v_and_b32_e32 v85, 16, v32
	v_mul_u32_u24_e32 v83, 0x90, v31
	v_and_or_b32 v29, v30, s0, v29
	v_mad_u64_u32 v[86:87], s[0:1], v28, s57, v[2:3]
	v_add3_u32 v2, v83, v85, 0
	v_add_u32_e32 v80, 0, v86
	v_mul_lo_u32 v92, v29, s57
	v_add_u32_e32 v109, v92, v85
	v_add_u32_e32 v84, 0, v109
	v_or_b32_e32 v150, 32, v85
	v_add3_u32 v82, v83, v150, 0
	v_add_u32_e32 v151, v92, v150
	v_add_u32_e32 v87, 0, v151
	v_or_b32_e32 v153, 64, v85
	v_add3_u32 v81, v83, v153, 0
	v_or_b32_e32 v162, 0x60, v85
	v_add3_u32 v83, v83, v162, 0
	v_add_u32_e32 v163, v92, v162
	v_add_u32_e32 v93, 0, v163
	v_readlane_b32 s0, v238, 25
	s_cmp_lt_u32 s2, 47
	v_readlane_b32 s64, v240, 1
	v_readlane_b32 s82, v241, 30
	v_readlane_b32 s83, v241, 31
	v_readlane_b32 s65, v240, 2
	s_mul_i32 s3, s26, 0xffffe800
	s_mul_hi_i32 s5, s25, 0xa57eb503
	s_waitcnt vmcnt(11)
	ds_write_b128 v80, v[4:7]
	s_waitcnt vmcnt(7)
	ds_write_b128 v80, v[20:23] offset:36864
	ds_write_b128 v80, v[8:11] offset:9216
	ds_write_b128 v80, v[12:15] offset:18432
	ds_write_b128 v80, v[16:19] offset:27648
	s_waitcnt vmcnt(6)
	ds_write_b128 v80, v[24:27] offset:46080
	s_waitcnt lgkmcnt(0)
	s_barrier
	ds_read_b128 v[4:7], v2
	ds_read_b128 v[8:11], v84 offset:36864
	ds_read_b128 v[88:91], v2 offset:32
	ds_read_b128 v[12:15], v2 offset:4608
	ds_read_b128 v[16:19], v84 offset:41472
	ds_read_b128 v[122:125], v84 offset:36960
	ds_read_b128 v[138:141], v82 offset:4608
	ds_read_b128 v[142:145], v81 offset:4608
	s_waitcnt lgkmcnt(6)
	v_mfma_f32_32x32x16_bf16 v[52:67], v[4:7], v[8:11], 0
	ds_read_b128 v[126:129], v84 offset:36896
	ds_read_b128 v[130:133], v84 offset:36928
	ds_read_b128 v[134:137], v87 offset:41472
	s_waitcnt lgkmcnt(7)
	v_mfma_f32_32x32x16_bf16 v[20:35], v[12:15], v[8:11], 0
	s_waitcnt lgkmcnt(6)
	v_mfma_f32_32x32x16_bf16 v[36:51], v[4:7], v[16:19], 0
	v_mfma_f32_32x32x16_bf16 v[4:19], v[12:15], v[16:19], 0
	s_waitcnt lgkmcnt(2)
	v_mfma_f32_32x32x16_bf16 v[52:67], v[88:91], v[126:129], v[52:67]
	v_mfma_f32_32x32x16_bf16 v[20:35], v[138:141], v[126:129], v[20:35]
	ds_read_b128 v[126:129], v2 offset:64
	s_waitcnt lgkmcnt(1)
	v_mfma_f32_32x32x16_bf16 v[36:51], v[88:91], v[134:137], v[36:51]
	v_add_u32_e32 v88, v92, v153
	v_add_u32_e32 v90, 0, v88
	v_add_u32_e32 v89, s0, v86
	v_add_u32_e32 v91, s59, v86
	v_add_u32_e32 v88, s59, v88
	s_cselect_b64 s[0:1], -1, 0
	s_and_b64 s[10:11], s[0:1], exec
	v_mfma_f32_32x32x16_bf16 v[4:19], v[138:141], v[134:137], v[4:19]
	ds_read_b128 v[138:141], v90 offset:41472
	ds_read_b128 v[134:137], v2 offset:96
	s_cselect_b32 s11, s83, s65
	s_cselect_b32 s10, s82, s64
	s_add_i32 s3, s23, s3
	s_addk_i32 s3, 0xea80
	s_and_b64 s[12:13], s[0:1], exec
	s_waitcnt lgkmcnt(2)
; template <bool SWAP, class Epi>
; DI void gemm_tile(const u16* __restrict__ A, int lda, const u16* __restrict__ Bw, int ldb, int K, char* lds, Epi epi) {
;     ...
;   for (int kt = 0; kt < nk; kt += 2) {
;     if (kt + 2 < nk) gload(kt + 2, ra0, rb0);
;     compute(0);
;     lstore(1, ra1, rb1);
;     __syncthreads();
;     if (kt + 3 < nk) gload(kt + 3, ra1, rb1);
;     compute(1);
;     if (kt + 2 < nk) lstore(0, ra0, rb0);
;     __syncthreads();
	v_mfma_f32_32x32x16_bf16 v[52:67], v[126:129], v[130:133], v[52:67]
	s_cselect_b32 s3, s3, 0
	s_add_i32 s5, s5, s25
	s_lshr_b32 s12, s5, 31
	s_ashr_i32 s5, s5, 10
	s_add_i32 s12, s5, s12
	s_mul_i32 s5, s12, 0xffffdf00
	s_add_i32 s5, s5, s4
	v_mfma_f32_32x32x16_bf16 v[20:35], v[142:145], v[130:133], v[20:35]
	ds_read_b128 v[130:133], v83 offset:4608
	s_ashr_i32 s13, s12, 31
	s_and_b64 s[0:1], s[0:1], exec
	s_cselect_b32 s0, 9, 7
	s_lshl_b64 s[0:1], s[12:13], s0
	s_movk_i32 s12, 0x4200
	s_waitcnt lgkmcnt(2)
	v_mfma_f32_32x32x16_bf16 v[36:51], v[126:129], v[138:141], v[36:51]
	ds_read_b128 v[126:129], v93 offset:41472
	v_mfma_f32_32x32x16_bf16 v[4:19], v[142:145], v[138:141], v[4:19]
	s_waitcnt lgkmcnt(2)
	v_mfma_f32_32x32x16_bf16 v[52:67], v[134:137], v[122:125], v[52:67]
	s_waitcnt lgkmcnt(0)
	v_mfma_f32_32x32x16_bf16 v[36:51], v[134:137], v[126:129], v[36:51]
	v_mfma_f32_32x32x16_bf16 v[20:35], v[130:133], v[122:125], v[20:35]
	global_load_dwordx4 v[122:125], v[70:71], off offset:256
	global_load_dwordx4 v[134:137], v[72:73], off offset:256
	global_load_dwordx4 v[138:141], v[74:75], off offset:256
	global_load_dwordx4 v[142:145], v[76:77], off offset:256
	global_load_dwordx4 v[146:149], v[68:69], off offset:256
	global_load_dwordx4 v[158:161], v[78:79], off offset:256
	s_waitcnt vmcnt(11)
	ds_write_b128 v80, v[94:97] offset:55296
	s_waitcnt vmcnt(9)
	ds_write_b128 v80, v[102:105] offset:64512
	s_waitcnt vmcnt(8)
	ds_write_b128 v89, v[110:113] offset:18432
	s_waitcnt vmcnt(7)
	ds_write_b128 v89, v[114:117] offset:27648
	ds_write_b128 v91, v[98:101]
	s_waitcnt vmcnt(6)
	ds_write_b128 v91, v[118:121] offset:9216
	s_waitcnt lgkmcnt(0)
	s_barrier
	ds_read_b128 v[98:101], v2 offset:55296
	v_add_u32_e32 v96, s59, v109
	v_add_u32_e32 v95, 0x1200, v92
	ds_read_b128 v[102:105], v96
	v_add3_u32 v97, v95, v85, s59
	ds_read_b128 v[110:113], v97
	ds_read_b128 v[114:117], v2 offset:55328
	v_mfma_f32_32x32x16_bf16 v[4:19], v[130:133], v[126:129], v[4:19]
	v_add_u32_e32 v85, s59, v151
	v_add3_u32 v86, v95, v150, s59
	v_add3_u32 v92, v95, v153, s59
	v_add_u32_e32 v94, s59, v163
	v_add3_u32 v95, v95, v162, s59
	s_waitcnt lgkmcnt(2)
	v_mfma_f32_32x32x16_bf16 v[52:67], v[98:101], v[102:105], v[52:67]
	s_waitcnt lgkmcnt(1)
	v_mfma_f32_32x32x16_bf16 v[36:51], v[98:101], v[110:113], v[36:51]
	ds_read_b128 v[98:101], v2 offset:59904
	ds_read_b128 v[118:121], v82 offset:59904
	s_waitcnt lgkmcnt(1)
	v_mfma_f32_32x32x16_bf16 v[20:35], v[98:101], v[102:105], v[20:35]
	ds_read_b128 v[102:105], v86
	v_mfma_f32_32x32x16_bf16 v[4:19], v[98:101], v[110:113], v[4:19]
	ds_read_b128 v[98:101], v85
	s_waitcnt lgkmcnt(0)
	v_mfma_f32_32x32x16_bf16 v[52:67], v[114:117], v[98:101], v[52:67]
	v_mfma_f32_32x32x16_bf16 v[20:35], v[118:121], v[98:101], v[20:35]
	ds_read_b128 v[98:101], v2 offset:55360
	v_mfma_f32_32x32x16_bf16 v[36:51], v[114:117], v[102:105], v[36:51]
	v_mfma_f32_32x32x16_bf16 v[4:19], v[118:121], v[102:105], v[4:19]
	ds_read_b128 v[102:105], v88
	ds_read_b128 v[110:113], v92
	ds_read_b128 v[114:117], v2 offset:55392
	s_waitcnt lgkmcnt(2)
	v_mfma_f32_32x32x16_bf16 v[52:67], v[98:101], v[102:105], v[52:67]
	s_waitcnt lgkmcnt(1)
	v_mfma_f32_32x32x16_bf16 v[36:51], v[98:101], v[110:113], v[36:51]
	ds_read_b128 v[98:101], v81 offset:59904
	ds_read_b128 v[118:121], v83 offset:59904
	s_waitcnt lgkmcnt(1)
	v_mfma_f32_32x32x16_bf16 v[20:35], v[98:101], v[102:105], v[20:35]
	ds_read_b128 v[102:105], v95
	v_mfma_f32_32x32x16_bf16 v[4:19], v[98:101], v[110:113], v[4:19]
	ds_read_b128 v[98:101], v94
	s_waitcnt lgkmcnt(0)
	v_mfma_f32_32x32x16_bf16 v[52:67], v[114:117], v[98:101], v[52:67]
	v_mfma_f32_32x32x16_bf16 v[36:51], v[114:117], v[102:105], v[36:51]
	v_mfma_f32_32x32x16_bf16 v[20:35], v[118:121], v[98:101], v[20:35]
	global_load_dwordx4 v[98:101], v[70:71], off offset:384
	global_load_dwordx4 v[110:113], v[72:73], off offset:384
	global_load_dwordx4 v[114:117], v[74:75], off offset:384
	global_load_dwordx4 v[126:129], v[76:77], off offset:384
	global_load_dwordx4 v[130:133], v[68:69], off offset:384
	global_load_dwordx4 v[162:165], v[78:79], off offset:384
	s_waitcnt vmcnt(11)
	ds_write_b128 v80, v[122:125]
	s_waitcnt vmcnt(10)
	ds_write_b128 v80, v[134:137] offset:9216
	s_waitcnt vmcnt(9)
	ds_write_b128 v80, v[138:141] offset:18432
	s_waitcnt vmcnt(8)
	ds_write_b128 v80, v[142:145] offset:27648
	s_waitcnt vmcnt(7)
	ds_write_b128 v80, v[146:149] offset:36864
	s_waitcnt vmcnt(6)
	ds_write_b128 v80, v[158:161] offset:46080
	s_waitcnt lgkmcnt(0)
	s_barrier
; template <bool SWAP, class Epi>
; DI void gemm_tile(const u16* __restrict__ A, int lda, const u16* __restrict__ Bw, int ldb, int K, char* lds, Epi epi) {
;     ...
;   for (int kt = 0; kt < nk; kt += 2) {
;     if (kt + 2 < nk) gload(kt + 2, ra0, rb0);
;     compute(0);
;     lstore(1, ra1, rb1);
;     __syncthreads();
;     if (kt + 3 < nk) gload(kt + 3, ra1, rb1);
;     compute(1);
;     if (kt + 2 < nk) lstore(0, ra0, rb0);
;     __syncthreads();
	v_mfma_f32_32x32x16_bf16 v[4:19], v[118:121], v[102:105], v[4:19]
	ds_read_b128 v[102:105], v2
	ds_read_b128 v[118:121], v84 offset:36864
	ds_read_b128 v[122:125], v2 offset:32
	ds_read_b128 v[134:137], v2 offset:4608
	ds_read_b128 v[138:141], v84 offset:41472
	ds_read_b128 v[142:145], v84 offset:36960
	s_waitcnt lgkmcnt(4)
	v_mfma_f32_32x32x16_bf16 v[52:67], v[102:105], v[118:121], v[52:67]
	s_waitcnt lgkmcnt(1)
	v_mfma_f32_32x32x16_bf16 v[36:51], v[102:105], v[138:141], v[36:51]
	v_mfma_f32_32x32x16_bf16 v[20:35], v[134:137], v[118:121], v[20:35]
	ds_read_b128 v[102:105], v84 offset:36896
	ds_read_b128 v[118:121], v84 offset:36928
	v_mfma_f32_32x32x16_bf16 v[4:19], v[134:137], v[138:141], v[4:19]
	ds_read_b128 v[134:137], v87 offset:41472
	ds_read_b128 v[138:141], v82 offset:4608
	s_waitcnt lgkmcnt(3)
	v_mfma_f32_32x32x16_bf16 v[52:67], v[122:125], v[102:105], v[52:67]
	s_waitcnt lgkmcnt(1)
	v_mfma_f32_32x32x16_bf16 v[36:51], v[122:125], v[134:137], v[36:51]
	s_waitcnt lgkmcnt(0)
	v_mfma_f32_32x32x16_bf16 v[20:35], v[138:141], v[102:105], v[20:35]
	ds_read_b128 v[102:105], v2 offset:64
	ds_read_b128 v[122:125], v2 offset:96
	v_mfma_f32_32x32x16_bf16 v[4:19], v[138:141], v[134:137], v[4:19]
	ds_read_b128 v[134:137], v90 offset:41472
	ds_read_b128 v[138:141], v81 offset:4608
	s_waitcnt lgkmcnt(3)
	v_mfma_f32_32x32x16_bf16 v[52:67], v[102:105], v[118:121], v[52:67]
	s_waitcnt lgkmcnt(1)
	v_mfma_f32_32x32x16_bf16 v[36:51], v[102:105], v[134:137], v[36:51]
	s_waitcnt lgkmcnt(0)
	v_mfma_f32_32x32x16_bf16 v[20:35], v[138:141], v[118:121], v[20:35]
	ds_read_b128 v[102:105], v93 offset:41472
	ds_read_b128 v[118:121], v83 offset:4608
	v_mfma_f32_32x32x16_bf16 v[4:19], v[138:141], v[134:137], v[4:19]
	v_mfma_f32_32x32x16_bf16 v[52:67], v[122:125], v[142:145], v[52:67]
	s_waitcnt lgkmcnt(1)
	v_mfma_f32_32x32x16_bf16 v[36:51], v[122:125], v[102:105], v[36:51]
	s_waitcnt lgkmcnt(0)
	v_mfma_f32_32x32x16_bf16 v[20:35], v[118:121], v[142:145], v[20:35]
	global_load_dwordx4 v[122:125], v[70:71], off offset:512
	global_load_dwordx4 v[134:137], v[72:73], off offset:512
	global_load_dwordx4 v[138:141], v[74:75], off offset:512
	global_load_dwordx4 v[142:145], v[76:77], off offset:512
	global_load_dwordx4 v[146:149], v[68:69], off offset:512
	global_load_dwordx4 v[158:161], v[78:79], off offset:512
	s_waitcnt vmcnt(11)
	ds_write_b128 v80, v[98:101] offset:55296
	s_waitcnt vmcnt(10)
	ds_write_b128 v80, v[110:113] offset:64512
	s_waitcnt vmcnt(9)
	ds_write_b128 v89, v[114:117] offset:18432
	s_waitcnt vmcnt(8)
	ds_write_b128 v89, v[126:129] offset:27648
	s_waitcnt vmcnt(7)
	ds_write_b128 v91, v[130:133]
	s_waitcnt vmcnt(6)
	ds_write_b128 v91, v[162:165] offset:9216
	s_waitcnt lgkmcnt(0)
	s_barrier
	v_mfma_f32_32x32x16_bf16 v[4:19], v[118:121], v[102:105], v[4:19]
	ds_read_b128 v[98:101], v2 offset:55296
	ds_read_b128 v[102:105], v96
	ds_read_b128 v[110:113], v97
	ds_read_b128 v[114:117], v2 offset:55328
	s_waitcnt lgkmcnt(2)
	v_mfma_f32_32x32x16_bf16 v[52:67], v[98:101], v[102:105], v[52:67]
	s_waitcnt lgkmcnt(1)
	v_mfma_f32_32x32x16_bf16 v[36:51], v[98:101], v[110:113], v[36:51]
	ds_read_b128 v[98:101], v2 offset:59904
	ds_read_b128 v[118:121], v82 offset:59904
	s_waitcnt lgkmcnt(1)
	v_mfma_f32_32x32x16_bf16 v[20:35], v[98:101], v[102:105], v[20:35]
	v_mfma_f32_32x32x16_bf16 v[4:19], v[98:101], v[110:113], v[4:19]
	ds_read_b128 v[98:101], v85
	ds_read_b128 v[102:105], v86
	s_waitcnt lgkmcnt(1)
	v_mfma_f32_32x32x16_bf16 v[52:67], v[114:117], v[98:101], v[52:67]
	s_waitcnt lgkmcnt(0)
	v_mfma_f32_32x32x16_bf16 v[36:51], v[114:117], v[102:105], v[36:51]
	v_mfma_f32_32x32x16_bf16 v[20:35], v[118:121], v[98:101], v[20:35]
	v_mfma_f32_32x32x16_bf16 v[4:19], v[118:121], v[102:105], v[4:19]
	ds_read_b128 v[98:101], v2 offset:55360
	ds_read_b128 v[102:105], v88
	ds_read_b128 v[110:113], v92
	ds_read_b128 v[114:117], v2 offset:55392
	s_waitcnt lgkmcnt(2)
	v_mfma_f32_32x32x16_bf16 v[52:67], v[98:101], v[102:105], v[52:67]
	s_waitcnt lgkmcnt(1)
	v_mfma_f32_32x32x16_bf16 v[36:51], v[98:101], v[110:113], v[36:51]
	ds_read_b128 v[98:101], v81 offset:59904
	ds_read_b128 v[118:121], v83 offset:59904
	s_waitcnt lgkmcnt(1)
	v_mfma_f32_32x32x16_bf16 v[20:35], v[98:101], v[102:105], v[20:35]
	v_mfma_f32_32x32x16_bf16 v[4:19], v[98:101], v[110:113], v[4:19]
	ds_read_b128 v[98:101], v94
	ds_read_b128 v[102:105], v95
	s_waitcnt lgkmcnt(1)
	v_mfma_f32_32x32x16_bf16 v[52:67], v[114:117], v[98:101], v[52:67]
	s_waitcnt lgkmcnt(0)
	v_mfma_f32_32x32x16_bf16 v[36:51], v[114:117], v[102:105], v[36:51]
	v_mfma_f32_32x32x16_bf16 v[20:35], v[118:121], v[98:101], v[20:35]
	global_load_dwordx4 v[98:101], v[70:71], off offset:640
	global_load_dwordx4 v[110:113], v[72:73], off offset:640
	global_load_dwordx4 v[114:117], v[74:75], off offset:640
	global_load_dwordx4 v[126:129], v[76:77], off offset:640
	global_load_dwordx4 v[130:133], v[68:69], off offset:640
	global_load_dwordx4 v[162:165], v[78:79], off offset:640
	s_waitcnt vmcnt(11)
	ds_write_b128 v80, v[122:125]
	s_waitcnt vmcnt(10)
	ds_write_b128 v80, v[134:137] offset:9216
	s_waitcnt vmcnt(9)
	ds_write_b128 v80, v[138:141] offset:18432
	s_waitcnt vmcnt(8)
	ds_write_b128 v80, v[142:145] offset:27648
	s_waitcnt vmcnt(7)
	ds_write_b128 v80, v[146:149] offset:36864
	s_waitcnt vmcnt(6)
	ds_write_b128 v80, v[158:161] offset:46080
	s_waitcnt lgkmcnt(0)
	s_barrier
; template <bool SWAP, class Epi>
; DI void gemm_tile(const u16* __restrict__ A, int lda, const u16* __restrict__ Bw, int ldb, int K, char* lds, Epi epi) {
;     ...
;   for (int kt = 0; kt < nk; kt += 2) {
;     if (kt + 2 < nk) gload(kt + 2, ra0, rb0);
;     compute(0);
;     lstore(1, ra1, rb1);
;     __syncthreads();
;     if (kt + 3 < nk) gload(kt + 3, ra1, rb1);
;     compute(1);
;     if (kt + 2 < nk) lstore(0, ra0, rb0);
;     __syncthreads();
	v_mfma_f32_32x32x16_bf16 v[4:19], v[118:121], v[102:105], v[4:19]
	ds_read_b128 v[102:105], v2
	ds_read_b128 v[118:121], v84 offset:36864
	ds_read_b128 v[122:125], v2 offset:32
	ds_read_b128 v[134:137], v2 offset:4608
	ds_read_b128 v[138:141], v84 offset:41472
	ds_read_b128 v[142:145], v84 offset:36960
	s_waitcnt lgkmcnt(4)
	v_mfma_f32_32x32x16_bf16 v[52:67], v[102:105], v[118:121], v[52:67]
	s_waitcnt lgkmcnt(1)
	v_mfma_f32_32x32x16_bf16 v[36:51], v[102:105], v[138:141], v[36:51]
	v_mfma_f32_32x32x16_bf16 v[20:35], v[134:137], v[118:121], v[20:35]
	ds_read_b128 v[102:105], v84 offset:36896
	ds_read_b128 v[118:121], v84 offset:36928
	v_mfma_f32_32x32x16_bf16 v[4:19], v[134:137], v[138:141], v[4:19]
	ds_read_b128 v[134:137], v87 offset:41472
	ds_read_b128 v[138:141], v82 offset:4608
	s_waitcnt lgkmcnt(3)
	v_mfma_f32_32x32x16_bf16 v[52:67], v[122:125], v[102:105], v[52:67]
	s_waitcnt lgkmcnt(1)
	v_mfma_f32_32x32x16_bf16 v[36:51], v[122:125], v[134:137], v[36:51]
	s_waitcnt lgkmcnt(0)
	v_mfma_f32_32x32x16_bf16 v[20:35], v[138:141], v[102:105], v[20:35]
	ds_read_b128 v[102:105], v2 offset:64
	ds_read_b128 v[122:125], v2 offset:96
	v_mfma_f32_32x32x16_bf16 v[4:19], v[138:141], v[134:137], v[4:19]
	ds_read_b128 v[134:137], v90 offset:41472
	ds_read_b128 v[138:141], v81 offset:4608
	s_waitcnt lgkmcnt(3)
	v_mfma_f32_32x32x16_bf16 v[52:67], v[102:105], v[118:121], v[52:67]
	s_waitcnt lgkmcnt(1)
	v_mfma_f32_32x32x16_bf16 v[36:51], v[102:105], v[134:137], v[36:51]
	s_waitcnt lgkmcnt(0)
	v_mfma_f32_32x32x16_bf16 v[20:35], v[138:141], v[118:121], v[20:35]
	ds_read_b128 v[102:105], v93 offset:41472
	ds_read_b128 v[118:121], v83 offset:4608
	v_mfma_f32_32x32x16_bf16 v[4:19], v[138:141], v[134:137], v[4:19]
	v_mfma_f32_32x32x16_bf16 v[52:67], v[122:125], v[142:145], v[52:67]
	s_waitcnt lgkmcnt(1)
	v_mfma_f32_32x32x16_bf16 v[36:51], v[122:125], v[102:105], v[36:51]
	s_waitcnt lgkmcnt(0)
	v_mfma_f32_32x32x16_bf16 v[20:35], v[118:121], v[142:145], v[20:35]
	global_load_dwordx4 v[122:125], v[70:71], off offset:768
	global_load_dwordx4 v[134:137], v[72:73], off offset:768
	global_load_dwordx4 v[138:141], v[74:75], off offset:768
	global_load_dwordx4 v[142:145], v[76:77], off offset:768
	global_load_dwordx4 v[146:149], v[68:69], off offset:768
	global_load_dwordx4 v[158:161], v[78:79], off offset:768
	s_waitcnt vmcnt(11)
	ds_write_b128 v80, v[98:101] offset:55296
	s_waitcnt vmcnt(10)
	ds_write_b128 v80, v[110:113] offset:64512
	s_waitcnt vmcnt(9)
	ds_write_b128 v89, v[114:117] offset:18432
	s_waitcnt vmcnt(8)
	ds_write_b128 v89, v[126:129] offset:27648
	s_waitcnt vmcnt(7)
	ds_write_b128 v91, v[130:133]
	s_waitcnt vmcnt(6)
	ds_write_b128 v91, v[162:165] offset:9216
	s_waitcnt lgkmcnt(0)
	s_barrier
	v_mfma_f32_32x32x16_bf16 v[4:19], v[118:121], v[102:105], v[4:19]
	ds_read_b128 v[98:101], v2 offset:55296
	ds_read_b128 v[102:105], v96
	ds_read_b128 v[110:113], v97
	ds_read_b128 v[114:117], v2 offset:55328
	s_waitcnt lgkmcnt(2)
	v_mfma_f32_32x32x16_bf16 v[52:67], v[98:101], v[102:105], v[52:67]
	s_waitcnt lgkmcnt(1)
	v_mfma_f32_32x32x16_bf16 v[36:51], v[98:101], v[110:113], v[36:51]
	ds_read_b128 v[98:101], v2 offset:59904
	ds_read_b128 v[118:121], v82 offset:59904
	s_waitcnt lgkmcnt(1)
	v_mfma_f32_32x32x16_bf16 v[20:35], v[98:101], v[102:105], v[20:35]
	v_mfma_f32_32x32x16_bf16 v[4:19], v[98:101], v[110:113], v[4:19]
	ds_read_b128 v[98:101], v85
	ds_read_b128 v[102:105], v86
	s_waitcnt lgkmcnt(1)
	v_mfma_f32_32x32x16_bf16 v[52:67], v[114:117], v[98:101], v[52:67]
	s_waitcnt lgkmcnt(0)
	v_mfma_f32_32x32x16_bf16 v[36:51], v[114:117], v[102:105], v[36:51]
	v_mfma_f32_32x32x16_bf16 v[20:35], v[118:121], v[98:101], v[20:35]
	v_mfma_f32_32x32x16_bf16 v[4:19], v[118:121], v[102:105], v[4:19]
	ds_read_b128 v[98:101], v2 offset:55360
	ds_read_b128 v[102:105], v88
	ds_read_b128 v[110:113], v92
	ds_read_b128 v[114:117], v2 offset:55392
	s_waitcnt lgkmcnt(2)
	v_mfma_f32_32x32x16_bf16 v[52:67], v[98:101], v[102:105], v[52:67]
	s_waitcnt lgkmcnt(1)
	v_mfma_f32_32x32x16_bf16 v[36:51], v[98:101], v[110:113], v[36:51]
	ds_read_b128 v[98:101], v81 offset:59904
	ds_read_b128 v[118:121], v83 offset:59904
	s_waitcnt lgkmcnt(1)
	v_mfma_f32_32x32x16_bf16 v[20:35], v[98:101], v[102:105], v[20:35]
	v_mfma_f32_32x32x16_bf16 v[4:19], v[98:101], v[110:113], v[4:19]
	ds_read_b128 v[98:101], v94
	ds_read_b128 v[102:105], v95
	s_waitcnt lgkmcnt(1)
	v_mfma_f32_32x32x16_bf16 v[52:67], v[114:117], v[98:101], v[52:67]
	s_waitcnt lgkmcnt(0)
	v_mfma_f32_32x32x16_bf16 v[36:51], v[114:117], v[102:105], v[36:51]
	v_mfma_f32_32x32x16_bf16 v[20:35], v[118:121], v[98:101], v[20:35]
	global_load_dwordx4 v[98:101], v[70:71], off offset:896
	global_load_dwordx4 v[110:113], v[72:73], off offset:896
	global_load_dwordx4 v[114:117], v[74:75], off offset:896
	global_load_dwordx4 v[126:129], v[76:77], off offset:896
	global_load_dwordx4 v[130:133], v[68:69], off offset:896
	global_load_dwordx4 v[162:165], v[78:79], off offset:896
	s_waitcnt vmcnt(11)
	ds_write_b128 v80, v[122:125]
	s_waitcnt vmcnt(10)
	ds_write_b128 v80, v[134:137] offset:9216
	s_waitcnt vmcnt(9)
	ds_write_b128 v80, v[138:141] offset:18432
	s_waitcnt vmcnt(8)
	ds_write_b128 v80, v[142:145] offset:27648
	s_waitcnt vmcnt(7)
	ds_write_b128 v80, v[146:149] offset:36864
	s_waitcnt vmcnt(6)
	ds_write_b128 v80, v[158:161] offset:46080
	s_waitcnt lgkmcnt(0)
	s_barrier
; template <bool SWAP, class Epi>
; DI void gemm_tile(const u16* __restrict__ A, int lda, const u16* __restrict__ Bw, int ldb, int K, char* lds, Epi epi) {
;     ...
;   for (int kt = 0; kt < nk; kt += 2) {
;     if (kt + 2 < nk) gload(kt + 2, ra0, rb0);
;     compute(0);
;     lstore(1, ra1, rb1);
;     __syncthreads();
;     if (kt + 3 < nk) gload(kt + 3, ra1, rb1);
;     compute(1);
;     if (kt + 2 < nk) lstore(0, ra0, rb0);
;     __syncthreads();
	v_mfma_f32_32x32x16_bf16 v[4:19], v[118:121], v[102:105], v[4:19]
	ds_read_b128 v[102:105], v2
	ds_read_b128 v[118:121], v84 offset:36864
	ds_read_b128 v[122:125], v2 offset:32
	ds_read_b128 v[134:137], v2 offset:4608
	ds_read_b128 v[138:141], v84 offset:41472
	ds_read_b128 v[142:145], v84 offset:36960
	s_waitcnt lgkmcnt(4)
	v_mfma_f32_32x32x16_bf16 v[52:67], v[102:105], v[118:121], v[52:67]
	s_waitcnt lgkmcnt(1)
	v_mfma_f32_32x32x16_bf16 v[36:51], v[102:105], v[138:141], v[36:51]
	v_mfma_f32_32x32x16_bf16 v[20:35], v[134:137], v[118:121], v[20:35]
	ds_read_b128 v[102:105], v84 offset:36896
	ds_read_b128 v[118:121], v84 offset:36928
	v_mfma_f32_32x32x16_bf16 v[4:19], v[134:137], v[138:141], v[4:19]
	ds_read_b128 v[134:137], v87 offset:41472
	ds_read_b128 v[138:141], v82 offset:4608
	s_waitcnt lgkmcnt(3)
	v_mfma_f32_32x32x16_bf16 v[52:67], v[122:125], v[102:105], v[52:67]
	s_waitcnt lgkmcnt(1)
	v_mfma_f32_32x32x16_bf16 v[36:51], v[122:125], v[134:137], v[36:51]
	s_waitcnt lgkmcnt(0)
	v_mfma_f32_32x32x16_bf16 v[20:35], v[138:141], v[102:105], v[20:35]
	ds_read_b128 v[102:105], v2 offset:64
	ds_read_b128 v[122:125], v2 offset:96
	v_mfma_f32_32x32x16_bf16 v[4:19], v[138:141], v[134:137], v[4:19]
	ds_read_b128 v[134:137], v90 offset:41472
	ds_read_b128 v[138:141], v81 offset:4608
	s_waitcnt lgkmcnt(3)
	v_mfma_f32_32x32x16_bf16 v[52:67], v[102:105], v[118:121], v[52:67]
	s_waitcnt lgkmcnt(1)
	v_mfma_f32_32x32x16_bf16 v[36:51], v[102:105], v[134:137], v[36:51]
	s_waitcnt lgkmcnt(0)
	v_mfma_f32_32x32x16_bf16 v[20:35], v[138:141], v[118:121], v[20:35]
	ds_read_b128 v[102:105], v93 offset:41472
	ds_read_b128 v[118:121], v83 offset:4608
	v_mfma_f32_32x32x16_bf16 v[4:19], v[138:141], v[134:137], v[4:19]
	v_mfma_f32_32x32x16_bf16 v[52:67], v[122:125], v[142:145], v[52:67]
	s_waitcnt lgkmcnt(1)
	v_mfma_f32_32x32x16_bf16 v[36:51], v[122:125], v[102:105], v[36:51]
	s_waitcnt lgkmcnt(0)
	v_mfma_f32_32x32x16_bf16 v[20:35], v[118:121], v[142:145], v[20:35]
	global_load_dwordx4 v[122:125], v[70:71], off offset:1024
	global_load_dwordx4 v[134:137], v[72:73], off offset:1024
	global_load_dwordx4 v[138:141], v[74:75], off offset:1024
	global_load_dwordx4 v[142:145], v[76:77], off offset:1024
	global_load_dwordx4 v[146:149], v[68:69], off offset:1024
	global_load_dwordx4 v[158:161], v[78:79], off offset:1024
	s_waitcnt vmcnt(11)
	ds_write_b128 v80, v[98:101] offset:55296
	s_waitcnt vmcnt(10)
	ds_write_b128 v80, v[110:113] offset:64512
	s_waitcnt vmcnt(9)
	ds_write_b128 v89, v[114:117] offset:18432
	s_waitcnt vmcnt(8)
	ds_write_b128 v89, v[126:129] offset:27648
	s_waitcnt vmcnt(7)
	ds_write_b128 v91, v[130:133]
	s_waitcnt vmcnt(6)
	ds_write_b128 v91, v[162:165] offset:9216
	s_waitcnt lgkmcnt(0)
	s_barrier
	v_mfma_f32_32x32x16_bf16 v[4:19], v[118:121], v[102:105], v[4:19]
	ds_read_b128 v[98:101], v2 offset:55296
	ds_read_b128 v[102:105], v96
	ds_read_b128 v[110:113], v97
	ds_read_b128 v[114:117], v2 offset:55328
	s_waitcnt lgkmcnt(2)
	v_mfma_f32_32x32x16_bf16 v[52:67], v[98:101], v[102:105], v[52:67]
	s_waitcnt lgkmcnt(1)
	v_mfma_f32_32x32x16_bf16 v[36:51], v[98:101], v[110:113], v[36:51]
	ds_read_b128 v[98:101], v2 offset:59904
	ds_read_b128 v[118:121], v82 offset:59904
	s_waitcnt lgkmcnt(1)
	v_mfma_f32_32x32x16_bf16 v[20:35], v[98:101], v[102:105], v[20:35]
	v_mfma_f32_32x32x16_bf16 v[4:19], v[98:101], v[110:113], v[4:19]
	ds_read_b128 v[98:101], v85
	ds_read_b128 v[102:105], v86
	s_waitcnt lgkmcnt(1)
	v_mfma_f32_32x32x16_bf16 v[52:67], v[114:117], v[98:101], v[52:67]
	s_waitcnt lgkmcnt(0)
	v_mfma_f32_32x32x16_bf16 v[36:51], v[114:117], v[102:105], v[36:51]
	v_mfma_f32_32x32x16_bf16 v[20:35], v[118:121], v[98:101], v[20:35]
	v_mfma_f32_32x32x16_bf16 v[4:19], v[118:121], v[102:105], v[4:19]
	ds_read_b128 v[98:101], v2 offset:55360
	ds_read_b128 v[102:105], v88
	ds_read_b128 v[110:113], v92
	ds_read_b128 v[114:117], v2 offset:55392
	s_waitcnt lgkmcnt(2)
	v_mfma_f32_32x32x16_bf16 v[52:67], v[98:101], v[102:105], v[52:67]
	s_waitcnt lgkmcnt(1)
	v_mfma_f32_32x32x16_bf16 v[36:51], v[98:101], v[110:113], v[36:51]
	ds_read_b128 v[98:101], v81 offset:59904
	ds_read_b128 v[118:121], v83 offset:59904
	s_waitcnt lgkmcnt(1)
	v_mfma_f32_32x32x16_bf16 v[20:35], v[98:101], v[102:105], v[20:35]
	v_mfma_f32_32x32x16_bf16 v[4:19], v[98:101], v[110:113], v[4:19]
	ds_read_b128 v[98:101], v94
	ds_read_b128 v[102:105], v95
	s_waitcnt lgkmcnt(1)
	v_mfma_f32_32x32x16_bf16 v[52:67], v[114:117], v[98:101], v[52:67]
	s_waitcnt lgkmcnt(0)
	v_mfma_f32_32x32x16_bf16 v[36:51], v[114:117], v[102:105], v[36:51]
	v_mfma_f32_32x32x16_bf16 v[20:35], v[118:121], v[98:101], v[20:35]
	global_load_dwordx4 v[98:101], v[70:71], off offset:1152
	global_load_dwordx4 v[110:113], v[72:73], off offset:1152
	global_load_dwordx4 v[114:117], v[74:75], off offset:1152
	global_load_dwordx4 v[126:129], v[76:77], off offset:1152
	global_load_dwordx4 v[130:133], v[68:69], off offset:1152
	global_load_dwordx4 v[162:165], v[78:79], off offset:1152
	s_waitcnt vmcnt(11)
	ds_write_b128 v80, v[122:125]
	s_waitcnt vmcnt(10)
	ds_write_b128 v80, v[134:137] offset:9216
	s_waitcnt vmcnt(9)
	ds_write_b128 v80, v[138:141] offset:18432
	s_waitcnt vmcnt(8)
	ds_write_b128 v80, v[142:145] offset:27648
	s_waitcnt vmcnt(7)
	ds_write_b128 v80, v[146:149] offset:36864
	s_waitcnt vmcnt(6)
	ds_write_b128 v80, v[158:161] offset:46080
	s_waitcnt lgkmcnt(0)
	s_barrier
; template <bool SWAP, class Epi>
; DI void gemm_tile(const u16* __restrict__ A, int lda, const u16* __restrict__ Bw, int ldb, int K, char* lds, Epi epi) {
;     ...
;   for (int kt = 0; kt < nk; kt += 2) {
;     if (kt + 2 < nk) gload(kt + 2, ra0, rb0);
;     compute(0);
;     lstore(1, ra1, rb1);
;     __syncthreads();
;     if (kt + 3 < nk) gload(kt + 3, ra1, rb1);
;     compute(1);
;     if (kt + 2 < nk) lstore(0, ra0, rb0);
;     __syncthreads();
	v_mfma_f32_32x32x16_bf16 v[4:19], v[118:121], v[102:105], v[4:19]
	ds_read_b128 v[102:105], v2
	ds_read_b128 v[118:121], v84 offset:36864
	ds_read_b128 v[122:125], v2 offset:32
	ds_read_b128 v[134:137], v2 offset:4608
	ds_read_b128 v[138:141], v84 offset:41472
	ds_read_b128 v[142:145], v84 offset:36960
	s_waitcnt lgkmcnt(4)
	v_mfma_f32_32x32x16_bf16 v[52:67], v[102:105], v[118:121], v[52:67]
	s_waitcnt lgkmcnt(1)
	v_mfma_f32_32x32x16_bf16 v[36:51], v[102:105], v[138:141], v[36:51]
	v_mfma_f32_32x32x16_bf16 v[20:35], v[134:137], v[118:121], v[20:35]
	ds_read_b128 v[102:105], v84 offset:36896
	ds_read_b128 v[118:121], v84 offset:36928
	v_mfma_f32_32x32x16_bf16 v[4:19], v[134:137], v[138:141], v[4:19]
	ds_read_b128 v[134:137], v87 offset:41472
	ds_read_b128 v[138:141], v82 offset:4608
	s_waitcnt lgkmcnt(3)
	v_mfma_f32_32x32x16_bf16 v[52:67], v[122:125], v[102:105], v[52:67]
	s_waitcnt lgkmcnt(1)
	v_mfma_f32_32x32x16_bf16 v[36:51], v[122:125], v[134:137], v[36:51]
	s_waitcnt lgkmcnt(0)
	v_mfma_f32_32x32x16_bf16 v[20:35], v[138:141], v[102:105], v[20:35]
	ds_read_b128 v[102:105], v2 offset:64
	ds_read_b128 v[122:125], v2 offset:96
	v_mfma_f32_32x32x16_bf16 v[4:19], v[138:141], v[134:137], v[4:19]
	ds_read_b128 v[134:137], v90 offset:41472
	ds_read_b128 v[138:141], v81 offset:4608
	s_waitcnt lgkmcnt(3)
	v_mfma_f32_32x32x16_bf16 v[52:67], v[102:105], v[118:121], v[52:67]
	s_waitcnt lgkmcnt(1)
	v_mfma_f32_32x32x16_bf16 v[36:51], v[102:105], v[134:137], v[36:51]
	s_waitcnt lgkmcnt(0)
	v_mfma_f32_32x32x16_bf16 v[20:35], v[138:141], v[118:121], v[20:35]
	ds_read_b128 v[102:105], v93 offset:41472
	ds_read_b128 v[118:121], v83 offset:4608
	v_mfma_f32_32x32x16_bf16 v[4:19], v[138:141], v[134:137], v[4:19]
	v_mfma_f32_32x32x16_bf16 v[52:67], v[122:125], v[142:145], v[52:67]
	s_waitcnt lgkmcnt(1)
	v_mfma_f32_32x32x16_bf16 v[36:51], v[122:125], v[102:105], v[36:51]
	s_waitcnt lgkmcnt(0)
	v_mfma_f32_32x32x16_bf16 v[20:35], v[118:121], v[142:145], v[20:35]
	global_load_dwordx4 v[122:125], v[70:71], off offset:1280
	global_load_dwordx4 v[134:137], v[72:73], off offset:1280
	global_load_dwordx4 v[138:141], v[74:75], off offset:1280
	global_load_dwordx4 v[142:145], v[76:77], off offset:1280
	global_load_dwordx4 v[146:149], v[68:69], off offset:1280
	global_load_dwordx4 v[158:161], v[78:79], off offset:1280
	s_waitcnt vmcnt(11)
	ds_write_b128 v80, v[98:101] offset:55296
	s_waitcnt vmcnt(10)
	ds_write_b128 v80, v[110:113] offset:64512
	s_waitcnt vmcnt(9)
	ds_write_b128 v89, v[114:117] offset:18432
	s_waitcnt vmcnt(8)
	ds_write_b128 v89, v[126:129] offset:27648
	s_waitcnt vmcnt(7)
	ds_write_b128 v91, v[130:133]
	s_waitcnt vmcnt(6)
	ds_write_b128 v91, v[162:165] offset:9216
	s_waitcnt lgkmcnt(0)
	s_barrier
	v_mfma_f32_32x32x16_bf16 v[4:19], v[118:121], v[102:105], v[4:19]
	ds_read_b128 v[98:101], v2 offset:55296
	ds_read_b128 v[102:105], v96
	ds_read_b128 v[110:113], v97
	ds_read_b128 v[114:117], v2 offset:55328
	s_waitcnt lgkmcnt(2)
	v_mfma_f32_32x32x16_bf16 v[52:67], v[98:101], v[102:105], v[52:67]
	s_waitcnt lgkmcnt(1)
	v_mfma_f32_32x32x16_bf16 v[36:51], v[98:101], v[110:113], v[36:51]
	ds_read_b128 v[98:101], v2 offset:59904
	ds_read_b128 v[118:121], v82 offset:59904
	s_waitcnt lgkmcnt(1)
	v_mfma_f32_32x32x16_bf16 v[20:35], v[98:101], v[102:105], v[20:35]
	v_mfma_f32_32x32x16_bf16 v[4:19], v[98:101], v[110:113], v[4:19]
	ds_read_b128 v[98:101], v85
	ds_read_b128 v[102:105], v86
	s_waitcnt lgkmcnt(1)
	v_mfma_f32_32x32x16_bf16 v[52:67], v[114:117], v[98:101], v[52:67]
	s_waitcnt lgkmcnt(0)
	v_mfma_f32_32x32x16_bf16 v[36:51], v[114:117], v[102:105], v[36:51]
	v_mfma_f32_32x32x16_bf16 v[20:35], v[118:121], v[98:101], v[20:35]
	v_mfma_f32_32x32x16_bf16 v[4:19], v[118:121], v[102:105], v[4:19]
	ds_read_b128 v[98:101], v2 offset:55360
	ds_read_b128 v[102:105], v88
	ds_read_b128 v[110:113], v92
	ds_read_b128 v[114:117], v2 offset:55392
	s_waitcnt lgkmcnt(2)
	v_mfma_f32_32x32x16_bf16 v[52:67], v[98:101], v[102:105], v[52:67]
	s_waitcnt lgkmcnt(1)
	v_mfma_f32_32x32x16_bf16 v[36:51], v[98:101], v[110:113], v[36:51]
	ds_read_b128 v[98:101], v81 offset:59904
	ds_read_b128 v[118:121], v83 offset:59904
	s_waitcnt lgkmcnt(1)
	v_mfma_f32_32x32x16_bf16 v[20:35], v[98:101], v[102:105], v[20:35]
	v_mfma_f32_32x32x16_bf16 v[4:19], v[98:101], v[110:113], v[4:19]
	ds_read_b128 v[98:101], v94
	ds_read_b128 v[102:105], v95
	s_waitcnt lgkmcnt(1)
	v_mfma_f32_32x32x16_bf16 v[52:67], v[114:117], v[98:101], v[52:67]
	s_waitcnt lgkmcnt(0)
	v_mfma_f32_32x32x16_bf16 v[36:51], v[114:117], v[102:105], v[36:51]
	v_mfma_f32_32x32x16_bf16 v[20:35], v[118:121], v[98:101], v[20:35]
	global_load_dwordx4 v[98:101], v[70:71], off offset:1408
	global_load_dwordx4 v[110:113], v[72:73], off offset:1408
	global_load_dwordx4 v[114:117], v[74:75], off offset:1408
	global_load_dwordx4 v[126:129], v[76:77], off offset:1408
	global_load_dwordx4 v[130:133], v[68:69], off offset:1408
	global_load_dwordx4 v[162:165], v[78:79], off offset:1408
	s_waitcnt vmcnt(11)
	ds_write_b128 v80, v[122:125]
	s_waitcnt vmcnt(10)
	ds_write_b128 v80, v[134:137] offset:9216
	s_waitcnt vmcnt(9)
	ds_write_b128 v80, v[138:141] offset:18432
	s_waitcnt vmcnt(8)
	ds_write_b128 v80, v[142:145] offset:27648
	s_waitcnt vmcnt(7)
	ds_write_b128 v80, v[146:149] offset:36864
	s_waitcnt vmcnt(6)
	ds_write_b128 v80, v[158:161] offset:46080
	s_waitcnt lgkmcnt(0)
	s_barrier
; template <bool SWAP, class Epi>
; DI void gemm_tile(const u16* __restrict__ A, int lda, const u16* __restrict__ Bw, int ldb, int K, char* lds, Epi epi) {
;     ...
;   for (int kt = 0; kt < nk; kt += 2) {
;     if (kt + 2 < nk) gload(kt + 2, ra0, rb0);
;     compute(0);
;     lstore(1, ra1, rb1);
;     __syncthreads();
;     if (kt + 3 < nk) gload(kt + 3, ra1, rb1);
;     compute(1);
;     if (kt + 2 < nk) lstore(0, ra0, rb0);
;     __syncthreads();
	v_mfma_f32_32x32x16_bf16 v[4:19], v[118:121], v[102:105], v[4:19]
	ds_read_b128 v[102:105], v2
	ds_read_b128 v[118:121], v84 offset:36864
	ds_read_b128 v[122:125], v2 offset:32
	ds_read_b128 v[134:137], v2 offset:4608
	ds_read_b128 v[138:141], v84 offset:41472
	ds_read_b128 v[142:145], v84 offset:36960
	s_waitcnt lgkmcnt(4)
	v_mfma_f32_32x32x16_bf16 v[52:67], v[102:105], v[118:121], v[52:67]
	s_waitcnt lgkmcnt(1)
	v_mfma_f32_32x32x16_bf16 v[36:51], v[102:105], v[138:141], v[36:51]
	v_mfma_f32_32x32x16_bf16 v[20:35], v[134:137], v[118:121], v[20:35]
	ds_read_b128 v[102:105], v84 offset:36896
	ds_read_b128 v[118:121], v84 offset:36928
	v_mfma_f32_32x32x16_bf16 v[4:19], v[134:137], v[138:141], v[4:19]
	ds_read_b128 v[134:137], v87 offset:41472
	ds_read_b128 v[138:141], v82 offset:4608
	s_waitcnt lgkmcnt(3)
	v_mfma_f32_32x32x16_bf16 v[52:67], v[122:125], v[102:105], v[52:67]
	s_waitcnt lgkmcnt(1)
	v_mfma_f32_32x32x16_bf16 v[36:51], v[122:125], v[134:137], v[36:51]
	s_waitcnt lgkmcnt(0)
	v_mfma_f32_32x32x16_bf16 v[20:35], v[138:141], v[102:105], v[20:35]
	ds_read_b128 v[102:105], v2 offset:64
	ds_read_b128 v[122:125], v2 offset:96
	v_mfma_f32_32x32x16_bf16 v[4:19], v[138:141], v[134:137], v[4:19]
	ds_read_b128 v[134:137], v90 offset:41472
	ds_read_b128 v[138:141], v81 offset:4608
	s_waitcnt lgkmcnt(3)
	v_mfma_f32_32x32x16_bf16 v[52:67], v[102:105], v[118:121], v[52:67]
	s_waitcnt lgkmcnt(1)
	v_mfma_f32_32x32x16_bf16 v[36:51], v[102:105], v[134:137], v[36:51]
	s_waitcnt lgkmcnt(0)
	v_mfma_f32_32x32x16_bf16 v[20:35], v[138:141], v[118:121], v[20:35]
	ds_read_b128 v[102:105], v93 offset:41472
	ds_read_b128 v[118:121], v83 offset:4608
	v_mfma_f32_32x32x16_bf16 v[4:19], v[138:141], v[134:137], v[4:19]
	v_mfma_f32_32x32x16_bf16 v[52:67], v[122:125], v[142:145], v[52:67]
	s_waitcnt lgkmcnt(1)
	v_mfma_f32_32x32x16_bf16 v[36:51], v[122:125], v[102:105], v[36:51]
	s_waitcnt lgkmcnt(0)
	v_mfma_f32_32x32x16_bf16 v[20:35], v[118:121], v[142:145], v[20:35]
	global_load_dwordx4 v[122:125], v[70:71], off offset:1536
	global_load_dwordx4 v[134:137], v[72:73], off offset:1536
	global_load_dwordx4 v[138:141], v[74:75], off offset:1536
	global_load_dwordx4 v[142:145], v[76:77], off offset:1536
	global_load_dwordx4 v[146:149], v[68:69], off offset:1536
	global_load_dwordx4 v[158:161], v[78:79], off offset:1536
	s_waitcnt vmcnt(11)
	ds_write_b128 v80, v[98:101] offset:55296
	s_waitcnt vmcnt(10)
	ds_write_b128 v80, v[110:113] offset:64512
	s_waitcnt vmcnt(9)
	ds_write_b128 v89, v[114:117] offset:18432
	s_waitcnt vmcnt(8)
	ds_write_b128 v89, v[126:129] offset:27648
	s_waitcnt vmcnt(7)
	ds_write_b128 v91, v[130:133]
	s_waitcnt vmcnt(6)
	ds_write_b128 v91, v[162:165] offset:9216
	s_waitcnt lgkmcnt(0)
	s_barrier
	v_mfma_f32_32x32x16_bf16 v[4:19], v[118:121], v[102:105], v[4:19]
	ds_read_b128 v[98:101], v2 offset:55296
	ds_read_b128 v[102:105], v96
	ds_read_b128 v[110:113], v97
	ds_read_b128 v[114:117], v2 offset:55328
	s_waitcnt lgkmcnt(2)
	v_mfma_f32_32x32x16_bf16 v[52:67], v[98:101], v[102:105], v[52:67]
	s_waitcnt lgkmcnt(1)
	v_mfma_f32_32x32x16_bf16 v[36:51], v[98:101], v[110:113], v[36:51]
	ds_read_b128 v[98:101], v2 offset:59904
	ds_read_b128 v[118:121], v82 offset:59904
	s_waitcnt lgkmcnt(1)
	v_mfma_f32_32x32x16_bf16 v[20:35], v[98:101], v[102:105], v[20:35]
	v_mfma_f32_32x32x16_bf16 v[4:19], v[98:101], v[110:113], v[4:19]
	ds_read_b128 v[98:101], v85
	ds_read_b128 v[102:105], v86
	s_waitcnt lgkmcnt(1)
	v_mfma_f32_32x32x16_bf16 v[52:67], v[114:117], v[98:101], v[52:67]
	s_waitcnt lgkmcnt(0)
	v_mfma_f32_32x32x16_bf16 v[36:51], v[114:117], v[102:105], v[36:51]
	v_mfma_f32_32x32x16_bf16 v[20:35], v[118:121], v[98:101], v[20:35]
	v_mfma_f32_32x32x16_bf16 v[4:19], v[118:121], v[102:105], v[4:19]
	ds_read_b128 v[98:101], v2 offset:55360
	ds_read_b128 v[102:105], v88
	ds_read_b128 v[110:113], v92
	ds_read_b128 v[114:117], v2 offset:55392
	s_waitcnt lgkmcnt(2)
	v_mfma_f32_32x32x16_bf16 v[52:67], v[98:101], v[102:105], v[52:67]
	s_waitcnt lgkmcnt(1)
	v_mfma_f32_32x32x16_bf16 v[36:51], v[98:101], v[110:113], v[36:51]
	ds_read_b128 v[98:101], v81 offset:59904
	ds_read_b128 v[118:121], v83 offset:59904
	s_waitcnt lgkmcnt(1)
	v_mfma_f32_32x32x16_bf16 v[20:35], v[98:101], v[102:105], v[20:35]
	v_mfma_f32_32x32x16_bf16 v[4:19], v[98:101], v[110:113], v[4:19]
	ds_read_b128 v[98:101], v94
	ds_read_b128 v[102:105], v95
	s_waitcnt lgkmcnt(1)
	v_mfma_f32_32x32x16_bf16 v[52:67], v[114:117], v[98:101], v[52:67]
	s_waitcnt lgkmcnt(0)
	v_mfma_f32_32x32x16_bf16 v[36:51], v[114:117], v[102:105], v[36:51]
	v_mfma_f32_32x32x16_bf16 v[20:35], v[118:121], v[98:101], v[20:35]
	global_load_dwordx4 v[98:101], v[70:71], off offset:1664
	global_load_dwordx4 v[110:113], v[72:73], off offset:1664
	global_load_dwordx4 v[114:117], v[74:75], off offset:1664
	global_load_dwordx4 v[126:129], v[76:77], off offset:1664
	global_load_dwordx4 v[130:133], v[68:69], off offset:1664
	global_load_dwordx4 v[162:165], v[78:79], off offset:1664
	s_waitcnt vmcnt(11)
	ds_write_b128 v80, v[122:125]
	s_waitcnt vmcnt(10)
	ds_write_b128 v80, v[134:137] offset:9216
	s_waitcnt vmcnt(9)
	ds_write_b128 v80, v[138:141] offset:18432
	s_waitcnt vmcnt(8)
	ds_write_b128 v80, v[142:145] offset:27648
	s_waitcnt vmcnt(7)
	ds_write_b128 v80, v[146:149] offset:36864
	s_waitcnt vmcnt(6)
	ds_write_b128 v80, v[158:161] offset:46080
	s_waitcnt lgkmcnt(0)
	s_barrier
; template <bool SWAP, class Epi>
; DI void gemm_tile(const u16* __restrict__ A, int lda, const u16* __restrict__ Bw, int ldb, int K, char* lds, Epi epi) {
;     ...
;   for (int kt = 0; kt < nk; kt += 2) {
;     if (kt + 2 < nk) gload(kt + 2, ra0, rb0);
;     compute(0);
;     lstore(1, ra1, rb1);
;     __syncthreads();
;     if (kt + 3 < nk) gload(kt + 3, ra1, rb1);
;     compute(1);
;     if (kt + 2 < nk) lstore(0, ra0, rb0);
;     __syncthreads();
	v_mfma_f32_32x32x16_bf16 v[4:19], v[118:121], v[102:105], v[4:19]
	ds_read_b128 v[102:105], v2
	ds_read_b128 v[118:121], v84 offset:36864
	ds_read_b128 v[122:125], v2 offset:32
	ds_read_b128 v[134:137], v2 offset:4608
	ds_read_b128 v[138:141], v84 offset:41472
	ds_read_b128 v[142:145], v84 offset:36960
	s_waitcnt lgkmcnt(4)
	v_mfma_f32_32x32x16_bf16 v[52:67], v[102:105], v[118:121], v[52:67]
	s_waitcnt lgkmcnt(1)
	v_mfma_f32_32x32x16_bf16 v[36:51], v[102:105], v[138:141], v[36:51]
	v_mfma_f32_32x32x16_bf16 v[20:35], v[134:137], v[118:121], v[20:35]
	ds_read_b128 v[102:105], v84 offset:36896
	ds_read_b128 v[118:121], v84 offset:36928
	v_mfma_f32_32x32x16_bf16 v[4:19], v[134:137], v[138:141], v[4:19]
	ds_read_b128 v[134:137], v87 offset:41472
	ds_read_b128 v[138:141], v82 offset:4608
	s_waitcnt lgkmcnt(3)
	v_mfma_f32_32x32x16_bf16 v[52:67], v[122:125], v[102:105], v[52:67]
	s_waitcnt lgkmcnt(1)
	v_mfma_f32_32x32x16_bf16 v[36:51], v[122:125], v[134:137], v[36:51]
	s_waitcnt lgkmcnt(0)
	v_mfma_f32_32x32x16_bf16 v[20:35], v[138:141], v[102:105], v[20:35]
	ds_read_b128 v[102:105], v2 offset:64
	ds_read_b128 v[122:125], v2 offset:96
	v_mfma_f32_32x32x16_bf16 v[4:19], v[138:141], v[134:137], v[4:19]
	ds_read_b128 v[134:137], v90 offset:41472
	ds_read_b128 v[138:141], v81 offset:4608
	s_waitcnt lgkmcnt(3)
	v_mfma_f32_32x32x16_bf16 v[52:67], v[102:105], v[118:121], v[52:67]
	s_waitcnt lgkmcnt(1)
	v_mfma_f32_32x32x16_bf16 v[36:51], v[102:105], v[134:137], v[36:51]
	s_waitcnt lgkmcnt(0)
	v_mfma_f32_32x32x16_bf16 v[20:35], v[138:141], v[118:121], v[20:35]
	ds_read_b128 v[102:105], v93 offset:41472
	ds_read_b128 v[118:121], v83 offset:4608
	v_mfma_f32_32x32x16_bf16 v[4:19], v[138:141], v[134:137], v[4:19]
	v_mfma_f32_32x32x16_bf16 v[52:67], v[122:125], v[142:145], v[52:67]
	s_waitcnt lgkmcnt(1)
	v_mfma_f32_32x32x16_bf16 v[36:51], v[122:125], v[102:105], v[36:51]
	s_waitcnt lgkmcnt(0)
	v_mfma_f32_32x32x16_bf16 v[20:35], v[118:121], v[142:145], v[20:35]
	global_load_dwordx4 v[122:125], v[70:71], off offset:1792
	global_load_dwordx4 v[134:137], v[72:73], off offset:1792
	global_load_dwordx4 v[138:141], v[74:75], off offset:1792
	global_load_dwordx4 v[142:145], v[76:77], off offset:1792
	global_load_dwordx4 v[146:149], v[68:69], off offset:1792
	global_load_dwordx4 v[158:161], v[78:79], off offset:1792
	s_waitcnt vmcnt(11)
	ds_write_b128 v80, v[98:101] offset:55296
	s_waitcnt vmcnt(10)
	ds_write_b128 v80, v[110:113] offset:64512
	s_waitcnt vmcnt(9)
	ds_write_b128 v89, v[114:117] offset:18432
	s_waitcnt vmcnt(8)
	ds_write_b128 v89, v[126:129] offset:27648
	s_waitcnt vmcnt(7)
	ds_write_b128 v91, v[130:133]
	s_waitcnt vmcnt(6)
	ds_write_b128 v91, v[162:165] offset:9216
	s_waitcnt lgkmcnt(0)
	s_barrier
	v_mfma_f32_32x32x16_bf16 v[4:19], v[118:121], v[102:105], v[4:19]
	ds_read_b128 v[98:101], v2 offset:55296
	ds_read_b128 v[102:105], v96
	ds_read_b128 v[110:113], v97
	ds_read_b128 v[114:117], v2 offset:55328
	s_waitcnt lgkmcnt(2)
	v_mfma_f32_32x32x16_bf16 v[52:67], v[98:101], v[102:105], v[52:67]
	s_waitcnt lgkmcnt(1)
	v_mfma_f32_32x32x16_bf16 v[36:51], v[98:101], v[110:113], v[36:51]
	ds_read_b128 v[98:101], v2 offset:59904
	ds_read_b128 v[118:121], v82 offset:59904
	s_waitcnt lgkmcnt(1)
	v_mfma_f32_32x32x16_bf16 v[20:35], v[98:101], v[102:105], v[20:35]
	v_mfma_f32_32x32x16_bf16 v[4:19], v[98:101], v[110:113], v[4:19]
	ds_read_b128 v[98:101], v85
	ds_read_b128 v[102:105], v86
	s_waitcnt lgkmcnt(1)
	v_mfma_f32_32x32x16_bf16 v[52:67], v[114:117], v[98:101], v[52:67]
	s_waitcnt lgkmcnt(0)
	v_mfma_f32_32x32x16_bf16 v[36:51], v[114:117], v[102:105], v[36:51]
	v_mfma_f32_32x32x16_bf16 v[20:35], v[118:121], v[98:101], v[20:35]
	v_mfma_f32_32x32x16_bf16 v[4:19], v[118:121], v[102:105], v[4:19]
	ds_read_b128 v[98:101], v2 offset:55360
	ds_read_b128 v[102:105], v88
	ds_read_b128 v[110:113], v92
	ds_read_b128 v[114:117], v2 offset:55392
	s_waitcnt lgkmcnt(2)
	v_mfma_f32_32x32x16_bf16 v[52:67], v[98:101], v[102:105], v[52:67]
	s_waitcnt lgkmcnt(1)
	v_mfma_f32_32x32x16_bf16 v[36:51], v[98:101], v[110:113], v[36:51]
	ds_read_b128 v[98:101], v81 offset:59904
	ds_read_b128 v[118:121], v83 offset:59904
	s_waitcnt lgkmcnt(1)
	v_mfma_f32_32x32x16_bf16 v[20:35], v[98:101], v[102:105], v[20:35]
	v_mfma_f32_32x32x16_bf16 v[4:19], v[98:101], v[110:113], v[4:19]
	ds_read_b128 v[98:101], v94
	ds_read_b128 v[102:105], v95
	s_waitcnt lgkmcnt(1)
	v_mfma_f32_32x32x16_bf16 v[52:67], v[114:117], v[98:101], v[52:67]
	s_waitcnt lgkmcnt(0)
	v_mfma_f32_32x32x16_bf16 v[36:51], v[114:117], v[102:105], v[36:51]
	v_mfma_f32_32x32x16_bf16 v[20:35], v[118:121], v[98:101], v[20:35]
	global_load_dwordx4 v[98:101], v[70:71], off offset:1920
	s_nop 0
	global_load_dwordx4 v[70:73], v[72:73], off offset:1920
	s_nop 0
	global_load_dwordx4 v[110:113], v[74:75], off offset:1920
	s_nop 0
	global_load_dwordx4 v[74:77], v[76:77], off offset:1920
	s_nop 0
	global_load_dwordx4 v[114:117], v[68:69], off offset:1920
	global_load_dwordx4 v[126:129], v[78:79], off offset:1920
	s_waitcnt vmcnt(11)
	ds_write_b128 v80, v[122:125]
	s_waitcnt vmcnt(10)
	ds_write_b128 v80, v[134:137] offset:9216
	s_waitcnt vmcnt(9)
	ds_write_b128 v80, v[138:141] offset:18432
	s_waitcnt vmcnt(8)
	ds_write_b128 v80, v[142:145] offset:27648
	s_waitcnt vmcnt(7)
	ds_write_b128 v80, v[146:149] offset:36864
	s_waitcnt vmcnt(6)
	ds_write_b128 v80, v[158:161] offset:46080
	s_waitcnt lgkmcnt(0)
	s_barrier
; template <bool SWAP, class Epi>
; DI void gemm_tile(const u16* __restrict__ A, int lda, const u16* __restrict__ Bw, int ldb, int K, char* lds, Epi epi) {
;     ...
;   for (int kt = 0; kt < nk; kt += 2) {
;     if (kt + 2 < nk) gload(kt + 2, ra0, rb0);
;     compute(0);
;     lstore(1, ra1, rb1);
;     __syncthreads();
;     if (kt + 3 < nk) gload(kt + 3, ra1, rb1);
;     compute(1);
;     if (kt + 2 < nk) lstore(0, ra0, rb0);
;     __syncthreads();
	v_mfma_f32_32x32x16_bf16 v[4:19], v[118:121], v[102:105], v[4:19]
	ds_read_b128 v[102:105], v2
	ds_read_b128 v[118:121], v84 offset:36864
	ds_read_b128 v[122:125], v2 offset:32
	ds_read_b128 v[130:133], v2 offset:4608
	ds_read_b128 v[134:137], v84 offset:41472
	ds_read_b128 v[138:141], v84 offset:36960
	s_waitcnt lgkmcnt(4)
	v_mfma_f32_32x32x16_bf16 v[52:67], v[102:105], v[118:121], v[52:67]
	s_waitcnt lgkmcnt(1)
	v_mfma_f32_32x32x16_bf16 v[36:51], v[102:105], v[134:137], v[36:51]
	v_mfma_f32_32x32x16_bf16 v[20:35], v[130:133], v[118:121], v[20:35]
	ds_read_b128 v[102:105], v84 offset:36896
	ds_read_b128 v[118:121], v84 offset:36928
	v_mfma_f32_32x32x16_bf16 v[4:19], v[130:133], v[134:137], v[4:19]
	ds_read_b128 v[130:133], v87 offset:41472
	ds_read_b128 v[134:137], v82 offset:4608
	s_waitcnt lgkmcnt(3)
	v_mfma_f32_32x32x16_bf16 v[52:67], v[122:125], v[102:105], v[52:67]
	s_waitcnt lgkmcnt(1)
	v_mfma_f32_32x32x16_bf16 v[36:51], v[122:125], v[130:133], v[36:51]
	s_waitcnt lgkmcnt(0)
	v_mfma_f32_32x32x16_bf16 v[20:35], v[134:137], v[102:105], v[20:35]
	ds_read_b128 v[102:105], v2 offset:64
	ds_read_b128 v[122:125], v2 offset:96
	s_waitcnt lgkmcnt(1)
	v_mfma_f32_32x32x16_bf16 v[52:67], v[102:105], v[118:121], v[52:67]
	v_mfma_f32_32x32x16_bf16 v[4:19], v[134:137], v[130:133], v[4:19]
	ds_read_b128 v[130:133], v90 offset:41472
	ds_read_b128 v[134:137], v81 offset:4608
	s_waitcnt lgkmcnt(1)
	v_mfma_f32_32x32x16_bf16 v[36:51], v[102:105], v[130:133], v[36:51]
	v_mfma_f32_32x32x16_bf16 v[52:67], v[122:125], v[138:141], v[52:67]
	s_waitcnt lgkmcnt(0)
	v_mfma_f32_32x32x16_bf16 v[20:35], v[134:137], v[118:121], v[20:35]
	ds_read_b128 v[102:105], v93 offset:41472
	ds_read_b128 v[118:121], v83 offset:4608
	s_waitcnt vmcnt(5)
	ds_write_b128 v80, v[98:101] offset:55296
	s_waitcnt vmcnt(4)
	ds_write_b128 v80, v[70:73] offset:64512
	s_waitcnt vmcnt(3)
	ds_write_b128 v89, v[110:113] offset:18432
	s_waitcnt vmcnt(2)
	ds_write_b128 v89, v[74:77] offset:27648
	s_waitcnt vmcnt(1)
	ds_write_b128 v91, v[114:117]
	s_waitcnt vmcnt(0)
	ds_write_b128 v91, v[126:129] offset:9216
	s_waitcnt lgkmcnt(0)
	s_barrier
	ds_read_b128 v[68:71], v2 offset:55296
	ds_read_b128 v[72:75], v96
	ds_read_b128 v[76:79], v97
	ds_read_b128 v[96:99], v2 offset:55328
	v_mfma_f32_32x32x16_bf16 v[4:19], v[134:137], v[130:133], v[4:19]
	v_mfma_f32_32x32x16_bf16 v[36:51], v[122:125], v[102:105], v[36:51]
	s_waitcnt lgkmcnt(2)
	v_mfma_f32_32x32x16_bf16 v[52:67], v[68:71], v[72:75], v[52:67]
	v_mfma_f32_32x32x16_bf16 v[20:35], v[118:121], v[138:141], v[20:35]
	v_mfma_f32_32x32x16_bf16 v[4:19], v[118:121], v[102:105], v[4:19]
	ds_read_b128 v[100:103], v2 offset:59904
	s_waitcnt lgkmcnt(2)
	v_mfma_f32_32x32x16_bf16 v[36:51], v[68:71], v[76:79], v[36:51]
	ds_read_b128 v[68:71], v82 offset:59904
	ds_read_b128 v[110:113], v85
	ds_read_b128 v[84:87], v86
	ds_read_b128 v[88:91], v88
	ds_read_b128 v[114:117], v92
	ds_read_b128 v[118:121], v2 offset:55360
	ds_read_b128 v[122:125], v2 offset:55392
	s_waitcnt lgkmcnt(5)
	v_mfma_f32_32x32x16_bf16 v[52:67], v[96:99], v[110:113], v[52:67]
	s_waitcnt lgkmcnt(1)
	v_mfma_f32_32x32x16_bf16 v[52:67], v[118:121], v[88:91], v[52:67]
	v_mfma_f32_32x32x16_bf16 v[20:35], v[100:103], v[72:75], v[20:35]
	ds_read_b128 v[72:75], v81 offset:59904
	ds_read_b128 v[80:83], v83 offset:59904
	ds_read_b128 v[126:129], v94
	ds_read_b128 v[92:95], v95
	s_waitcnt lgkmcnt(0)
	s_barrier
; DI unsigned pk2(float a, float b) { f32x2 v = {a, b}; return __builtin_bit_cast(unsigned, __builtin_convertvector(v, bf2_t)); }
; DI void store_transposed(u16* dst, const f32x16& a, int h, const float* rs  ) {
; #pragma unroll
;   for (int g = 0; g < 4; ++g) {
;     float s0 = 1.f, s1 = 1.f, s2 = 1.f, s3 = 1.f;
;     if (rs) { f32x4 sv = *(const f32x4*)(rs + 8 * g + 4 * h); s0 = sv[0]; s1 = sv[1]; s2 = sv[2]; s3 = sv[3]; }
;     u32x2 v = {pk2(a[4 * g] * s0, a[4 * g + 1] * s1), pk2(a[4 * g + 2] * s2, a[4 * g + 3] * s3)};
;     *(u32x2*)(dst + 8 * g + 4 * h) = v;
;   }
; }
; DI void inproj_tile(const Params& p, int l, int mt, int nt, char* lds) {
;     ...
;     gemm_tile<false>(A, DM, Bw, DM, DM, lds, [&](int mi, int ni, const f32x16& a) {
;       const int b = m0 / PP, t0 = m0 - b * PP + wm * 64 + mi * 32;
;       const int col = c0 + wn * 64 + ni * 32 + r;
;       store_transposed(vt + ((size_t)b * nv + col) * PP + t0, a, h, nullptr);
;     });
	v_mfma_f32_32x32x16_bf16 v[36:51], v[96:99], v[84:87], v[36:51]
	v_mov_b64_e32 v[96:97], s[10:11]
	v_mfma_f32_32x32x16_bf16 v[4:19], v[100:103], v[76:79], v[4:19]
	v_lshlrev_b32_e32 v101, 6, v0
	v_add_u32_e32 v2, s3, v101
	v_or_b32_e32 v78, v2, v107
	v_lshlrev_b32_e32 v100, 6, v108
	v_ashrrev_i32_e32 v79, 31, v78
	v_or_b32_e32 v76, s5, v100
	v_lshl_add_u64 v[78:79], s[0:1], 0, v[78:79]
	v_mfma_f32_32x32x16_bf16 v[52:67], v[122:125], v[126:129], v[52:67]
	v_mad_u64_u32 v[98:99], s[10:11], v78, s12, v[96:97]
	v_ashrrev_i32_e32 v77, 31, v76
	v_mad_i32_i24 v99, v79, s12, v99
	v_lshlrev_b64 v[76:77], 1, v[76:77]
	v_lshl_add_u64 v[78:79], v[98:99], 0, v[76:77]
	v_lshlrev_b32_e32 v2, 3, v106
	v_mfma_f32_32x32x16_bf16 v[20:35], v[68:71], v[110:113], v[20:35]
	v_lshl_add_u64 v[78:79], v[78:79], 0, v[2:3]
	s_nop 3
	v_cvt_pk_bf16_f32 v52, v52, v53
	v_cvt_pk_bf16_f32 v53, v54, v55
	global_store_dwordx2 v[78:79], v[52:53], off
	v_cvt_pk_bf16_f32 v52, v56, v57
	v_cvt_pk_bf16_f32 v53, v58, v59
	global_store_dwordx2 v[78:79], v[52:53], off offset:16
	v_mfma_f32_32x32x16_bf16 v[36:51], v[118:121], v[114:117], v[36:51]
	v_cvt_pk_bf16_f32 v52, v60, v61
	v_cvt_pk_bf16_f32 v53, v62, v63
	global_store_dwordx2 v[78:79], v[52:53], off offset:32
	v_cvt_pk_bf16_f32 v52, v64, v65
	v_cvt_pk_bf16_f32 v53, v66, v67
	global_store_dwordx2 v[78:79], v[52:53], off offset:48
	v_or_b32_e32 v52, s3, v107
	v_mfma_f32_32x32x16_bf16 v[4:19], v[68:71], v[84:87], v[4:19]
	v_add3_u32 v52, v101, v52, 32
	v_ashrrev_i32_e32 v53, 31, v52
	v_lshl_add_u64 v[52:53], s[0:1], 0, v[52:53]
	v_mad_u64_u32 v[54:55], s[0:1], v52, s12, v[96:97]
	v_mad_i32_i24 v55, v53, s12, v55
	v_lshl_add_u64 v[52:53], v[54:55], 0, v[76:77]
	v_mfma_f32_32x32x16_bf16 v[36:51], v[122:125], v[92:95], v[36:51]
	v_lshl_add_u64 v[52:53], v[52:53], 0, v[2:3]
	s_add_i32 s5, s5, 32
	s_mov_b64 s[0:1], 0
	v_mfma_f32_32x32x16_bf16 v[20:35], v[72:75], v[88:91], v[20:35]
	s_nop 7
	v_cvt_pk_bf16_f32 v36, v36, v37
	v_cvt_pk_bf16_f32 v37, v38, v39
	global_store_dwordx2 v[52:53], v[36:37], off
	v_cvt_pk_bf16_f32 v36, v40, v41
	v_cvt_pk_bf16_f32 v37, v42, v43
	global_store_dwordx2 v[52:53], v[36:37], off offset:16
	v_cvt_pk_bf16_f32 v36, v44, v45
	v_mfma_f32_32x32x16_bf16 v[4:19], v[72:75], v[114:117], v[4:19]
	v_cvt_pk_bf16_f32 v37, v46, v47
	global_store_dwordx2 v[52:53], v[36:37], off offset:32
	v_cvt_pk_bf16_f32 v36, v48, v49
	v_cvt_pk_bf16_f32 v37, v50, v51
	global_store_dwordx2 v[52:53], v[36:37], off offset:48
	v_or_b32_e32 v36, s5, v100
	v_ashrrev_i32_e32 v37, 31, v36
	v_mfma_f32_32x32x16_bf16 v[20:35], v[80:83], v[126:129], v[20:35]
	v_lshlrev_b64 v[36:37], 1, v[36:37]
	v_lshl_add_u64 v[38:39], v[98:99], 0, v[36:37]
	v_lshl_add_u64 v[38:39], v[38:39], 0, v[2:3]
	v_mfma_f32_32x32x16_bf16 v[4:19], v[80:83], v[92:95], v[4:19]
	s_nop 7
	v_cvt_pk_bf16_f32 v20, v20, v21
	v_cvt_pk_bf16_f32 v21, v22, v23
	global_store_dwordx2 v[38:39], v[20:21], off
	v_cvt_pk_bf16_f32 v20, v24, v25
	v_cvt_pk_bf16_f32 v21, v26, v27
	global_store_dwordx2 v[38:39], v[20:21], off offset:16
	v_cvt_pk_bf16_f32 v20, v28, v29
	v_cvt_pk_bf16_f32 v21, v30, v31
	global_store_dwordx2 v[38:39], v[20:21], off offset:32
	v_cvt_pk_bf16_f32 v20, v32, v33
	v_cvt_pk_bf16_f32 v21, v34, v35
	global_store_dwordx2 v[38:39], v[20:21], off offset:48
	v_lshl_add_u64 v[20:21], v[54:55], 0, v[36:37]
	v_lshl_add_u64 v[20:21], v[20:21], 0, v[2:3]
	v_cvt_pk_bf16_f32 v4, v4, v5
	v_cvt_pk_bf16_f32 v5, v6, v7
	global_store_dwordx2 v[20:21], v[4:5], off
	v_cvt_pk_bf16_f32 v4, v8, v9
	v_cvt_pk_bf16_f32 v5, v10, v11
	global_store_dwordx2 v[20:21], v[4:5], off offset:16
	v_cvt_pk_bf16_f32 v4, v12, v13
	v_cvt_pk_bf16_f32 v5, v14, v15
	global_store_dwordx2 v[20:21], v[4:5], off offset:32
	v_cvt_pk_bf16_f32 v4, v16, v17
	v_cvt_pk_bf16_f32 v5, v18, v19
	global_store_dwordx2 v[20:21], v[4:5], off offset:48

; template <bool SWAP, class Epi>
; DI void gemm_tile(const u16* __restrict__ A, int lda, const u16* __restrict__ Bw, int ldb, int K, char* lds, Epi epi) {
;     ...
;   gload(0, ra0, rb0);
;   lstore(0, ra0, rb0);
;   gload(1, ra1, rb1);
;   __syncthreads();
;   for (int kt = 0; kt < nk; kt += 2) {
;     if (kt + 2 < nk) gload(kt + 2, ra0, rb0);
;     compute(0);
;     lstore(1, ra1, rb1);
;     __syncthreads();
;     if (kt + 3 < nk) gload(kt + 3, ra1, rb1);
;     compute(1);
.LBB0_358:
	s_andn2_b64 vcc, exec, s[0:1]
	s_cbranch_vccnz .LBB0_323
	v_mov_b32_e32 v30, v152
	v_readlane_b32 s76, v241, 24
	v_readlane_b32 s77, v241, 25
	v_lshrrev_b32_e32 v185, 3, v152
	v_and_b32_e32 v186, 7, v152
	v_lshlrev_b32_e32 v186, 4, v186
	v_lshl_add_u32 v176, v185, 11, v186
	v_add_u32_e32 v177, 0x20000, v176
	v_add_u32_e32 v178, 0x40000, v176
	v_add_u32_e32 v179, 0x60000, v176
	global_load_dwordx4 v[68:71], v176, s[6:7] offset:0
	global_load_dwordx4 v[72:75], v177, s[6:7] offset:0
	global_load_dwordx4 v[76:79], v178, s[6:7] offset:0
	global_load_dwordx4 v[80:83], v179, s[6:7] offset:0
	global_load_dwordx4 v[84:87], v176, s[8:9] offset:0
	global_load_dwordx4 v[88:91], v177, s[8:9] offset:0
	global_load_dwordx4 v[112:115], v176, s[6:7] offset:128
	global_load_dwordx4 v[116:119], v177, s[6:7] offset:128
	global_load_dwordx4 v[120:123], v178, s[6:7] offset:128
	global_load_dwordx4 v[124:127], v179, s[6:7] offset:128
	global_load_dwordx4 v[128:131], v176, s[8:9] offset:128
	global_load_dwordx4 v[132:135], v177, s[8:9] offset:128
	global_load_dwordx4 v[208:211], v176, s[6:7] offset:256
	global_load_dwordx4 v[212:215], v177, s[6:7] offset:256
	global_load_dwordx4 v[216:219], v178, s[6:7] offset:256
	global_load_dwordx4 v[220:223], v179, s[6:7] offset:256
	global_load_dwordx4 v[224:227], v176, s[8:9] offset:256
	global_load_dwordx4 v[228:231], v177, s[8:9] offset:256
	s_movk_i32 s0, 0x90
	v_mad_u32_u24 v180, v185, s0, v186
	v_add_u32_e32 v181, 0xd800, v180
	v_and_b32_e32 v187, 0xdf, v152
	v_lshrrev_b32_e32 v2, 1, v152
	v_and_b32_e32 v2, 16, v2
	v_mad_u32_u24 v182, v187, s0, v2
	v_lshrrev_b32_e32 v187, 2, v152
	v_and_b32_e32 v187, 64, v187
	v_and_or_b32 v187, v152, 31, v187
	v_mad_u32_u24 v183, v187, s0, v2
	v_add_u32_e32 v183, 0x9000, v183
	v_add_u32_e32 v184, 0xd800, v183
	s_waitcnt vmcnt(17)
	ds_write_b128 v180, v[68:71]
	s_waitcnt vmcnt(16)
	ds_write_b128 v180, v[72:75] offset:9216
	global_load_dwordx4 v[68:71], v176, s[6:7] offset:384
	s_waitcnt vmcnt(16)
	ds_write_b128 v180, v[76:79] offset:18432
	global_load_dwordx4 v[72:75], v177, s[6:7] offset:384
	s_waitcnt vmcnt(16)
	ds_write_b128 v180, v[80:83] offset:27648
	global_load_dwordx4 v[76:79], v178, s[6:7] offset:384
	s_waitcnt vmcnt(16)
	ds_write_b128 v180, v[84:87] offset:36864
	global_load_dwordx4 v[80:83], v179, s[6:7] offset:384
	s_waitcnt vmcnt(16)
	ds_write_b128 v180, v[88:91] offset:46080
	global_load_dwordx4 v[84:87], v176, s[8:9] offset:384
	global_load_dwordx4 v[88:91], v177, s[8:9] offset:384
	s_waitcnt lgkmcnt(0)
	s_barrier
	ds_read_b128 v[136:139], v183
	ds_read_b128 v[140:143], v182
	ds_read_b128 v[144:147], v183 offset:4608
	ds_read_b128 v[92:95], v182 offset:4608
	ds_read_b128 v[96:99], v183 offset:32
	ds_read_b128 v[100:103], v182 offset:32
	ds_read_b128 v[168:171], v183 offset:4640
	ds_read_b128 v[172:175], v182 offset:4640
	s_waitcnt lgkmcnt(6)
	v_mfma_f32_32x32x16_bf16 v[52:67], v[136:139], v[140:143], 0
	s_waitcnt lgkmcnt(5)
	v_mfma_f32_32x32x16_bf16 v[36:51], v[144:147], v[140:143], 0
	s_waitcnt lgkmcnt(4)
	v_mfma_f32_32x32x16_bf16 v[20:35], v[136:139], v[92:95], 0
	v_mfma_f32_32x32x16_bf16 v[4:19], v[144:147], v[92:95], 0
	ds_read_b128 v[136:139], v183 offset:64
	ds_read_b128 v[140:143], v182 offset:64
	ds_read_b128 v[144:147], v183 offset:4672
	ds_read_b128 v[92:95], v182 offset:4672
	s_waitcnt lgkmcnt(6)
	v_mfma_f32_32x32x16_bf16 v[52:67], v[96:99], v[100:103], v[52:67]
	s_waitcnt vmcnt(17)
	ds_write_b128 v181, v[112:115]
	s_waitcnt lgkmcnt(6)
	v_mfma_f32_32x32x16_bf16 v[36:51], v[168:171], v[100:103], v[36:51]
	s_waitcnt vmcnt(16)
	ds_write_b128 v181, v[116:119] offset:9216
	global_load_dwordx4 v[112:115], v176, s[6:7] offset:512
	s_waitcnt lgkmcnt(6)
	v_mfma_f32_32x32x16_bf16 v[20:35], v[96:99], v[172:175], v[20:35]
	v_mfma_f32_32x32x16_bf16 v[4:19], v[168:171], v[172:175], v[4:19]
	ds_read_b128 v[96:99], v183 offset:96
	ds_read_b128 v[100:103], v182 offset:96
	ds_read_b128 v[168:171], v183 offset:4704
	ds_read_b128 v[172:175], v182 offset:4704
	s_waitcnt lgkmcnt(8)
	v_mfma_f32_32x32x16_bf16 v[52:67], v[136:139], v[140:143], v[52:67]
	s_waitcnt vmcnt(16)
	ds_write_b128 v181, v[120:123] offset:18432
	global_load_dwordx4 v[116:119], v177, s[6:7] offset:512
	s_waitcnt lgkmcnt(8)
	v_mfma_f32_32x32x16_bf16 v[36:51], v[144:147], v[140:143], v[36:51]
	s_waitcnt vmcnt(16)
	ds_write_b128 v181, v[124:127] offset:27648
	global_load_dwordx4 v[120:123], v178, s[6:7] offset:512
	s_waitcnt lgkmcnt(8)
	v_mfma_f32_32x32x16_bf16 v[20:35], v[136:139], v[92:95], v[20:35]
	v_mfma_f32_32x32x16_bf16 v[4:19], v[144:147], v[92:95], v[4:19]
	s_waitcnt lgkmcnt(4)
	v_mfma_f32_32x32x16_bf16 v[52:67], v[96:99], v[100:103], v[52:67]
	s_waitcnt vmcnt(16)
	ds_write_b128 v181, v[128:131] offset:36864
	global_load_dwordx4 v[124:127], v179, s[6:7] offset:512
	s_waitcnt lgkmcnt(4)
	v_mfma_f32_32x32x16_bf16 v[36:51], v[168:171], v[100:103], v[36:51]
	s_waitcnt vmcnt(16)
	ds_write_b128 v181, v[132:135] offset:46080
	global_load_dwordx4 v[128:131], v176, s[8:9] offset:512
	global_load_dwordx4 v[132:135], v177, s[8:9] offset:512
	s_waitcnt lgkmcnt(4)
	v_mfma_f32_32x32x16_bf16 v[20:35], v[96:99], v[172:175], v[20:35]
	v_mfma_f32_32x32x16_bf16 v[4:19], v[168:171], v[172:175], v[4:19]
	s_waitcnt lgkmcnt(0)
	s_barrier
; template <bool SWAP, class Epi>
; DI void gemm_tile(const u16* __restrict__ A, int lda, const u16* __restrict__ Bw, int ldb, int K, char* lds, Epi epi) {
;     ...
;   for (int kt = 0; kt < nk; kt += 2) {
;     if (kt + 2 < nk) gload(kt + 2, ra0, rb0);
;     compute(0);
;     lstore(1, ra1, rb1);
;     __syncthreads();
;     if (kt + 3 < nk) gload(kt + 3, ra1, rb1);
;     compute(1);
;     if (kt + 2 < nk) lstore(0, ra0, rb0);
;     __syncthreads();
	ds_read_b128 v[136:139], v184
	ds_read_b128 v[140:143], v182 offset:55296
	ds_read_b128 v[144:147], v184 offset:4608
	ds_read_b128 v[92:95], v182 offset:59904
	ds_read_b128 v[96:99], v184 offset:32
	ds_read_b128 v[100:103], v182 offset:55328
	ds_read_b128 v[168:171], v184 offset:4640
	ds_read_b128 v[172:175], v182 offset:59936
	s_waitcnt lgkmcnt(6)
	v_mfma_f32_32x32x16_bf16 v[52:67], v[136:139], v[140:143], v[52:67]
	s_waitcnt lgkmcnt(5)
	v_mfma_f32_32x32x16_bf16 v[36:51], v[144:147], v[140:143], v[36:51]
	s_waitcnt lgkmcnt(4)
	v_mfma_f32_32x32x16_bf16 v[20:35], v[136:139], v[92:95], v[20:35]
	v_mfma_f32_32x32x16_bf16 v[4:19], v[144:147], v[92:95], v[4:19]
	ds_read_b128 v[136:139], v184 offset:64
	ds_read_b128 v[140:143], v182 offset:55360
	ds_read_b128 v[144:147], v184 offset:4672
	ds_read_b128 v[92:95], v182 offset:59968
	s_waitcnt lgkmcnt(6)
	v_mfma_f32_32x32x16_bf16 v[52:67], v[96:99], v[100:103], v[52:67]
	s_waitcnt vmcnt(17)
	ds_write_b128 v180, v[208:211]
	s_waitcnt lgkmcnt(6)
	v_mfma_f32_32x32x16_bf16 v[36:51], v[168:171], v[100:103], v[36:51]
	s_waitcnt vmcnt(16)
	ds_write_b128 v180, v[212:215] offset:9216
	global_load_dwordx4 v[208:211], v176, s[6:7] offset:640
	s_waitcnt lgkmcnt(6)
	v_mfma_f32_32x32x16_bf16 v[20:35], v[96:99], v[172:175], v[20:35]
	v_mfma_f32_32x32x16_bf16 v[4:19], v[168:171], v[172:175], v[4:19]
	ds_read_b128 v[96:99], v184 offset:96
	ds_read_b128 v[100:103], v182 offset:55392
	ds_read_b128 v[168:171], v184 offset:4704
	ds_read_b128 v[172:175], v182 offset:60000
	s_waitcnt lgkmcnt(8)
	v_mfma_f32_32x32x16_bf16 v[52:67], v[136:139], v[140:143], v[52:67]
	s_waitcnt vmcnt(16)
	ds_write_b128 v180, v[216:219] offset:18432
	global_load_dwordx4 v[212:215], v177, s[6:7] offset:640
	s_waitcnt lgkmcnt(8)
	v_mfma_f32_32x32x16_bf16 v[36:51], v[144:147], v[140:143], v[36:51]
	s_waitcnt vmcnt(16)
	ds_write_b128 v180, v[220:223] offset:27648
	global_load_dwordx4 v[216:219], v178, s[6:7] offset:640
	s_waitcnt lgkmcnt(8)
	v_mfma_f32_32x32x16_bf16 v[20:35], v[136:139], v[92:95], v[20:35]
	v_mfma_f32_32x32x16_bf16 v[4:19], v[144:147], v[92:95], v[4:19]
	s_waitcnt lgkmcnt(4)
	v_mfma_f32_32x32x16_bf16 v[52:67], v[96:99], v[100:103], v[52:67]
	s_waitcnt vmcnt(16)
	ds_write_b128 v180, v[224:227] offset:36864
	global_load_dwordx4 v[220:223], v179, s[6:7] offset:640
	s_waitcnt lgkmcnt(4)
	v_mfma_f32_32x32x16_bf16 v[36:51], v[168:171], v[100:103], v[36:51]
	s_waitcnt vmcnt(16)
	ds_write_b128 v180, v[228:231] offset:46080
	global_load_dwordx4 v[224:227], v176, s[8:9] offset:640
	global_load_dwordx4 v[228:231], v177, s[8:9] offset:640
	s_waitcnt lgkmcnt(4)
	v_mfma_f32_32x32x16_bf16 v[20:35], v[96:99], v[172:175], v[20:35]
	v_mfma_f32_32x32x16_bf16 v[4:19], v[168:171], v[172:175], v[4:19]
	s_waitcnt lgkmcnt(0)
	s_barrier
	ds_read_b128 v[136:139], v183
	ds_read_b128 v[140:143], v182
	ds_read_b128 v[144:147], v183 offset:4608
	ds_read_b128 v[92:95], v182 offset:4608
	ds_read_b128 v[96:99], v183 offset:32
	ds_read_b128 v[100:103], v182 offset:32
	ds_read_b128 v[168:171], v183 offset:4640
	ds_read_b128 v[172:175], v182 offset:4640
	s_waitcnt lgkmcnt(6)
	v_mfma_f32_32x32x16_bf16 v[52:67], v[136:139], v[140:143], v[52:67]
	s_waitcnt lgkmcnt(5)
	v_mfma_f32_32x32x16_bf16 v[36:51], v[144:147], v[140:143], v[36:51]
	s_waitcnt lgkmcnt(4)
	v_mfma_f32_32x32x16_bf16 v[20:35], v[136:139], v[92:95], v[20:35]
	v_mfma_f32_32x32x16_bf16 v[4:19], v[144:147], v[92:95], v[4:19]
	ds_read_b128 v[136:139], v183 offset:64
	ds_read_b128 v[140:143], v182 offset:64
	ds_read_b128 v[144:147], v183 offset:4672
	ds_read_b128 v[92:95], v182 offset:4672
	s_waitcnt lgkmcnt(6)
	v_mfma_f32_32x32x16_bf16 v[52:67], v[96:99], v[100:103], v[52:67]
	s_waitcnt vmcnt(17)
	ds_write_b128 v181, v[68:71]
	s_waitcnt lgkmcnt(6)
	v_mfma_f32_32x32x16_bf16 v[36:51], v[168:171], v[100:103], v[36:51]
	s_waitcnt vmcnt(16)
	ds_write_b128 v181, v[72:75] offset:9216
	global_load_dwordx4 v[68:71], v176, s[6:7] offset:768
	s_waitcnt lgkmcnt(6)
	v_mfma_f32_32x32x16_bf16 v[20:35], v[96:99], v[172:175], v[20:35]
	v_mfma_f32_32x32x16_bf16 v[4:19], v[168:171], v[172:175], v[4:19]
	ds_read_b128 v[96:99], v183 offset:96
	ds_read_b128 v[100:103], v182 offset:96
	ds_read_b128 v[168:171], v183 offset:4704
	ds_read_b128 v[172:175], v182 offset:4704
	s_waitcnt lgkmcnt(8)
	v_mfma_f32_32x32x16_bf16 v[52:67], v[136:139], v[140:143], v[52:67]
	s_waitcnt vmcnt(16)
	ds_write_b128 v181, v[76:79] offset:18432
	global_load_dwordx4 v[72:75], v177, s[6:7] offset:768
	s_waitcnt lgkmcnt(8)
	v_mfma_f32_32x32x16_bf16 v[36:51], v[144:147], v[140:143], v[36:51]
	s_waitcnt vmcnt(16)
	ds_write_b128 v181, v[80:83] offset:27648
	global_load_dwordx4 v[76:79], v178, s[6:7] offset:768
	s_waitcnt lgkmcnt(8)
	v_mfma_f32_32x32x16_bf16 v[20:35], v[136:139], v[92:95], v[20:35]
	v_mfma_f32_32x32x16_bf16 v[4:19], v[144:147], v[92:95], v[4:19]
	s_waitcnt lgkmcnt(4)
	v_mfma_f32_32x32x16_bf16 v[52:67], v[96:99], v[100:103], v[52:67]
	s_waitcnt vmcnt(16)
	ds_write_b128 v181, v[84:87] offset:36864
	global_load_dwordx4 v[80:83], v179, s[6:7] offset:768
	s_waitcnt lgkmcnt(4)
	v_mfma_f32_32x32x16_bf16 v[36:51], v[168:171], v[100:103], v[36:51]
	s_waitcnt vmcnt(16)
	ds_write_b128 v181, v[88:91] offset:46080
	global_load_dwordx4 v[84:87], v176, s[8:9] offset:768
	global_load_dwordx4 v[88:91], v177, s[8:9] offset:768
	s_waitcnt lgkmcnt(4)
	v_mfma_f32_32x32x16_bf16 v[20:35], v[96:99], v[172:175], v[20:35]
	v_mfma_f32_32x32x16_bf16 v[4:19], v[168:171], v[172:175], v[4:19]
	s_waitcnt lgkmcnt(0)
	s_barrier
; template <bool SWAP, class Epi>
; DI void gemm_tile(const u16* __restrict__ A, int lda, const u16* __restrict__ Bw, int ldb, int K, char* lds, Epi epi) {
;     ...
;   for (int kt = 0; kt < nk; kt += 2) {
;     if (kt + 2 < nk) gload(kt + 2, ra0, rb0);
;     compute(0);
;     lstore(1, ra1, rb1);
;     __syncthreads();
;     if (kt + 3 < nk) gload(kt + 3, ra1, rb1);
;     compute(1);
;     if (kt + 2 < nk) lstore(0, ra0, rb0);
;     __syncthreads();
	ds_read_b128 v[136:139], v184
	ds_read_b128 v[140:143], v182 offset:55296
	ds_read_b128 v[144:147], v184 offset:4608
	ds_read_b128 v[92:95], v182 offset:59904
	ds_read_b128 v[96:99], v184 offset:32
	ds_read_b128 v[100:103], v182 offset:55328
	ds_read_b128 v[168:171], v184 offset:4640
	ds_read_b128 v[172:175], v182 offset:59936
	s_waitcnt lgkmcnt(6)
	v_mfma_f32_32x32x16_bf16 v[52:67], v[136:139], v[140:143], v[52:67]
	s_waitcnt lgkmcnt(5)
	v_mfma_f32_32x32x16_bf16 v[36:51], v[144:147], v[140:143], v[36:51]
	s_waitcnt lgkmcnt(4)
	v_mfma_f32_32x32x16_bf16 v[20:35], v[136:139], v[92:95], v[20:35]
	v_mfma_f32_32x32x16_bf16 v[4:19], v[144:147], v[92:95], v[4:19]
	ds_read_b128 v[136:139], v184 offset:64
	ds_read_b128 v[140:143], v182 offset:55360
	ds_read_b128 v[144:147], v184 offset:4672
	ds_read_b128 v[92:95], v182 offset:59968
	s_waitcnt lgkmcnt(6)
	v_mfma_f32_32x32x16_bf16 v[52:67], v[96:99], v[100:103], v[52:67]
	s_waitcnt vmcnt(17)
	ds_write_b128 v180, v[112:115]
	s_waitcnt lgkmcnt(6)
	v_mfma_f32_32x32x16_bf16 v[36:51], v[168:171], v[100:103], v[36:51]
	s_waitcnt vmcnt(16)
	ds_write_b128 v180, v[116:119] offset:9216
	global_load_dwordx4 v[112:115], v176, s[6:7] offset:896
	s_waitcnt lgkmcnt(6)
	v_mfma_f32_32x32x16_bf16 v[20:35], v[96:99], v[172:175], v[20:35]
	v_mfma_f32_32x32x16_bf16 v[4:19], v[168:171], v[172:175], v[4:19]
	ds_read_b128 v[96:99], v184 offset:96
	ds_read_b128 v[100:103], v182 offset:55392
	ds_read_b128 v[168:171], v184 offset:4704
	ds_read_b128 v[172:175], v182 offset:60000
	s_waitcnt lgkmcnt(8)
	v_mfma_f32_32x32x16_bf16 v[52:67], v[136:139], v[140:143], v[52:67]
	s_waitcnt vmcnt(16)
	ds_write_b128 v180, v[120:123] offset:18432
	global_load_dwordx4 v[116:119], v177, s[6:7] offset:896
	s_waitcnt lgkmcnt(8)
	v_mfma_f32_32x32x16_bf16 v[36:51], v[144:147], v[140:143], v[36:51]
	s_waitcnt vmcnt(16)
	ds_write_b128 v180, v[124:127] offset:27648
	global_load_dwordx4 v[120:123], v178, s[6:7] offset:896
	s_waitcnt lgkmcnt(8)
	v_mfma_f32_32x32x16_bf16 v[20:35], v[136:139], v[92:95], v[20:35]
	v_mfma_f32_32x32x16_bf16 v[4:19], v[144:147], v[92:95], v[4:19]
	s_waitcnt lgkmcnt(4)
	v_mfma_f32_32x32x16_bf16 v[52:67], v[96:99], v[100:103], v[52:67]
	s_waitcnt vmcnt(16)
	ds_write_b128 v180, v[128:131] offset:36864
	global_load_dwordx4 v[124:127], v179, s[6:7] offset:896
	s_waitcnt lgkmcnt(4)
	v_mfma_f32_32x32x16_bf16 v[36:51], v[168:171], v[100:103], v[36:51]
	s_waitcnt vmcnt(16)
	ds_write_b128 v180, v[132:135] offset:46080
	global_load_dwordx4 v[128:131], v176, s[8:9] offset:896
	global_load_dwordx4 v[132:135], v177, s[8:9] offset:896
	s_waitcnt lgkmcnt(4)
	v_mfma_f32_32x32x16_bf16 v[20:35], v[96:99], v[172:175], v[20:35]
	v_mfma_f32_32x32x16_bf16 v[4:19], v[168:171], v[172:175], v[4:19]
	s_waitcnt lgkmcnt(0)
	s_barrier
	ds_read_b128 v[136:139], v183
	ds_read_b128 v[140:143], v182
	ds_read_b128 v[144:147], v183 offset:4608
	ds_read_b128 v[92:95], v182 offset:4608
	ds_read_b128 v[96:99], v183 offset:32
	ds_read_b128 v[100:103], v182 offset:32
	ds_read_b128 v[168:171], v183 offset:4640
	ds_read_b128 v[172:175], v182 offset:4640
	s_waitcnt lgkmcnt(6)
	v_mfma_f32_32x32x16_bf16 v[52:67], v[136:139], v[140:143], v[52:67]
	s_waitcnt lgkmcnt(5)
	v_mfma_f32_32x32x16_bf16 v[36:51], v[144:147], v[140:143], v[36:51]
	s_waitcnt lgkmcnt(4)
	v_mfma_f32_32x32x16_bf16 v[20:35], v[136:139], v[92:95], v[20:35]
	v_mfma_f32_32x32x16_bf16 v[4:19], v[144:147], v[92:95], v[4:19]
	ds_read_b128 v[136:139], v183 offset:64
	ds_read_b128 v[140:143], v182 offset:64
	ds_read_b128 v[144:147], v183 offset:4672
	ds_read_b128 v[92:95], v182 offset:4672
	s_waitcnt lgkmcnt(6)
	v_mfma_f32_32x32x16_bf16 v[52:67], v[96:99], v[100:103], v[52:67]
	s_waitcnt vmcnt(17)
	ds_write_b128 v181, v[208:211]
	s_waitcnt lgkmcnt(6)
	v_mfma_f32_32x32x16_bf16 v[36:51], v[168:171], v[100:103], v[36:51]
	s_waitcnt vmcnt(16)
	ds_write_b128 v181, v[212:215] offset:9216
	global_load_dwordx4 v[208:211], v176, s[6:7] offset:1024
	s_waitcnt lgkmcnt(6)
	v_mfma_f32_32x32x16_bf16 v[20:35], v[96:99], v[172:175], v[20:35]
	v_mfma_f32_32x32x16_bf16 v[4:19], v[168:171], v[172:175], v[4:19]
	ds_read_b128 v[96:99], v183 offset:96
	ds_read_b128 v[100:103], v182 offset:96
	ds_read_b128 v[168:171], v183 offset:4704
	ds_read_b128 v[172:175], v182 offset:4704
	s_waitcnt lgkmcnt(8)
	v_mfma_f32_32x32x16_bf16 v[52:67], v[136:139], v[140:143], v[52:67]
	s_waitcnt vmcnt(16)
	ds_write_b128 v181, v[216:219] offset:18432
	global_load_dwordx4 v[212:215], v177, s[6:7] offset:1024
	s_waitcnt lgkmcnt(8)
	v_mfma_f32_32x32x16_bf16 v[36:51], v[144:147], v[140:143], v[36:51]
	s_waitcnt vmcnt(16)
	ds_write_b128 v181, v[220:223] offset:27648
	global_load_dwordx4 v[216:219], v178, s[6:7] offset:1024
	s_waitcnt lgkmcnt(8)
	v_mfma_f32_32x32x16_bf16 v[20:35], v[136:139], v[92:95], v[20:35]
	v_mfma_f32_32x32x16_bf16 v[4:19], v[144:147], v[92:95], v[4:19]
	s_waitcnt lgkmcnt(4)
	v_mfma_f32_32x32x16_bf16 v[52:67], v[96:99], v[100:103], v[52:67]
	s_waitcnt vmcnt(16)
	ds_write_b128 v181, v[224:227] offset:36864
	global_load_dwordx4 v[220:223], v179, s[6:7] offset:1024
	s_waitcnt lgkmcnt(4)
	v_mfma_f32_32x32x16_bf16 v[36:51], v[168:171], v[100:103], v[36:51]
	s_waitcnt vmcnt(16)
	ds_write_b128 v181, v[228:231] offset:46080
	global_load_dwordx4 v[224:227], v176, s[8:9] offset:1024
	global_load_dwordx4 v[228:231], v177, s[8:9] offset:1024
	s_waitcnt lgkmcnt(4)
	v_mfma_f32_32x32x16_bf16 v[20:35], v[96:99], v[172:175], v[20:35]
	v_mfma_f32_32x32x16_bf16 v[4:19], v[168:171], v[172:175], v[4:19]
	s_waitcnt lgkmcnt(0)
	s_barrier
; template <bool SWAP, class Epi>
; DI void gemm_tile(const u16* __restrict__ A, int lda, const u16* __restrict__ Bw, int ldb, int K, char* lds, Epi epi) {
;     ...
;   for (int kt = 0; kt < nk; kt += 2) {
;     if (kt + 2 < nk) gload(kt + 2, ra0, rb0);
;     compute(0);
;     lstore(1, ra1, rb1);
;     __syncthreads();
;     if (kt + 3 < nk) gload(kt + 3, ra1, rb1);
;     compute(1);
;     if (kt + 2 < nk) lstore(0, ra0, rb0);
;     __syncthreads();
	ds_read_b128 v[136:139], v184
	ds_read_b128 v[140:143], v182 offset:55296
	ds_read_b128 v[144:147], v184 offset:4608
	ds_read_b128 v[92:95], v182 offset:59904
	ds_read_b128 v[96:99], v184 offset:32
	ds_read_b128 v[100:103], v182 offset:55328
	ds_read_b128 v[168:171], v184 offset:4640
	ds_read_b128 v[172:175], v182 offset:59936
	s_waitcnt lgkmcnt(6)
	v_mfma_f32_32x32x16_bf16 v[52:67], v[136:139], v[140:143], v[52:67]
	s_waitcnt lgkmcnt(5)
	v_mfma_f32_32x32x16_bf16 v[36:51], v[144:147], v[140:143], v[36:51]
	s_waitcnt lgkmcnt(4)
	v_mfma_f32_32x32x16_bf16 v[20:35], v[136:139], v[92:95], v[20:35]
	v_mfma_f32_32x32x16_bf16 v[4:19], v[144:147], v[92:95], v[4:19]
	ds_read_b128 v[136:139], v184 offset:64
	ds_read_b128 v[140:143], v182 offset:55360
	ds_read_b128 v[144:147], v184 offset:4672
	ds_read_b128 v[92:95], v182 offset:59968
	s_waitcnt lgkmcnt(6)
	v_mfma_f32_32x32x16_bf16 v[52:67], v[96:99], v[100:103], v[52:67]
	s_waitcnt vmcnt(17)
	ds_write_b128 v180, v[68:71]
	s_waitcnt lgkmcnt(6)
	v_mfma_f32_32x32x16_bf16 v[36:51], v[168:171], v[100:103], v[36:51]
	s_waitcnt vmcnt(16)
	ds_write_b128 v180, v[72:75] offset:9216
	global_load_dwordx4 v[68:71], v176, s[6:7] offset:1152
	s_waitcnt lgkmcnt(6)
	v_mfma_f32_32x32x16_bf16 v[20:35], v[96:99], v[172:175], v[20:35]
	v_mfma_f32_32x32x16_bf16 v[4:19], v[168:171], v[172:175], v[4:19]
	ds_read_b128 v[96:99], v184 offset:96
	ds_read_b128 v[100:103], v182 offset:55392
	ds_read_b128 v[168:171], v184 offset:4704
	ds_read_b128 v[172:175], v182 offset:60000
	s_waitcnt lgkmcnt(8)
	v_mfma_f32_32x32x16_bf16 v[52:67], v[136:139], v[140:143], v[52:67]
	s_waitcnt vmcnt(16)
	ds_write_b128 v180, v[76:79] offset:18432
	global_load_dwordx4 v[72:75], v177, s[6:7] offset:1152
	s_waitcnt lgkmcnt(8)
	v_mfma_f32_32x32x16_bf16 v[36:51], v[144:147], v[140:143], v[36:51]
	s_waitcnt vmcnt(16)
	ds_write_b128 v180, v[80:83] offset:27648
	global_load_dwordx4 v[76:79], v178, s[6:7] offset:1152
	s_waitcnt lgkmcnt(8)
	v_mfma_f32_32x32x16_bf16 v[20:35], v[136:139], v[92:95], v[20:35]
	v_mfma_f32_32x32x16_bf16 v[4:19], v[144:147], v[92:95], v[4:19]
	s_waitcnt lgkmcnt(4)
	v_mfma_f32_32x32x16_bf16 v[52:67], v[96:99], v[100:103], v[52:67]
	s_waitcnt vmcnt(16)
	ds_write_b128 v180, v[84:87] offset:36864
	global_load_dwordx4 v[80:83], v179, s[6:7] offset:1152
	s_waitcnt lgkmcnt(4)
	v_mfma_f32_32x32x16_bf16 v[36:51], v[168:171], v[100:103], v[36:51]
	s_waitcnt vmcnt(16)
	ds_write_b128 v180, v[88:91] offset:46080
	global_load_dwordx4 v[84:87], v176, s[8:9] offset:1152
	global_load_dwordx4 v[88:91], v177, s[8:9] offset:1152
	s_waitcnt lgkmcnt(4)
	v_mfma_f32_32x32x16_bf16 v[20:35], v[96:99], v[172:175], v[20:35]
	v_mfma_f32_32x32x16_bf16 v[4:19], v[168:171], v[172:175], v[4:19]
	s_waitcnt lgkmcnt(0)
	s_barrier
	ds_read_b128 v[136:139], v183
	ds_read_b128 v[140:143], v182
	ds_read_b128 v[144:147], v183 offset:4608
	ds_read_b128 v[92:95], v182 offset:4608
	ds_read_b128 v[96:99], v183 offset:32
	ds_read_b128 v[100:103], v182 offset:32
	ds_read_b128 v[168:171], v183 offset:4640
	ds_read_b128 v[172:175], v182 offset:4640
	s_waitcnt lgkmcnt(6)
	v_mfma_f32_32x32x16_bf16 v[52:67], v[136:139], v[140:143], v[52:67]
	s_waitcnt lgkmcnt(5)
	v_mfma_f32_32x32x16_bf16 v[36:51], v[144:147], v[140:143], v[36:51]
	s_waitcnt lgkmcnt(4)
	v_mfma_f32_32x32x16_bf16 v[20:35], v[136:139], v[92:95], v[20:35]
	v_mfma_f32_32x32x16_bf16 v[4:19], v[144:147], v[92:95], v[4:19]
	ds_read_b128 v[136:139], v183 offset:64
	ds_read_b128 v[140:143], v182 offset:64
	ds_read_b128 v[144:147], v183 offset:4672
	ds_read_b128 v[92:95], v182 offset:4672
	s_waitcnt lgkmcnt(6)
	v_mfma_f32_32x32x16_bf16 v[52:67], v[96:99], v[100:103], v[52:67]
	s_waitcnt vmcnt(17)
	ds_write_b128 v181, v[112:115]
	s_waitcnt lgkmcnt(6)
	v_mfma_f32_32x32x16_bf16 v[36:51], v[168:171], v[100:103], v[36:51]
	s_waitcnt vmcnt(16)
	ds_write_b128 v181, v[116:119] offset:9216
	global_load_dwordx4 v[112:115], v176, s[6:7] offset:1280
	s_waitcnt lgkmcnt(6)
	v_mfma_f32_32x32x16_bf16 v[20:35], v[96:99], v[172:175], v[20:35]
	v_mfma_f32_32x32x16_bf16 v[4:19], v[168:171], v[172:175], v[4:19]
	ds_read_b128 v[96:99], v183 offset:96
	ds_read_b128 v[100:103], v182 offset:96
	ds_read_b128 v[168:171], v183 offset:4704
	ds_read_b128 v[172:175], v182 offset:4704
	s_waitcnt lgkmcnt(8)
	v_mfma_f32_32x32x16_bf16 v[52:67], v[136:139], v[140:143], v[52:67]
	s_waitcnt vmcnt(16)
	ds_write_b128 v181, v[120:123] offset:18432
	global_load_dwordx4 v[116:119], v177, s[6:7] offset:1280
	s_waitcnt lgkmcnt(8)
	v_mfma_f32_32x32x16_bf16 v[36:51], v[144:147], v[140:143], v[36:51]
	s_waitcnt vmcnt(16)
	ds_write_b128 v181, v[124:127] offset:27648
	global_load_dwordx4 v[120:123], v178, s[6:7] offset:1280
	s_waitcnt lgkmcnt(8)
	v_mfma_f32_32x32x16_bf16 v[20:35], v[136:139], v[92:95], v[20:35]
	v_mfma_f32_32x32x16_bf16 v[4:19], v[144:147], v[92:95], v[4:19]
	s_waitcnt lgkmcnt(4)
	v_mfma_f32_32x32x16_bf16 v[52:67], v[96:99], v[100:103], v[52:67]
	s_waitcnt vmcnt(16)
	ds_write_b128 v181, v[128:131] offset:36864
	global_load_dwordx4 v[124:127], v179, s[6:7] offset:1280
	s_waitcnt lgkmcnt(4)
	v_mfma_f32_32x32x16_bf16 v[36:51], v[168:171], v[100:103], v[36:51]
	s_waitcnt vmcnt(16)
	ds_write_b128 v181, v[132:135] offset:46080
	global_load_dwordx4 v[128:131], v176, s[8:9] offset:1280
	global_load_dwordx4 v[132:135], v177, s[8:9] offset:1280
	s_waitcnt lgkmcnt(4)
	v_mfma_f32_32x32x16_bf16 v[20:35], v[96:99], v[172:175], v[20:35]
	v_mfma_f32_32x32x16_bf16 v[4:19], v[168:171], v[172:175], v[4:19]
	s_waitcnt lgkmcnt(0)
	s_barrier
; template <bool SWAP, class Epi>
; DI void gemm_tile(const u16* __restrict__ A, int lda, const u16* __restrict__ Bw, int ldb, int K, char* lds, Epi epi) {
;     ...
;   for (int kt = 0; kt < nk; kt += 2) {
;     if (kt + 2 < nk) gload(kt + 2, ra0, rb0);
;     compute(0);
;     lstore(1, ra1, rb1);
;     __syncthreads();
;     if (kt + 3 < nk) gload(kt + 3, ra1, rb1);
;     compute(1);
;     if (kt + 2 < nk) lstore(0, ra0, rb0);
;     __syncthreads();
	ds_read_b128 v[136:139], v184
	ds_read_b128 v[140:143], v182 offset:55296
	ds_read_b128 v[144:147], v184 offset:4608
	ds_read_b128 v[92:95], v182 offset:59904
	ds_read_b128 v[96:99], v184 offset:32
	ds_read_b128 v[100:103], v182 offset:55328
	ds_read_b128 v[168:171], v184 offset:4640
	ds_read_b128 v[172:175], v182 offset:59936
	s_waitcnt lgkmcnt(6)
	v_mfma_f32_32x32x16_bf16 v[52:67], v[136:139], v[140:143], v[52:67]
	s_waitcnt lgkmcnt(5)
	v_mfma_f32_32x32x16_bf16 v[36:51], v[144:147], v[140:143], v[36:51]
	s_waitcnt lgkmcnt(4)
	v_mfma_f32_32x32x16_bf16 v[20:35], v[136:139], v[92:95], v[20:35]
	v_mfma_f32_32x32x16_bf16 v[4:19], v[144:147], v[92:95], v[4:19]
	ds_read_b128 v[136:139], v184 offset:64
	ds_read_b128 v[140:143], v182 offset:55360
	ds_read_b128 v[144:147], v184 offset:4672
	ds_read_b128 v[92:95], v182 offset:59968
	s_waitcnt lgkmcnt(6)
	v_mfma_f32_32x32x16_bf16 v[52:67], v[96:99], v[100:103], v[52:67]
	s_waitcnt vmcnt(17)
	ds_write_b128 v180, v[208:211]
	s_waitcnt lgkmcnt(6)
	v_mfma_f32_32x32x16_bf16 v[36:51], v[168:171], v[100:103], v[36:51]
	s_waitcnt vmcnt(16)
	ds_write_b128 v180, v[212:215] offset:9216
	global_load_dwordx4 v[208:211], v176, s[6:7] offset:1408
	s_waitcnt lgkmcnt(6)
	v_mfma_f32_32x32x16_bf16 v[20:35], v[96:99], v[172:175], v[20:35]
	v_mfma_f32_32x32x16_bf16 v[4:19], v[168:171], v[172:175], v[4:19]
	ds_read_b128 v[96:99], v184 offset:96
	ds_read_b128 v[100:103], v182 offset:55392
	ds_read_b128 v[168:171], v184 offset:4704
	ds_read_b128 v[172:175], v182 offset:60000
	s_waitcnt lgkmcnt(8)
	v_mfma_f32_32x32x16_bf16 v[52:67], v[136:139], v[140:143], v[52:67]
	s_waitcnt vmcnt(16)
	ds_write_b128 v180, v[216:219] offset:18432
	global_load_dwordx4 v[212:215], v177, s[6:7] offset:1408
	s_waitcnt lgkmcnt(8)
	v_mfma_f32_32x32x16_bf16 v[36:51], v[144:147], v[140:143], v[36:51]
	s_waitcnt vmcnt(16)
	ds_write_b128 v180, v[220:223] offset:27648
	global_load_dwordx4 v[216:219], v178, s[6:7] offset:1408
	s_waitcnt lgkmcnt(8)
	v_mfma_f32_32x32x16_bf16 v[20:35], v[136:139], v[92:95], v[20:35]
	v_mfma_f32_32x32x16_bf16 v[4:19], v[144:147], v[92:95], v[4:19]
	s_waitcnt lgkmcnt(4)
	v_mfma_f32_32x32x16_bf16 v[52:67], v[96:99], v[100:103], v[52:67]
	s_waitcnt vmcnt(16)
	ds_write_b128 v180, v[224:227] offset:36864
	global_load_dwordx4 v[220:223], v179, s[6:7] offset:1408
	s_waitcnt lgkmcnt(4)
	v_mfma_f32_32x32x16_bf16 v[36:51], v[168:171], v[100:103], v[36:51]
	s_waitcnt vmcnt(16)
	ds_write_b128 v180, v[228:231] offset:46080
	global_load_dwordx4 v[224:227], v176, s[8:9] offset:1408
	global_load_dwordx4 v[228:231], v177, s[8:9] offset:1408
	s_waitcnt lgkmcnt(4)
	v_mfma_f32_32x32x16_bf16 v[20:35], v[96:99], v[172:175], v[20:35]
	v_mfma_f32_32x32x16_bf16 v[4:19], v[168:171], v[172:175], v[4:19]
	s_waitcnt lgkmcnt(0)
	s_barrier
	ds_read_b128 v[136:139], v183
	ds_read_b128 v[140:143], v182
	ds_read_b128 v[144:147], v183 offset:4608
	ds_read_b128 v[92:95], v182 offset:4608
	ds_read_b128 v[96:99], v183 offset:32
	ds_read_b128 v[100:103], v182 offset:32
	ds_read_b128 v[168:171], v183 offset:4640
	ds_read_b128 v[172:175], v182 offset:4640
	s_waitcnt lgkmcnt(6)
	v_mfma_f32_32x32x16_bf16 v[52:67], v[136:139], v[140:143], v[52:67]
	s_waitcnt lgkmcnt(5)
	v_mfma_f32_32x32x16_bf16 v[36:51], v[144:147], v[140:143], v[36:51]
	s_waitcnt lgkmcnt(4)
	v_mfma_f32_32x32x16_bf16 v[20:35], v[136:139], v[92:95], v[20:35]
	v_mfma_f32_32x32x16_bf16 v[4:19], v[144:147], v[92:95], v[4:19]
	ds_read_b128 v[136:139], v183 offset:64
	ds_read_b128 v[140:143], v182 offset:64
	ds_read_b128 v[144:147], v183 offset:4672
	ds_read_b128 v[92:95], v182 offset:4672
	s_waitcnt lgkmcnt(6)
	v_mfma_f32_32x32x16_bf16 v[52:67], v[96:99], v[100:103], v[52:67]
	s_waitcnt vmcnt(17)
	ds_write_b128 v181, v[68:71]
	s_waitcnt lgkmcnt(6)
	v_mfma_f32_32x32x16_bf16 v[36:51], v[168:171], v[100:103], v[36:51]
	s_waitcnt vmcnt(16)
	ds_write_b128 v181, v[72:75] offset:9216
	global_load_dwordx4 v[68:71], v176, s[6:7] offset:1536
	s_waitcnt lgkmcnt(6)
	v_mfma_f32_32x32x16_bf16 v[20:35], v[96:99], v[172:175], v[20:35]
	v_mfma_f32_32x32x16_bf16 v[4:19], v[168:171], v[172:175], v[4:19]
	ds_read_b128 v[96:99], v183 offset:96
	ds_read_b128 v[100:103], v182 offset:96
	ds_read_b128 v[168:171], v183 offset:4704
	ds_read_b128 v[172:175], v182 offset:4704
	s_waitcnt lgkmcnt(8)
	v_mfma_f32_32x32x16_bf16 v[52:67], v[136:139], v[140:143], v[52:67]
	s_waitcnt vmcnt(16)
	ds_write_b128 v181, v[76:79] offset:18432
	global_load_dwordx4 v[72:75], v177, s[6:7] offset:1536
	s_waitcnt lgkmcnt(8)
	v_mfma_f32_32x32x16_bf16 v[36:51], v[144:147], v[140:143], v[36:51]
	s_waitcnt vmcnt(16)
	ds_write_b128 v181, v[80:83] offset:27648
	global_load_dwordx4 v[76:79], v178, s[6:7] offset:1536
	s_waitcnt lgkmcnt(8)
	v_mfma_f32_32x32x16_bf16 v[20:35], v[136:139], v[92:95], v[20:35]
	v_mfma_f32_32x32x16_bf16 v[4:19], v[144:147], v[92:95], v[4:19]
	s_waitcnt lgkmcnt(4)
	v_mfma_f32_32x32x16_bf16 v[52:67], v[96:99], v[100:103], v[52:67]
	s_waitcnt vmcnt(16)
	ds_write_b128 v181, v[84:87] offset:36864
	global_load_dwordx4 v[80:83], v179, s[6:7] offset:1536
	s_waitcnt lgkmcnt(4)
	v_mfma_f32_32x32x16_bf16 v[36:51], v[168:171], v[100:103], v[36:51]
	s_waitcnt vmcnt(16)
	ds_write_b128 v181, v[88:91] offset:46080
	global_load_dwordx4 v[84:87], v176, s[8:9] offset:1536
	global_load_dwordx4 v[88:91], v177, s[8:9] offset:1536
	s_waitcnt lgkmcnt(4)
	v_mfma_f32_32x32x16_bf16 v[20:35], v[96:99], v[172:175], v[20:35]
	v_mfma_f32_32x32x16_bf16 v[4:19], v[168:171], v[172:175], v[4:19]
	s_waitcnt lgkmcnt(0)
	s_barrier
; template <bool SWAP, class Epi>
; DI void gemm_tile(const u16* __restrict__ A, int lda, const u16* __restrict__ Bw, int ldb, int K, char* lds, Epi epi) {
;     ...
;   for (int kt = 0; kt < nk; kt += 2) {
;     if (kt + 2 < nk) gload(kt + 2, ra0, rb0);
;     compute(0);
;     lstore(1, ra1, rb1);
;     __syncthreads();
;     if (kt + 3 < nk) gload(kt + 3, ra1, rb1);
;     compute(1);
;     if (kt + 2 < nk) lstore(0, ra0, rb0);
;     __syncthreads();
	ds_read_b128 v[136:139], v184
	ds_read_b128 v[140:143], v182 offset:55296
	ds_read_b128 v[144:147], v184 offset:4608
	ds_read_b128 v[92:95], v182 offset:59904
	ds_read_b128 v[96:99], v184 offset:32
	ds_read_b128 v[100:103], v182 offset:55328
	ds_read_b128 v[168:171], v184 offset:4640
	ds_read_b128 v[172:175], v182 offset:59936
	s_waitcnt lgkmcnt(6)
	v_mfma_f32_32x32x16_bf16 v[52:67], v[136:139], v[140:143], v[52:67]
	s_waitcnt lgkmcnt(5)
	v_mfma_f32_32x32x16_bf16 v[36:51], v[144:147], v[140:143], v[36:51]
	s_waitcnt lgkmcnt(4)
	v_mfma_f32_32x32x16_bf16 v[20:35], v[136:139], v[92:95], v[20:35]
	v_mfma_f32_32x32x16_bf16 v[4:19], v[144:147], v[92:95], v[4:19]
	ds_read_b128 v[136:139], v184 offset:64
	ds_read_b128 v[140:143], v182 offset:55360
	ds_read_b128 v[144:147], v184 offset:4672
	ds_read_b128 v[92:95], v182 offset:59968
	s_waitcnt lgkmcnt(6)
	v_mfma_f32_32x32x16_bf16 v[52:67], v[96:99], v[100:103], v[52:67]
	s_waitcnt vmcnt(17)
	ds_write_b128 v180, v[112:115]
	s_waitcnt lgkmcnt(6)
	v_mfma_f32_32x32x16_bf16 v[36:51], v[168:171], v[100:103], v[36:51]
	s_waitcnt vmcnt(16)
	ds_write_b128 v180, v[116:119] offset:9216
	global_load_dwordx4 v[112:115], v176, s[6:7] offset:1664
	s_waitcnt lgkmcnt(6)
	v_mfma_f32_32x32x16_bf16 v[20:35], v[96:99], v[172:175], v[20:35]
	v_mfma_f32_32x32x16_bf16 v[4:19], v[168:171], v[172:175], v[4:19]
	ds_read_b128 v[96:99], v184 offset:96
	ds_read_b128 v[100:103], v182 offset:55392
	ds_read_b128 v[168:171], v184 offset:4704
	ds_read_b128 v[172:175], v182 offset:60000
	s_waitcnt lgkmcnt(8)
	v_mfma_f32_32x32x16_bf16 v[52:67], v[136:139], v[140:143], v[52:67]
	s_waitcnt vmcnt(16)
	ds_write_b128 v180, v[120:123] offset:18432
	global_load_dwordx4 v[116:119], v177, s[6:7] offset:1664
	s_waitcnt lgkmcnt(8)
	v_mfma_f32_32x32x16_bf16 v[36:51], v[144:147], v[140:143], v[36:51]
	s_waitcnt vmcnt(16)
	ds_write_b128 v180, v[124:127] offset:27648
	global_load_dwordx4 v[120:123], v178, s[6:7] offset:1664
	s_waitcnt lgkmcnt(8)
	v_mfma_f32_32x32x16_bf16 v[20:35], v[136:139], v[92:95], v[20:35]
	v_mfma_f32_32x32x16_bf16 v[4:19], v[144:147], v[92:95], v[4:19]
	s_waitcnt lgkmcnt(4)
	v_mfma_f32_32x32x16_bf16 v[52:67], v[96:99], v[100:103], v[52:67]
	s_waitcnt vmcnt(16)
	ds_write_b128 v180, v[128:131] offset:36864
	global_load_dwordx4 v[124:127], v179, s[6:7] offset:1664
	s_waitcnt lgkmcnt(4)
	v_mfma_f32_32x32x16_bf16 v[36:51], v[168:171], v[100:103], v[36:51]
	s_waitcnt vmcnt(16)
	ds_write_b128 v180, v[132:135] offset:46080
	global_load_dwordx4 v[128:131], v176, s[8:9] offset:1664
	global_load_dwordx4 v[132:135], v177, s[8:9] offset:1664
	s_waitcnt lgkmcnt(4)
	v_mfma_f32_32x32x16_bf16 v[20:35], v[96:99], v[172:175], v[20:35]
	v_mfma_f32_32x32x16_bf16 v[4:19], v[168:171], v[172:175], v[4:19]
	s_waitcnt lgkmcnt(0)
	s_barrier
	ds_read_b128 v[136:139], v183
	ds_read_b128 v[140:143], v182
	ds_read_b128 v[144:147], v183 offset:4608
	ds_read_b128 v[92:95], v182 offset:4608
	ds_read_b128 v[96:99], v183 offset:32
	ds_read_b128 v[100:103], v182 offset:32
	ds_read_b128 v[168:171], v183 offset:4640
	ds_read_b128 v[172:175], v182 offset:4640
	s_waitcnt lgkmcnt(6)
	v_mfma_f32_32x32x16_bf16 v[52:67], v[136:139], v[140:143], v[52:67]
	s_waitcnt lgkmcnt(5)
	v_mfma_f32_32x32x16_bf16 v[36:51], v[144:147], v[140:143], v[36:51]
	s_waitcnt lgkmcnt(4)
	v_mfma_f32_32x32x16_bf16 v[20:35], v[136:139], v[92:95], v[20:35]
	v_mfma_f32_32x32x16_bf16 v[4:19], v[144:147], v[92:95], v[4:19]
	ds_read_b128 v[136:139], v183 offset:64
	ds_read_b128 v[140:143], v182 offset:64
	ds_read_b128 v[144:147], v183 offset:4672
	ds_read_b128 v[92:95], v182 offset:4672
	s_waitcnt lgkmcnt(6)
	v_mfma_f32_32x32x16_bf16 v[52:67], v[96:99], v[100:103], v[52:67]
	s_waitcnt vmcnt(17)
	ds_write_b128 v181, v[208:211]
	s_waitcnt lgkmcnt(6)
	v_mfma_f32_32x32x16_bf16 v[36:51], v[168:171], v[100:103], v[36:51]
	s_waitcnt vmcnt(16)
	ds_write_b128 v181, v[212:215] offset:9216
	global_load_dwordx4 v[208:211], v176, s[6:7] offset:1792
	s_waitcnt lgkmcnt(6)
	v_mfma_f32_32x32x16_bf16 v[20:35], v[96:99], v[172:175], v[20:35]
	v_mfma_f32_32x32x16_bf16 v[4:19], v[168:171], v[172:175], v[4:19]
	ds_read_b128 v[96:99], v183 offset:96
	ds_read_b128 v[100:103], v182 offset:96
	ds_read_b128 v[168:171], v183 offset:4704
	ds_read_b128 v[172:175], v182 offset:4704
	s_waitcnt lgkmcnt(8)
	v_mfma_f32_32x32x16_bf16 v[52:67], v[136:139], v[140:143], v[52:67]
	s_waitcnt vmcnt(16)
	ds_write_b128 v181, v[216:219] offset:18432
	global_load_dwordx4 v[212:215], v177, s[6:7] offset:1792
	s_waitcnt lgkmcnt(8)
	v_mfma_f32_32x32x16_bf16 v[36:51], v[144:147], v[140:143], v[36:51]
	s_waitcnt vmcnt(16)
	ds_write_b128 v181, v[220:223] offset:27648
	global_load_dwordx4 v[216:219], v178, s[6:7] offset:1792
	s_waitcnt lgkmcnt(8)
	v_mfma_f32_32x32x16_bf16 v[20:35], v[136:139], v[92:95], v[20:35]
	v_mfma_f32_32x32x16_bf16 v[4:19], v[144:147], v[92:95], v[4:19]
	s_waitcnt lgkmcnt(4)
	v_mfma_f32_32x32x16_bf16 v[52:67], v[96:99], v[100:103], v[52:67]
	s_waitcnt vmcnt(16)
	ds_write_b128 v181, v[224:227] offset:36864
	global_load_dwordx4 v[220:223], v179, s[6:7] offset:1792
	s_waitcnt lgkmcnt(4)
	v_mfma_f32_32x32x16_bf16 v[36:51], v[168:171], v[100:103], v[36:51]
	s_waitcnt vmcnt(16)
	ds_write_b128 v181, v[228:231] offset:46080
	global_load_dwordx4 v[224:227], v176, s[8:9] offset:1792
	global_load_dwordx4 v[228:231], v177, s[8:9] offset:1792
	s_waitcnt lgkmcnt(4)
	v_mfma_f32_32x32x16_bf16 v[20:35], v[96:99], v[172:175], v[20:35]
	v_mfma_f32_32x32x16_bf16 v[4:19], v[168:171], v[172:175], v[4:19]
	s_waitcnt lgkmcnt(0)
	s_barrier
; #define MFMA32(a, b, c) __builtin_amdgcn_mfma_f32_32x32x16_bf16((a), (b), (c), 0, 0, 0)
; template <bool SWAP, class Epi>
; DI void gemm_tile(const u16* __restrict__ A, int lda, const u16* __restrict__ Bw, int ldb, int K, char* lds, Epi epi) {
;     ...
;   auto compute = [&](int st) {
;     const char* as = lds + st * GEMM_STAGE;
;     const char* bs = as + 36864;
; #pragma unroll
;     for (int ks = 0; ks < 4; ++ks) {
;       bf16x8 af[2], bfr[2];
; #pragma unroll
;       for (int mi = 0; mi < 2; ++mi) af[mi] = *(const bf16x8*)(as + ((wm * 64 + mi * 32 + r) * 72 + ks * 16 + 8 * h) * 2);
; #pragma unroll
;       for (int ni = 0; ni < 2; ++ni) bfr[ni] = *(const bf16x8*)(bs + ((wn * 64 + ni * 32 + r) * 72 + ks * 16 + 8 * h) * 2);
; #pragma unroll
;       for (int mi = 0; mi < 2; ++mi)
; #pragma unroll
;         for (int ni = 0; ni < 2; ++ni) {
;           if (SWAP) acc[mi][ni] = MFMA32(bfr[ni], af[mi], acc[mi][ni]);
;           else acc[mi][ni] = MFMA32(af[mi], bfr[ni], acc[mi][ni]);
;         }
;     }
;   };
;   gload(0, ra0, rb0);
;   lstore(0, ra0, rb0);
;   gload(1, ra1, rb1);
;   __syncthreads();
;   for (int kt = 0; kt < nk; kt += 2) {
;     if (kt + 2 < nk) gload(kt + 2, ra0, rb0);
;     compute(0);
;     lstore(1, ra1, rb1);
;     __syncthreads();
;     if (kt + 3 < nk) gload(kt + 3, ra1, rb1);
;     compute(1);
;     if (kt + 2 < nk) lstore(0, ra0, rb0);
;     __syncthreads();
	ds_read_b128 v[136:139], v184
	ds_read_b128 v[140:143], v182 offset:55296
	ds_read_b128 v[144:147], v184 offset:4608
	ds_read_b128 v[92:95], v182 offset:59904
	ds_read_b128 v[96:99], v184 offset:32
	ds_read_b128 v[100:103], v182 offset:55328
	ds_read_b128 v[168:171], v184 offset:4640
	ds_read_b128 v[172:175], v182 offset:59936
	s_waitcnt lgkmcnt(6)
	v_mfma_f32_32x32x16_bf16 v[52:67], v[136:139], v[140:143], v[52:67]
	s_waitcnt lgkmcnt(5)
	v_mfma_f32_32x32x16_bf16 v[36:51], v[144:147], v[140:143], v[36:51]
	s_waitcnt lgkmcnt(4)
	v_mfma_f32_32x32x16_bf16 v[20:35], v[136:139], v[92:95], v[20:35]
	v_mfma_f32_32x32x16_bf16 v[4:19], v[144:147], v[92:95], v[4:19]
	ds_read_b128 v[136:139], v184 offset:64
	ds_read_b128 v[140:143], v182 offset:55360
	ds_read_b128 v[144:147], v184 offset:4672
	ds_read_b128 v[92:95], v182 offset:59968
	s_waitcnt lgkmcnt(6)
	v_mfma_f32_32x32x16_bf16 v[52:67], v[96:99], v[100:103], v[52:67]
	s_waitcnt vmcnt(17)
	ds_write_b128 v180, v[68:71]
	s_waitcnt lgkmcnt(6)
	v_mfma_f32_32x32x16_bf16 v[36:51], v[168:171], v[100:103], v[36:51]
	s_waitcnt vmcnt(16)
	ds_write_b128 v180, v[72:75] offset:9216
	global_load_dwordx4 v[68:71], v176, s[6:7] offset:1920
	s_waitcnt lgkmcnt(6)
	v_mfma_f32_32x32x16_bf16 v[20:35], v[96:99], v[172:175], v[20:35]
	v_mfma_f32_32x32x16_bf16 v[4:19], v[168:171], v[172:175], v[4:19]
	ds_read_b128 v[96:99], v184 offset:96
	ds_read_b128 v[100:103], v182 offset:55392
	ds_read_b128 v[168:171], v184 offset:4704
	ds_read_b128 v[172:175], v182 offset:60000
	s_waitcnt lgkmcnt(8)
	v_mfma_f32_32x32x16_bf16 v[52:67], v[136:139], v[140:143], v[52:67]
	s_waitcnt vmcnt(16)
	ds_write_b128 v180, v[76:79] offset:18432
	global_load_dwordx4 v[72:75], v177, s[6:7] offset:1920
	s_waitcnt lgkmcnt(8)
	v_mfma_f32_32x32x16_bf16 v[36:51], v[144:147], v[140:143], v[36:51]
	s_waitcnt vmcnt(16)
	ds_write_b128 v180, v[80:83] offset:27648
	global_load_dwordx4 v[76:79], v178, s[6:7] offset:1920
	s_waitcnt lgkmcnt(8)
	v_mfma_f32_32x32x16_bf16 v[20:35], v[136:139], v[92:95], v[20:35]
	v_mfma_f32_32x32x16_bf16 v[4:19], v[144:147], v[92:95], v[4:19]
	s_waitcnt lgkmcnt(4)
	v_mfma_f32_32x32x16_bf16 v[52:67], v[96:99], v[100:103], v[52:67]
	s_waitcnt vmcnt(16)
	ds_write_b128 v180, v[84:87] offset:36864
	global_load_dwordx4 v[80:83], v179, s[6:7] offset:1920
	s_waitcnt lgkmcnt(4)
	v_mfma_f32_32x32x16_bf16 v[36:51], v[168:171], v[100:103], v[36:51]
	s_waitcnt vmcnt(16)
	ds_write_b128 v180, v[88:91] offset:46080
	global_load_dwordx4 v[84:87], v176, s[8:9] offset:1920
	global_load_dwordx4 v[88:91], v177, s[8:9] offset:1920
	s_waitcnt lgkmcnt(4)
	v_mfma_f32_32x32x16_bf16 v[20:35], v[96:99], v[172:175], v[20:35]
	v_mfma_f32_32x32x16_bf16 v[4:19], v[168:171], v[172:175], v[4:19]
	s_waitcnt lgkmcnt(0)
	s_barrier
	ds_read_b128 v[136:139], v183
	ds_read_b128 v[140:143], v182
	ds_read_b128 v[144:147], v183 offset:4608
	ds_read_b128 v[92:95], v182 offset:4608
	ds_read_b128 v[96:99], v183 offset:32
	ds_read_b128 v[100:103], v182 offset:32
	ds_read_b128 v[168:171], v183 offset:4640
	ds_read_b128 v[172:175], v182 offset:4640
	s_waitcnt lgkmcnt(6)
	v_mfma_f32_32x32x16_bf16 v[52:67], v[136:139], v[140:143], v[52:67]
	s_waitcnt lgkmcnt(5)
	v_mfma_f32_32x32x16_bf16 v[36:51], v[144:147], v[140:143], v[36:51]
	s_waitcnt lgkmcnt(4)
	v_mfma_f32_32x32x16_bf16 v[20:35], v[136:139], v[92:95], v[20:35]
	v_mfma_f32_32x32x16_bf16 v[4:19], v[144:147], v[92:95], v[4:19]
	ds_read_b128 v[136:139], v183 offset:64
	ds_read_b128 v[140:143], v182 offset:64
	ds_read_b128 v[144:147], v183 offset:4672
	ds_read_b128 v[92:95], v182 offset:4672
	s_waitcnt lgkmcnt(6)
	v_mfma_f32_32x32x16_bf16 v[52:67], v[96:99], v[100:103], v[52:67]
	s_waitcnt vmcnt(17)
	ds_write_b128 v181, v[112:115]
	s_waitcnt lgkmcnt(6)
	v_mfma_f32_32x32x16_bf16 v[36:51], v[168:171], v[100:103], v[36:51]
	s_waitcnt vmcnt(16)
	ds_write_b128 v181, v[116:119] offset:9216
	s_waitcnt lgkmcnt(6)
	v_mfma_f32_32x32x16_bf16 v[20:35], v[96:99], v[172:175], v[20:35]
	v_mfma_f32_32x32x16_bf16 v[4:19], v[168:171], v[172:175], v[4:19]
	ds_read_b128 v[96:99], v183 offset:96
	ds_read_b128 v[100:103], v182 offset:96
	ds_read_b128 v[168:171], v183 offset:4704
	ds_read_b128 v[172:175], v182 offset:4704
	s_waitcnt lgkmcnt(8)
	v_mfma_f32_32x32x16_bf16 v[52:67], v[136:139], v[140:143], v[52:67]
	s_waitcnt vmcnt(15)
	ds_write_b128 v181, v[120:123] offset:18432
	s_waitcnt lgkmcnt(8)
	v_mfma_f32_32x32x16_bf16 v[36:51], v[144:147], v[140:143], v[36:51]
	s_waitcnt vmcnt(14)
	ds_write_b128 v181, v[124:127] offset:27648
	s_waitcnt lgkmcnt(8)
	v_mfma_f32_32x32x16_bf16 v[20:35], v[136:139], v[92:95], v[20:35]
	v_mfma_f32_32x32x16_bf16 v[4:19], v[144:147], v[92:95], v[4:19]
	s_waitcnt lgkmcnt(4)
	v_mfma_f32_32x32x16_bf16 v[52:67], v[96:99], v[100:103], v[52:67]
	s_waitcnt vmcnt(13)
	ds_write_b128 v181, v[128:131] offset:36864
	s_waitcnt lgkmcnt(4)
	v_mfma_f32_32x32x16_bf16 v[36:51], v[168:171], v[100:103], v[36:51]
	s_waitcnt vmcnt(12)
	ds_write_b128 v181, v[132:135] offset:46080
	s_waitcnt lgkmcnt(4)
	v_mfma_f32_32x32x16_bf16 v[20:35], v[96:99], v[172:175], v[20:35]
	v_mfma_f32_32x32x16_bf16 v[4:19], v[168:171], v[172:175], v[4:19]
	s_waitcnt lgkmcnt(0)
	s_barrier
; #define MFMA32(a, b, c) __builtin_amdgcn_mfma_f32_32x32x16_bf16((a), (b), (c), 0, 0, 0)
; template <bool SWAP, class Epi>
; DI void gemm_tile(const u16* __restrict__ A, int lda, const u16* __restrict__ Bw, int ldb, int K, char* lds, Epi epi) {
;     ...
;   auto compute = [&](int st) {
;     const char* as = lds + st * GEMM_STAGE;
;     const char* bs = as + 36864;
; #pragma unroll
;     for (int ks = 0; ks < 4; ++ks) {
;       bf16x8 af[2], bfr[2];
; #pragma unroll
;       for (int mi = 0; mi < 2; ++mi) af[mi] = *(const bf16x8*)(as + ((wm * 64 + mi * 32 + r) * 72 + ks * 16 + 8 * h) * 2);
; #pragma unroll
;       for (int ni = 0; ni < 2; ++ni) bfr[ni] = *(const bf16x8*)(bs + ((wn * 64 + ni * 32 + r) * 72 + ks * 16 + 8 * h) * 2);
; #pragma unroll
;       for (int mi = 0; mi < 2; ++mi)
; #pragma unroll
;         for (int ni = 0; ni < 2; ++ni) {
;           if (SWAP) acc[mi][ni] = MFMA32(bfr[ni], af[mi], acc[mi][ni]);
;           else acc[mi][ni] = MFMA32(af[mi], bfr[ni], acc[mi][ni]);
;         }
;     }
;   };
;   gload(0, ra0, rb0);
;   lstore(0, ra0, rb0);
;   gload(1, ra1, rb1);
;   __syncthreads();
;   for (int kt = 0; kt < nk; kt += 2) {
;     if (kt + 2 < nk) gload(kt + 2, ra0, rb0);
;     compute(0);
;     lstore(1, ra1, rb1);
;     __syncthreads();
;     if (kt + 3 < nk) gload(kt + 3, ra1, rb1);
;     compute(1);
;     if (kt + 2 < nk) lstore(0, ra0, rb0);
;     __syncthreads();
	ds_read_b128 v[136:139], v184
	ds_read_b128 v[140:143], v182 offset:55296
	ds_read_b128 v[144:147], v184 offset:4608
	ds_read_b128 v[92:95], v182 offset:59904
	ds_read_b128 v[96:99], v184 offset:32
	ds_read_b128 v[100:103], v182 offset:55328
	ds_read_b128 v[168:171], v184 offset:4640
	ds_read_b128 v[172:175], v182 offset:59936
	s_waitcnt lgkmcnt(6)
	v_mfma_f32_32x32x16_bf16 v[52:67], v[136:139], v[140:143], v[52:67]
	s_waitcnt lgkmcnt(5)
	v_mfma_f32_32x32x16_bf16 v[36:51], v[144:147], v[140:143], v[36:51]
	s_waitcnt lgkmcnt(4)
	v_mfma_f32_32x32x16_bf16 v[20:35], v[136:139], v[92:95], v[20:35]
	v_mfma_f32_32x32x16_bf16 v[4:19], v[144:147], v[92:95], v[4:19]
	ds_read_b128 v[136:139], v184 offset:64
	ds_read_b128 v[140:143], v182 offset:55360
	ds_read_b128 v[144:147], v184 offset:4672
	ds_read_b128 v[92:95], v182 offset:59968
	s_waitcnt lgkmcnt(6)
	v_mfma_f32_32x32x16_bf16 v[52:67], v[96:99], v[100:103], v[52:67]
	s_waitcnt vmcnt(11)
	ds_write_b128 v180, v[208:211]
	s_waitcnt lgkmcnt(6)
	v_mfma_f32_32x32x16_bf16 v[36:51], v[168:171], v[100:103], v[36:51]
	s_waitcnt vmcnt(10)
	ds_write_b128 v180, v[212:215] offset:9216
	s_waitcnt lgkmcnt(6)
	v_mfma_f32_32x32x16_bf16 v[20:35], v[96:99], v[172:175], v[20:35]
	v_mfma_f32_32x32x16_bf16 v[4:19], v[168:171], v[172:175], v[4:19]
	ds_read_b128 v[96:99], v184 offset:96
	ds_read_b128 v[100:103], v182 offset:55392
	ds_read_b128 v[168:171], v184 offset:4704
	ds_read_b128 v[172:175], v182 offset:60000
	s_waitcnt lgkmcnt(8)
	v_mfma_f32_32x32x16_bf16 v[52:67], v[136:139], v[140:143], v[52:67]
	s_waitcnt vmcnt(9)
	ds_write_b128 v180, v[216:219] offset:18432
	s_waitcnt lgkmcnt(8)
	v_mfma_f32_32x32x16_bf16 v[36:51], v[144:147], v[140:143], v[36:51]
	s_waitcnt vmcnt(8)
	ds_write_b128 v180, v[220:223] offset:27648
	s_waitcnt lgkmcnt(8)
	v_mfma_f32_32x32x16_bf16 v[20:35], v[136:139], v[92:95], v[20:35]
	v_mfma_f32_32x32x16_bf16 v[4:19], v[144:147], v[92:95], v[4:19]
	s_waitcnt lgkmcnt(4)
	v_mfma_f32_32x32x16_bf16 v[52:67], v[96:99], v[100:103], v[52:67]
	s_waitcnt vmcnt(7)
	ds_write_b128 v180, v[224:227] offset:36864
	s_waitcnt lgkmcnt(4)
	v_mfma_f32_32x32x16_bf16 v[36:51], v[168:171], v[100:103], v[36:51]
	s_waitcnt vmcnt(6)
	ds_write_b128 v180, v[228:231] offset:46080
	s_waitcnt lgkmcnt(4)
	v_mfma_f32_32x32x16_bf16 v[20:35], v[96:99], v[172:175], v[20:35]
	v_mfma_f32_32x32x16_bf16 v[4:19], v[168:171], v[172:175], v[4:19]
	s_waitcnt lgkmcnt(0)
	s_barrier
	ds_read_b128 v[136:139], v183
	ds_read_b128 v[140:143], v182
	ds_read_b128 v[144:147], v183 offset:4608
	ds_read_b128 v[92:95], v182 offset:4608
	ds_read_b128 v[96:99], v183 offset:32
	ds_read_b128 v[100:103], v182 offset:32
	ds_read_b128 v[168:171], v183 offset:4640
	ds_read_b128 v[172:175], v182 offset:4640
	s_waitcnt lgkmcnt(6)
	v_mfma_f32_32x32x16_bf16 v[52:67], v[136:139], v[140:143], v[52:67]
	s_waitcnt lgkmcnt(5)
	v_mfma_f32_32x32x16_bf16 v[36:51], v[144:147], v[140:143], v[36:51]
	s_waitcnt lgkmcnt(4)
	v_mfma_f32_32x32x16_bf16 v[20:35], v[136:139], v[92:95], v[20:35]
	v_mfma_f32_32x32x16_bf16 v[4:19], v[144:147], v[92:95], v[4:19]
	ds_read_b128 v[136:139], v183 offset:64
	ds_read_b128 v[140:143], v182 offset:64
	ds_read_b128 v[144:147], v183 offset:4672
	ds_read_b128 v[92:95], v182 offset:4672
	s_waitcnt lgkmcnt(6)
	v_mfma_f32_32x32x16_bf16 v[52:67], v[96:99], v[100:103], v[52:67]
	s_waitcnt vmcnt(5)
	ds_write_b128 v181, v[68:71]
	s_waitcnt lgkmcnt(6)
	v_mfma_f32_32x32x16_bf16 v[36:51], v[168:171], v[100:103], v[36:51]
	s_waitcnt vmcnt(4)
	ds_write_b128 v181, v[72:75] offset:9216
	s_waitcnt lgkmcnt(6)
	v_mfma_f32_32x32x16_bf16 v[20:35], v[96:99], v[172:175], v[20:35]
	v_mfma_f32_32x32x16_bf16 v[4:19], v[168:171], v[172:175], v[4:19]
	ds_read_b128 v[96:99], v183 offset:96
	ds_read_b128 v[100:103], v182 offset:96
	ds_read_b128 v[168:171], v183 offset:4704
	ds_read_b128 v[172:175], v182 offset:4704
	s_waitcnt lgkmcnt(8)
	v_mfma_f32_32x32x16_bf16 v[52:67], v[136:139], v[140:143], v[52:67]
	s_waitcnt vmcnt(3)
	ds_write_b128 v181, v[76:79] offset:18432
	s_waitcnt lgkmcnt(8)
	v_mfma_f32_32x32x16_bf16 v[36:51], v[144:147], v[140:143], v[36:51]
	s_waitcnt vmcnt(2)
	ds_write_b128 v181, v[80:83] offset:27648
	s_waitcnt lgkmcnt(8)
	v_mfma_f32_32x32x16_bf16 v[20:35], v[136:139], v[92:95], v[20:35]
	v_mfma_f32_32x32x16_bf16 v[4:19], v[144:147], v[92:95], v[4:19]
	s_waitcnt lgkmcnt(4)
	v_mfma_f32_32x32x16_bf16 v[52:67], v[96:99], v[100:103], v[52:67]
	s_waitcnt vmcnt(1)
	ds_write_b128 v181, v[84:87] offset:36864
	s_waitcnt lgkmcnt(4)
	v_mfma_f32_32x32x16_bf16 v[36:51], v[168:171], v[100:103], v[36:51]
	s_waitcnt vmcnt(0)
	ds_write_b128 v181, v[88:91] offset:46080
	s_waitcnt lgkmcnt(4)
	v_mfma_f32_32x32x16_bf16 v[20:35], v[96:99], v[172:175], v[20:35]
	v_mfma_f32_32x32x16_bf16 v[4:19], v[168:171], v[172:175], v[4:19]
	s_waitcnt lgkmcnt(0)
	s_barrier
; #define MFMA32(a, b, c) __builtin_amdgcn_mfma_f32_32x32x16_bf16((a), (b), (c), 0, 0, 0)
; template <bool SWAP, class Epi>
; DI void gemm_tile(const u16* __restrict__ A, int lda, const u16* __restrict__ Bw, int ldb, int K, char* lds, Epi epi) {
;     ...
;   auto compute = [&](int st) {
;     const char* as = lds + st * GEMM_STAGE;
;     const char* bs = as + 36864;
; #pragma unroll
;     for (int ks = 0; ks < 4; ++ks) {
;       bf16x8 af[2], bfr[2];
; #pragma unroll
;       for (int mi = 0; mi < 2; ++mi) af[mi] = *(const bf16x8*)(as + ((wm * 64 + mi * 32 + r) * 72 + ks * 16 + 8 * h) * 2);
; #pragma unroll
;       for (int ni = 0; ni < 2; ++ni) bfr[ni] = *(const bf16x8*)(bs + ((wn * 64 + ni * 32 + r) * 72 + ks * 16 + 8 * h) * 2);
; #pragma unroll
;       for (int mi = 0; mi < 2; ++mi)
; #pragma unroll
;         for (int ni = 0; ni < 2; ++ni) {
;           if (SWAP) acc[mi][ni] = MFMA32(bfr[ni], af[mi], acc[mi][ni]);
;           else acc[mi][ni] = MFMA32(af[mi], bfr[ni], acc[mi][ni]);
;         }
;     }
;   };
;   gload(0, ra0, rb0);
;   lstore(0, ra0, rb0);
;   gload(1, ra1, rb1);
;   __syncthreads();
;   for (int kt = 0; kt < nk; kt += 2) {
;     if (kt + 2 < nk) gload(kt + 2, ra0, rb0);
;     compute(0);
;     lstore(1, ra1, rb1);
;     __syncthreads();
;     if (kt + 3 < nk) gload(kt + 3, ra1, rb1);
;     compute(1);
;     if (kt + 2 < nk) lstore(0, ra0, rb0);
;     __syncthreads();
;   }
; #pragma unroll
;   for (int mi = 0; mi < 2; ++mi)
; #pragma unroll
;     for (int ni = 0; ni < 2; ++ni) epi(mi, ni, acc[mi][ni]);
; DI void inproj_tile(const Params& p, int l, int mt, int nt, char* lds) {
;     ...
;     gemm_tile<true>(A, DM, Bw, DM, DM, lds, [&](int mi, int ni, const f32x16& a) {
;       const int tok = m0 + wm * 64 + mi * 32 + r;
;       store_rowmajor(p.H + (size_t)tok * LDH + nt * 128 + wn * 64 + ni * 32, a, h, 1.f);
;       if (nt >= 4 && nt < 8) {
;         if (ni == 0) ssq = 0.f;
; #pragma unroll
;         for (int i = 0; i < 16; ++i) ssq += a[i] * a[i];
;         if (ni == 1) {
	ds_read_b128 v[136:139], v184
	ds_read_b128 v[140:143], v182 offset:55296
	ds_read_b128 v[144:147], v184 offset:4608
	ds_read_b128 v[92:95], v182 offset:59904
	ds_read_b128 v[96:99], v184 offset:32
	ds_read_b128 v[100:103], v182 offset:55328
	ds_read_b128 v[168:171], v184 offset:4640
	ds_read_b128 v[172:175], v182 offset:59936
	s_waitcnt lgkmcnt(6)
	v_mfma_f32_32x32x16_bf16 v[52:67], v[136:139], v[140:143], v[52:67]
	s_waitcnt lgkmcnt(5)
	v_mfma_f32_32x32x16_bf16 v[36:51], v[144:147], v[140:143], v[36:51]
	s_waitcnt lgkmcnt(4)
	v_mfma_f32_32x32x16_bf16 v[20:35], v[136:139], v[92:95], v[20:35]
	v_mfma_f32_32x32x16_bf16 v[4:19], v[144:147], v[92:95], v[4:19]
	ds_read_b128 v[136:139], v184 offset:64
	ds_read_b128 v[140:143], v182 offset:55360
	ds_read_b128 v[144:147], v184 offset:4672
	ds_read_b128 v[92:95], v182 offset:59968
	s_waitcnt lgkmcnt(6)
	v_mfma_f32_32x32x16_bf16 v[52:67], v[96:99], v[100:103], v[52:67]
	s_waitcnt lgkmcnt(5)
	v_mfma_f32_32x32x16_bf16 v[36:51], v[168:171], v[100:103], v[36:51]
	s_waitcnt lgkmcnt(4)
	v_mfma_f32_32x32x16_bf16 v[20:35], v[96:99], v[172:175], v[20:35]
	v_mfma_f32_32x32x16_bf16 v[4:19], v[168:171], v[172:175], v[4:19]
	ds_read_b128 v[96:99], v184 offset:96
	ds_read_b128 v[100:103], v182 offset:55392
	ds_read_b128 v[168:171], v184 offset:4704
	ds_read_b128 v[172:175], v182 offset:60000
	s_waitcnt lgkmcnt(6)
	v_mfma_f32_32x32x16_bf16 v[52:67], v[136:139], v[140:143], v[52:67]
	s_waitcnt lgkmcnt(5)
	v_mfma_f32_32x32x16_bf16 v[36:51], v[144:147], v[140:143], v[36:51]
	s_waitcnt lgkmcnt(4)
	v_mfma_f32_32x32x16_bf16 v[20:35], v[136:139], v[92:95], v[20:35]
	v_mfma_f32_32x32x16_bf16 v[4:19], v[144:147], v[92:95], v[4:19]
	s_waitcnt lgkmcnt(0)
	s_barrier
	v_mfma_f32_32x32x16_bf16 v[52:67], v[96:99], v[100:103], v[52:67]
	v_mfma_f32_32x32x16_bf16 v[36:51], v[168:171], v[100:103], v[36:51]
	v_mfma_f32_32x32x16_bf16 v[20:35], v[96:99], v[172:175], v[20:35]
	v_mfma_f32_32x32x16_bf16 v[4:19], v[168:171], v[172:175], v[4:19]
	v_mov_b64_e32 v[68:69], s[76:77]
    	v_mov_b32_e32 v72, 0
    	v_lshlrev_b32_e32 v2, 6, v108
    	v_or3_b32 v73, v2, s4, v107
    	v_mad_i64_i32 v[68:69], s[0:1], v73, s53, v[68:69]
    	s_mul_i32 s0, s26, 0xffffe800
    	s_add_i32 s4, s23, s0
    	s_ashr_i32 s5, s4, 31
    	v_lshl_add_u64 v[70:71], s[4:5], 1, v[68:69]
    	v_lshlrev_b32_e32 v68, 6, v0
    	v_ashrrev_i32_e32 v69, 31, v68
    	v_lshl_add_u64 v[70:71], v[68:69], 1, v[70:71]
    	v_lshlrev_b32_e32 v2, 4, v106
    	v_lshl_add_u64 v[70:71], v[70:71], 0, v[2:3]
    	s_and_b32 s0, s2, -4
    	s_cmp_eq_u32 s0, 4
    	s_cselect_b64 s[2:3], -1, 0
    	s_cmp_lg_u32 s0, 4
	s_nop 7
	v_cvt_pk_bf16_f32 v74, v52, v53
	v_cvt_pk_bf16_f32 v75, v54, v55
	v_cvt_pk_bf16_f32 v76, v56, v57
	v_cvt_pk_bf16_f32 v77, v58, v59
	s_nop 0
	v_permlane32_swap_b32_e32 v74, v76
	v_permlane32_swap_b32_e32 v75, v77
	s_nop 0
	global_store_dwordx4 v[70:71], v[74:77], off
	s_nop 1
	v_cvt_pk_bf16_f32 v74, v60, v61
	v_cvt_pk_bf16_f32 v75, v62, v63
	v_cvt_pk_bf16_f32 v76, v64, v65
	v_cvt_pk_bf16_f32 v77, v66, v67
	s_nop 0
	v_permlane32_swap_b32_e32 v74, v76
	v_permlane32_swap_b32_e32 v75, v77
	global_store_dwordx4 v[70:71], v[74:77], off offset:32
	s_cbranch_scc1 .LBB0_361
	v_mul_f32_e32 v2, v52, v52
	v_fmac_f32_e32 v2, v53, v53
	v_fmac_f32_e32 v2, v54, v54
	v_fmac_f32_e32 v2, v55, v55
	v_pk_mul_f32 v[56:57], v[56:57], v[56:57]
	v_pk_mul_f32 v[58:59], v[58:59], v[58:59]
	v_add_f32_e32 v2, v56, v2
	v_add_f32_e32 v2, v57, v2
	v_add_f32_e32 v2, v58, v2
	v_pk_mul_f32 v[60:61], v[60:61], v[60:61]
	v_add_f32_e32 v2, v59, v2
	v_add_f32_e32 v2, v60, v2
	v_pk_mul_f32 v[62:63], v[62:63], v[62:63]
	v_add_f32_e32 v2, v61, v2
	v_add_f32_e32 v2, v62, v2
	v_pk_mul_f32 v[54:55], v[64:65], v[64:65]
	v_add_f32_e32 v2, v63, v2
	v_add_f32_e32 v2, v54, v2
	v_pk_mul_f32 v[52:53], v[66:67], v[66:67]
	v_add_f32_e32 v2, v55, v2
	v_add_f32_e32 v2, v52, v2
	v_add_f32_e32 v72, v53, v2

; DI int next_job(unsigned* ctr, char* lds, int& pending, int njobs, int& par) {
;   int* sj = (int*)(lds + LDS_JOB);
;   if (threadIdx.x == 0) sj[par] = pending;
;   __syncthreads();
;   const int j = sj[par];
;   par ^= 1;
;   if (threadIdx.x == 0 && j < njobs) pending = (int)atomicAdd(ctr, 1u);
;   return j;
; DI void topk_job(const Params& p, int b, int t0, char* lds) {
;     ...
;     __syncthreads();
;     bool small = false;
;     int nb[4] = {0, 0, 0, 0};
; #pragma unroll
;     for (int pass = 0; pass < 3; ++pass) {
;       if (pass == 2) {
;         small = true;
; #pragma unroll
;         for (int q = 0; q < 4; ++q) small = small && (few[q] || nb[q] <= 64);
;         if (small) break;
;       }
;       {
;         const u32x4 z = {0u, 0u, 0u, 0u};
; #pragma unroll
;         for (int j = 0; j < 8; ++j) ((u32x4*)hist)[tid + 512 * j] = z;
;       }
;       __syncthreads();
; #pragma unroll
;       for (int i = 0; i < 17; ++i) {
; #pragma unroll
;         for (int q = 0; q < 4; ++q) {
;           const unsigned u = sc[i][q];
;           bool part; unsigned bin;
;           if (pass == 0) { part = (u != 0u); bin = (u >> 22) + (lane & 3) * 1024; }
;           else if (pass == 1) { part = (u != 0u) && ((u >> 22) == pref[q]) && !few[q]; bin = ((u >> 12) & 1023u) + (lane & 3) * 1024; }
;           else { part = (u != 0u) && ((u >> 12) == pref[q]) && !few[q]; bin = u & 4095u; }
;           if (part) atomicAdd(hist + q * 4096 + bin, 1u);
.LBB0_756:
	v_writelane_b32 v237, s46, 9
	s_nop 1
	v_writelane_b32 v237, s47, 10
	v_writelane_b32 v237, s44, 11
	s_nop 1
	v_writelane_b32 v237, s45, 12
	v_writelane_b32 v237, s42, 13
	s_nop 1
	v_writelane_b32 v237, s43, 14
	v_writelane_b32 v237, s40, 15
	s_nop 1
	v_writelane_b32 v237, s41, 16
	v_writelane_b32 v237, s36, 17
	s_nop 1
	v_writelane_b32 v237, s37, 18
	v_writelane_b32 v237, s34, 19
	s_nop 1
	v_writelane_b32 v237, s35, 20
	v_writelane_b32 v237, s30, 21
	s_nop 1
	v_writelane_b32 v237, s31, 22
	v_writelane_b32 v237, s28, 23
	s_nop 1
	v_writelane_b32 v237, s29, 24
	s_or_b64 exec, exec, s[18:19]
	s_waitcnt vmcnt(0) lgkmcnt(0)
	v_lshrrev_b32_e32 v0, 6, v100
	s_mov_b32 s3, s90
	v_readfirstlane_b32 s2, v0
	s_lshl_b32 s4, s87, 1
	s_and_b32 s4, s4, 0x3ffc
	s_sub_i32 s4, 0x209c, s4
	s_bitcmp1_b32 s87, 0
	s_cselect_b32 s5, 0x2100, 0
	s_add_i32 s4, s4, s5
	v_readlane_b32 s6, v240, 13
	v_readlane_b32 s7, v240, 14
	s_lshl_b32 s5, s4, 9
	s_add_u32 s40, s6, s5
	s_addc_u32 s41, s7, 0
	s_add_u32 s42, s40, 0x200
	s_addc_u32 s43, s41, 0
	s_add_u32 s44, s42, 0x200
	s_addc_u32 s45, s43, 0
	s_add_u32 s46, s44, 0x200
	s_addc_u32 s47, s45, 0
	s_mov_b32 s16, 0x55555555
	s_mov_b32 s17, 0x55555555
	s_mov_b32 s18, 0x33333333
	s_mov_b32 s19, 0x33333333
	s_mov_b32 s20, 0xf0f0f0f
	s_mov_b32 s21, 0xf0f0f0f
	s_mov_b32 s22, 0xff00ff
	s_mov_b32 s23, 0xff00ff
	s_mov_b32 s24, 0xffff
	s_mov_b32 s25, 0xffff
	s_mov_b32 s26, 0xffffffff
	s_mov_b32 s27, 0
	v_mov_b32_e32 v20, 1
	v_and_b32_e32 v0, 3, v101
	v_lshlrev_b32_e32 v0, 12, v0
	v_add_u32_e32 v21, 0x4000, v0
	v_add_u32_e32 v25, 0x14000, v0
	v_mov_b32_e32 v29, 0x4000
	v_add_u32_e32 v22, 0x8000, v0
	v_add_u32_e32 v26, 0x18000, v0
	v_mov_b32_e32 v30, 0x8000
	v_add_u32_e32 v23, 0xc000, v0
	v_add_u32_e32 v27, 0x1c000, v0
	v_mov_b32_e32 v31, 0xc000
	v_add_u32_e32 v24, 0x10000, v0
	v_add_u32_e32 v28, 0x20000, v0
	v_mov_b32_e32 v32, 0x10000
	s_movk_i32 s85, 0x100
	s_mov_b32 s56, 0
	s_mov_b32 s58, 0
	v_cmp_eq_u32_e32 vcc, 0, v100
	s_and_saveexec_b64 s[30:31], vcc
	ds_write_b32 v3, v136 offset:768
	s_mov_b64 exec, s[30:31]
	s_waitcnt lgkmcnt(0)
	v_lshlrev_b32_e32 v75, 2, v100
	v_add_u32_e32 v75, 0x2800, v75
	v_lshlrev_b32_e32 v76, 1, v100
	v_add_u32_e32 v76, 0x800, v76
	s_barrier
	v_mov_b32_e32 v4, 0
	v_mov_b32_e32 v5, 0
	v_mov_b32_e32 v6, 0
	v_mov_b32_e32 v7, 0
	v_lshlrev_b32_e32 v0, 4, v100
	v_add_u32_e32 v0, 0x4000, v0
	v_add_u32_e32 v1, 0x10000, v0
	ds_write_b128 v0, v[4:7]
	ds_write_b128 v0, v[4:7] offset:8192
	ds_write_b128 v0, v[4:7] offset:16384
	ds_write_b128 v0, v[4:7] offset:24576
	ds_write_b128 v0, v[4:7] offset:32768
	ds_write_b128 v0, v[4:7] offset:40960
	ds_write_b128 v0, v[4:7] offset:49152
	ds_write_b128 v0, v[4:7] offset:57344
	v_mov_b32_e32 v2, -1
	v_lshlrev_b32_e32 v0, 2, v100
	ds_write_b32 v0, v2 offset:8192
	s_waitcnt lgkmcnt(0)
	s_barrier
	ds_read_b32 v0, v3 offset:768
	s_waitcnt lgkmcnt(0)
	v_readfirstlane_b32 s63, v0
	s_cmp_lt_u32 s63, 16
	s_cbranch_scc1 .Ltk_pf_end_1
	s_cmpk_gt_u32 s63, 0x1017
	s_cbranch_scc1 .Ltk_pf_end_1
	s_lshl_b32 s4, s63, 1
	s_and_b32 s4, s4, 0x3ffc
	s_sub_i32 s4, 0x209c, s4
	s_bitcmp1_b32 s63, 0
	s_cselect_b32 s5, 0x2100, 0
	s_add_i32 s60, s4, 3
	s_lshr_b32 s60, s60, 6
	s_add_i32 s62, s2, 1
	s_cmp_gt_u32 s62, s60
	s_cbranch_scc1 .Ltk_pf_w_2
	v_readlane_b32 s64, v240, 11
	v_readlane_b32 s65, v240, 12
	s_lshl_b32 s62, s62, 6
	s_add_i32 s62, s62, s5
	v_add_lshl_u32 v0, s62, v101, 7
	s_nop 1
	global_load_dword v242, v0, s[64:65]
.Ltk_pf_w_2:
	s_cmp_lg_u32 s2, 0
	s_cbranch_scc1 .Ltk_pf_end_1
	v_readlane_b32 s64, v241, 24
	v_readlane_b32 s65, v241, 25
	s_add_i32 s62, s4, s5
	v_lshrrev_b32_e32 v0, 3, v101
	v_add_u32_e32 v0, s62, v0
	s_movk_i32 s60, 0x2a00
	v_mul_lo_u32 v0, v0, s60
	v_and_b32_e32 v1, 7, v101
	v_lshlrev_b32_e32 v1, 7, v1
	v_add_u32_e32 v0, v0, v1
	v_add_u32_e32 v0, 0x1900, v0
	s_mov_b32 exec_lo, -1
	s_mov_b32 exec_hi, 0
	global_load_dword v242, v0, s[64:65]
	s_mov_b64 exec, -1
.Ltk_pf_end_1:
	s_add_i32 s28, s2, 1
	s_cmp_gt_u32 s28, s3
	s_cbranch_scc1 .Ltk_p0_done_3
	v_lshrrev_b32_e32 v0, 22, v208
	v_lshl_add_u32 v0, v0, 2, v21
	ds_add_u32 v0, v20
	v_lshrrev_b32_e32 v1, 22, v175
	v_lshl_add_u32 v1, v1, 2, v22
	ds_add_u32 v1, v20
	v_lshrrev_b32_e32 v4, 22, v161
	v_lshl_add_u32 v4, v4, 2, v23
	ds_add_u32 v4, v20
	v_lshrrev_b32_e32 v5, 22, v138
	v_lshl_add_u32 v5, v5, 2, v24
	ds_add_u32 v5, v20
	s_add_i32 s28, s28, 8
	s_cmp_gt_u32 s28, s3
	s_cbranch_scc1 .Ltk_p0_done_3
	v_lshrrev_b32_e32 v0, 22, v207
	v_lshl_add_u32 v0, v0, 2, v21
	ds_add_u32 v0, v20
	v_lshrrev_b32_e32 v1, 22, v173
	v_lshl_add_u32 v1, v1, 2, v22
	ds_add_u32 v1, v20
	v_lshrrev_b32_e32 v4, 22, v159
	v_lshl_add_u32 v4, v4, 2, v23
	ds_add_u32 v4, v20
	v_lshrrev_b32_e32 v5, 22, v135
	v_lshl_add_u32 v5, v5, 2, v24
	ds_add_u32 v5, v20
	s_add_i32 s28, s28, 8
	s_cmp_gt_u32 s28, s3
	s_cbranch_scc1 .Ltk_p0_done_3
	v_lshrrev_b32_e32 v0, 22, v187
	v_lshl_add_u32 v0, v0, 2, v21
	ds_add_u32 v0, v20
	v_lshrrev_b32_e32 v1, 22, v172
	v_lshl_add_u32 v1, v1, 2, v22
	ds_add_u32 v1, v20
	v_lshrrev_b32_e32 v4, 22, v158
	v_lshl_add_u32 v4, v4, 2, v23
	ds_add_u32 v4, v20
	v_lshrrev_b32_e32 v5, 22, v133
	v_lshl_add_u32 v5, v5, 2, v24
	ds_add_u32 v5, v20
	s_add_i32 s28, s28, 8
	s_cmp_gt_u32 s28, s3
	s_cbranch_scc1 .Ltk_p0_done_3
	v_lshrrev_b32_e32 v0, 22, v186
	v_lshl_add_u32 v0, v0, 2, v21
	ds_add_u32 v0, v20
	v_lshrrev_b32_e32 v1, 22, v171
	v_lshl_add_u32 v1, v1, 2, v22
	ds_add_u32 v1, v20
	v_lshrrev_b32_e32 v4, 22, v153
	v_lshl_add_u32 v4, v4, 2, v23
	ds_add_u32 v4, v20
	v_lshrrev_b32_e32 v5, 22, v129
	v_lshl_add_u32 v5, v5, 2, v24
	ds_add_u32 v5, v20
	s_add_i32 s28, s28, 8
	s_cmp_gt_u32 s28, s3
	s_cbranch_scc1 .Ltk_p0_done_3
; DI void topk_job(const Params& p, int b, int t0, char* lds) {
;     ...
; #pragma unroll
;       for (int i = 0; i < 17; ++i) {
; #pragma unroll
;         for (int q = 0; q < 4; ++q) {
;           const unsigned u = sc[i][q];
;           bool part; unsigned bin;
;           if (pass == 0) { part = (u != 0u); bin = (u >> 22) + (lane & 3) * 1024; }
;           else if (pass == 1) { part = (u != 0u) && ((u >> 22) == pref[q]) && !few[q]; bin = ((u >> 12) & 1023u) + (lane & 3) * 1024; }
;           else { part = (u != 0u) && ((u >> 12) == pref[q]) && !few[q]; bin = u & 4095u; }
;           if (part) atomicAdd(hist + q * 4096 + bin, 1u);
;         }
;       }
	v_lshrrev_b32_e32 v0, 22, v185
	v_lshl_add_u32 v0, v0, 2, v21
	ds_add_u32 v0, v20
	v_lshrrev_b32_e32 v1, 22, v170
	v_lshl_add_u32 v1, v1, 2, v22
	ds_add_u32 v1, v20
	v_lshrrev_b32_e32 v4, 22, v150
	v_lshl_add_u32 v4, v4, 2, v23
	ds_add_u32 v4, v20
	v_lshrrev_b32_e32 v5, 22, v127
	v_lshl_add_u32 v5, v5, 2, v24
	ds_add_u32 v5, v20
	s_add_i32 s28, s28, 8
	s_cmp_gt_u32 s28, s3
	s_cbranch_scc1 .Ltk_p0_done_3
	v_lshrrev_b32_e32 v0, 22, v184
	v_lshl_add_u32 v0, v0, 2, v21
	ds_add_u32 v0, v20
	v_lshrrev_b32_e32 v1, 22, v168
	v_lshl_add_u32 v1, v1, 2, v22
	ds_add_u32 v1, v20
	v_lshrrev_b32_e32 v4, 22, v149
	v_lshl_add_u32 v4, v4, 2, v23
	ds_add_u32 v4, v20
	v_lshrrev_b32_e32 v5, 22, v125
	v_lshl_add_u32 v5, v5, 2, v24
	ds_add_u32 v5, v20
	s_add_i32 s28, s28, 8
	s_cmp_gt_u32 s28, s3
	s_cbranch_scc1 .Ltk_p0_done_3
	v_lshrrev_b32_e32 v0, 22, v183
	v_lshl_add_u32 v0, v0, 2, v21
	ds_add_u32 v0, v20
	v_lshrrev_b32_e32 v1, 22, v167
	v_lshl_add_u32 v1, v1, 2, v22
	ds_add_u32 v1, v20
	v_lshrrev_b32_e32 v4, 22, v147
	v_lshl_add_u32 v4, v4, 2, v23
	ds_add_u32 v4, v20
	v_lshrrev_b32_e32 v5, 22, v123
	v_lshl_add_u32 v5, v5, 2, v24
	ds_add_u32 v5, v20
	s_add_i32 s28, s28, 8
	s_cmp_gt_u32 s28, s3
	s_cbranch_scc1 .Ltk_p0_done_3
	v_lshrrev_b32_e32 v0, 22, v182
	v_lshl_add_u32 v0, v0, 2, v21
	ds_add_u32 v0, v20
	v_lshrrev_b32_e32 v1, 22, v166
	v_lshl_add_u32 v1, v1, 2, v22
	ds_add_u32 v1, v20
	v_lshrrev_b32_e32 v4, 22, v146
	v_lshl_add_u32 v4, v4, 2, v23
	ds_add_u32 v4, v20
	v_lshrrev_b32_e32 v5, 22, v121
	v_lshl_add_u32 v5, v5, 2, v24
	ds_add_u32 v5, v20
	s_add_i32 s28, s28, 8
	s_cmp_gt_u32 s28, s3
	s_cbranch_scc1 .Ltk_p0_done_3
	v_lshrrev_b32_e32 v0, 22, v181
	v_lshl_add_u32 v0, v0, 2, v21
	ds_add_u32 v0, v20
	v_lshrrev_b32_e32 v1, 22, v165
	v_lshl_add_u32 v1, v1, 2, v22
	ds_add_u32 v1, v20
	v_lshrrev_b32_e32 v4, 22, v145
	v_lshl_add_u32 v4, v4, 2, v23
	ds_add_u32 v4, v20
	v_lshrrev_b32_e32 v5, 22, v119
	v_lshl_add_u32 v5, v5, 2, v24
	ds_add_u32 v5, v20
	s_add_i32 s28, s28, 8
	s_cmp_gt_u32 s28, s3
	s_cbranch_scc1 .Ltk_p0_done_3
	v_lshrrev_b32_e32 v0, 22, v180
	v_lshl_add_u32 v0, v0, 2, v21
	ds_add_u32 v0, v20
	v_lshrrev_b32_e32 v1, 22, v164
	v_lshl_add_u32 v1, v1, 2, v22
	ds_add_u32 v1, v20
	v_lshrrev_b32_e32 v4, 22, v143
	v_lshl_add_u32 v4, v4, 2, v23
	ds_add_u32 v4, v20
	v_lshrrev_b32_e32 v5, 22, v115
	v_lshl_add_u32 v5, v5, 2, v24
	ds_add_u32 v5, v20
	s_add_i32 s28, s28, 8
	s_cmp_gt_u32 s28, s3
	s_cbranch_scc1 .Ltk_p0_done_3
	v_lshrrev_b32_e32 v0, 22, v179
	v_lshl_add_u32 v0, v0, 2, v21
	ds_add_u32 v0, v20
	v_lshrrev_b32_e32 v1, 22, v163
	v_lshl_add_u32 v1, v1, 2, v22
	ds_add_u32 v1, v20
	v_lshrrev_b32_e32 v4, 22, v142
	v_lshl_add_u32 v4, v4, 2, v23
	ds_add_u32 v4, v20
	v_lshrrev_b32_e32 v5, 22, v113
	v_lshl_add_u32 v5, v5, 2, v24
	ds_add_u32 v5, v20
	s_add_i32 s28, s28, 8
	s_cmp_gt_u32 s28, s3
	s_cbranch_scc1 .Ltk_p0_done_3
	v_lshrrev_b32_e32 v0, 22, v178
	v_lshl_add_u32 v0, v0, 2, v21
	ds_add_u32 v0, v20
	v_lshrrev_b32_e32 v1, 22, v162
	v_lshl_add_u32 v1, v1, 2, v22
	ds_add_u32 v1, v20
	v_lshrrev_b32_e32 v4, 22, v141
	v_lshl_add_u32 v4, v4, 2, v23
	ds_add_u32 v4, v20
	v_lshrrev_b32_e32 v5, 22, v111
	v_lshl_add_u32 v5, v5, 2, v24
	ds_add_u32 v5, v20
	s_add_i32 s28, s28, 8
	s_cmp_gt_u32 s28, s3
	s_cbranch_scc1 .Ltk_p0_done_3
	v_lshrrev_b32_e32 v0, 22, v177
	v_lshl_add_u32 v0, v0, 2, v21
	ds_add_u32 v0, v20
	v_lshrrev_b32_e32 v1, 22, v160
	v_lshl_add_u32 v1, v1, 2, v22
	ds_add_u32 v1, v20
	v_lshrrev_b32_e32 v4, 22, v140
	v_lshl_add_u32 v4, v4, 2, v23
	ds_add_u32 v4, v20
	v_lshrrev_b32_e32 v5, 22, v109
	v_lshl_add_u32 v5, v5, 2, v24
	ds_add_u32 v5, v20
	s_add_i32 s28, s28, 8
	s_cmp_gt_u32 s28, s3
	s_cbranch_scc1 .Ltk_p0_done_3
	v_lshrrev_b32_e32 v0, 22, v176
	v_lshl_add_u32 v0, v0, 2, v21
	ds_add_u32 v0, v20
	v_lshrrev_b32_e32 v1, 22, v151
	v_lshl_add_u32 v1, v1, 2, v22
	ds_add_u32 v1, v20
	v_lshrrev_b32_e32 v4, 22, v139
	v_lshl_add_u32 v4, v4, 2, v23
	ds_add_u32 v4, v20
	v_lshrrev_b32_e32 v5, 22, v107
	v_lshl_add_u32 v5, v5, 2, v24
	ds_add_u32 v5, v20
	s_add_i32 s28, s28, 8
	s_cmp_gt_u32 s28, s3
	s_cbranch_scc1 .Ltk_p0_done_3
	v_lshrrev_b32_e32 v0, 22, v174
	v_lshl_add_u32 v0, v0, 2, v21
	ds_add_u32 v0, v20
	v_lshrrev_b32_e32 v1, 22, v148
	v_lshl_add_u32 v1, v1, 2, v22
	ds_add_u32 v1, v20
	v_lshrrev_b32_e32 v4, 22, v131
	v_lshl_add_u32 v4, v4, 2, v23
	ds_add_u32 v4, v20
	v_lshrrev_b32_e32 v5, 22, v105
	v_lshl_add_u32 v5, v5, 2, v24
	ds_add_u32 v5, v20
	s_add_i32 s28, s28, 8
	s_cmp_gt_u32 s28, s3
	s_cbranch_scc1 .Ltk_p0_done_3
	v_lshrrev_b32_e32 v0, 22, v169
	v_lshl_add_u32 v0, v0, 2, v21
	ds_add_u32 v0, v20
	v_lshrrev_b32_e32 v1, 22, v144
	v_lshl_add_u32 v1, v1, 2, v22
	ds_add_u32 v1, v20
	v_lshrrev_b32_e32 v4, 22, v117
	v_lshl_add_u32 v4, v4, 2, v23
	ds_add_u32 v4, v20
	v_lshrrev_b32_e32 v5, 22, v103
	v_lshl_add_u32 v5, v5, 2, v24
	ds_add_u32 v5, v20
	s_add_i32 s28, s28, 8
	s_cmp_gt_u32 s28, s3
	s_cbranch_scc1 .Ltk_p0_done_3
	v_lshrrev_b32_e32 v0, 22, v19
	v_lshl_add_u32 v0, v0, 2, v21
	ds_add_u32 v0, v20
	v_lshrrev_b32_e32 v1, 22, v18
	v_lshl_add_u32 v1, v1, 2, v22
	ds_add_u32 v1, v20
	v_lshrrev_b32_e32 v4, 22, v17
	v_lshl_add_u32 v4, v4, 2, v23
	ds_add_u32 v4, v20
	v_lshrrev_b32_e32 v5, 22, v16
	v_lshl_add_u32 v5, v5, 2, v24
	ds_add_u32 v5, v20
; DI void topk_job(const Params& p, int b, int t0, char* lds) {
;     ...
;       __syncthreads();
;       if (w < 4) {
;         const int q = w;
;         const unsigned* hq = hist + q * 4096;
;         const int need = 256 - chi[q];
;         int G = 0;
;         if (pass < 2) {
; #pragma unroll
;           for (int rep = 0; rep < 4; ++rep)
; #pragma unroll
;             for (int j = 0; j < 16; ++j) G += (int)hq[rep * 1024 + 16 * lane + ((j + lane) & 15)];
;         } else {
; #pragma unroll 8
;           for (int j = 0; j < 64; ++j) G += (int)hq[64 * lane + ((j + lane) & 63)];
;         }
;         int S = G;
;         { int tt; S = wscan<false>(S, lane, tt); }
;         const unsigned long long mk = __ballot(S >= need);
.Ltk_p0_done_3:
	s_waitcnt lgkmcnt(0)
	s_barrier
	s_cmp_gt_u32 s2, 3
	s_cbranch_scc1 .Ltk_scan_idle_7
	s_lshl_b32 s84, s2, 14
	s_add_i32 s84, s84, 0x4000
	s_cmp_eq_u32 s56, 1
	s_cbranch_scc1 .Ltk_scan_few_5
	v_lshlrev_b32_e32 v0, 12, v101
	v_add_u32_e32 v0, s84, v0
	s_mov_b64 exec, 15
	ds_write_b32 v0, v3
	s_mov_b64 exec, -1
	v_lshlrev_b32_e32 v33, 6, v101
	v_add_u32_e32 v33, s84, v33
	v_mov_b32_e32 v66, 0
	v_lshrrev_b32_e32 v1, 2, v101
	v_add_u32_e32 v0, 0, v1
	v_and_b32_e32 v0, 3, v0
	v_lshl_add_u32 v34, v0, 4, v33
	v_add_u32_e32 v0, 1, v1
	v_and_b32_e32 v0, 3, v0
	v_lshl_add_u32 v35, v0, 4, v33
	v_add_u32_e32 v0, 2, v1
	v_and_b32_e32 v0, 3, v0
	v_lshl_add_u32 v36, v0, 4, v33
	v_add_u32_e32 v0, 3, v1
	v_and_b32_e32 v0, 3, v0
	v_lshl_add_u32 v37, v0, 4, v33
	ds_read_b128 v[50:53], v34
	ds_read_b128 v[54:57], v35
	ds_read_b128 v[58:61], v36
	ds_read_b128 v[62:65], v37
	s_waitcnt lgkmcnt(0)
	v_add3_u32 v66, v66, v50, v51
	v_add3_u32 v66, v66, v52, v53
	v_add3_u32 v66, v66, v54, v55
	v_add3_u32 v66, v66, v56, v57
	v_add3_u32 v66, v66, v58, v59
	v_add3_u32 v66, v66, v60, v61
	v_add3_u32 v66, v66, v62, v63
	v_add3_u32 v66, v66, v64, v65
	ds_read_b128 v[50:53], v34 offset:4096
	ds_read_b128 v[54:57], v35 offset:4096
	ds_read_b128 v[58:61], v36 offset:4096
	ds_read_b128 v[62:65], v37 offset:4096
	s_waitcnt lgkmcnt(0)
	v_add3_u32 v66, v66, v50, v51
	v_add3_u32 v66, v66, v52, v53
	v_add3_u32 v66, v66, v54, v55
	v_add3_u32 v66, v66, v56, v57
	v_add3_u32 v66, v66, v58, v59
	v_add3_u32 v66, v66, v60, v61
	v_add3_u32 v66, v66, v62, v63
	v_add3_u32 v66, v66, v64, v65
	ds_read_b128 v[50:53], v34 offset:8192
	ds_read_b128 v[54:57], v35 offset:8192
	ds_read_b128 v[58:61], v36 offset:8192
	ds_read_b128 v[62:65], v37 offset:8192
	s_waitcnt lgkmcnt(0)
	v_add3_u32 v66, v66, v50, v51
	v_add3_u32 v66, v66, v52, v53
	v_add3_u32 v66, v66, v54, v55
	v_add3_u32 v66, v66, v56, v57
	v_add3_u32 v66, v66, v58, v59
	v_add3_u32 v66, v66, v60, v61
	v_add3_u32 v66, v66, v62, v63
	v_add3_u32 v66, v66, v64, v65
	ds_read_b128 v[50:53], v34 offset:12288
	ds_read_b128 v[54:57], v35 offset:12288
	ds_read_b128 v[58:61], v36 offset:12288
	ds_read_b128 v[62:65], v37 offset:12288
	s_waitcnt lgkmcnt(0)
	v_add3_u32 v66, v66, v50, v51
	v_add3_u32 v66, v66, v52, v53
	v_add3_u32 v66, v66, v54, v55
	v_add3_u32 v66, v66, v56, v57
	v_add3_u32 v66, v66, v58, v59
	v_add3_u32 v66, v66, v60, v61
	v_add3_u32 v66, v66, v62, v63
	v_add3_u32 v66, v66, v64, v65
	s_nop 1
	v_add_u32_dpp v68, v66, v66 quad_perm:[1,0,3,2] row_mask:0xf bank_mask:0xf bound_ctrl:1
	v_cndmask_b32_e64 v67, v66, v68, s[16:17]
	s_nop 1
	v_mov_b32_dpp v69, v68 quad_perm:[2,3,0,1] row_mask:0xf bank_mask:0xf bound_ctrl:1
	v_add_u32_e32 v68, v68, v69
	v_cndmask_b32_e64 v70, 0, v69, s[18:19]
	v_add_u32_e32 v67, v67, v70
	s_nop 0
	v_mov_b32_dpp v69, v68 row_half_mirror row_mask:0xf bank_mask:0xf bound_ctrl:1
	v_add_u32_e32 v68, v68, v69
	v_cndmask_b32_e64 v70, 0, v69, s[20:21]
	v_add_u32_e32 v67, v67, v70
	s_nop 0
	v_mov_b32_dpp v69, v68 row_mirror row_mask:0xf bank_mask:0xf bound_ctrl:1
	v_add_u32_e32 v68, v68, v69
	v_cndmask_b32_e64 v70, 0, v69, s[22:23]
	v_add_u32_e32 v67, v67, v70
	v_mov_b32_e32 v71, v68
	v_mov_b32_e32 v72, v68
	s_nop 1
	v_permlane16_swap_b32_e32 v71, v72
	v_cndmask_b32_e64 v69, v71, v72, s[24:25]
	v_add_u32_e32 v68, v68, v69
	v_cndmask_b32_e64 v70, 0, v69, s[24:25]
	v_add_u32_e32 v67, v67, v70
	v_mov_b32_e32 v71, v68
	v_mov_b32_e32 v72, v68
	s_nop 1
	v_permlane32_swap_b32_e32 v71, v72
	v_cndmask_b32_e64 v69, v71, v72, s[26:27]
	v_cndmask_b32_e64 v70, 0, v69, s[26:27]
	v_add_u32_e32 v67, v67, v70
	v_cmp_le_u32_e64 s[30:31], s85, v67
	s_cmp_eq_u64 s[30:31], 0
	s_cbranch_scc1 .Ltk_scan_few_5
	s_flbit_i32_b64 s88, s[30:31]
	s_sub_i32 s88, 63, s88
	s_mov_b32 s90, 0
	s_cmp_eq_u32 s88, 63
	s_cbranch_scc1 .Ltk_noabove_8
	s_add_i32 s4, s88, 1
	s_nop 0
	v_readlane_b32 s90, v67, s4

; DI void topk_job(const Params& p, int b, int t0, char* lds) {
;     ...
;       {
;         const u32x4 z = {0u, 0u, 0u, 0u};
; #pragma unroll
;         for (int j = 0; j < 8; ++j) ((u32x4*)hist)[tid + 512 * j] = z;
;       }
;       __syncthreads();
; #pragma unroll
;       for (int i = 0; i < 17; ++i) {
; #pragma unroll
;         for (int q = 0; q < 4; ++q) {
;           const unsigned u = sc[i][q];
;           bool part; unsigned bin;
;           if (pass == 0) { part = (u != 0u); bin = (u >> 22) + (lane & 3) * 1024; }
;           else if (pass == 1) { part = (u != 0u) && ((u >> 22) == pref[q]) && !few[q]; bin = ((u >> 12) & 1023u) + (lane & 3) * 1024; }
;           else { part = (u != 0u) && ((u >> 12) == pref[q]) && !few[q]; bin = u & 4095u; }
;           if (part) atomicAdd(hist + q * 4096 + bin, 1u);
;         }
;       }
;     ...
;         if (lane == 0) { sel[q * 4 + 0] = B; sel[q * 4 + 1] = chi[q] + cg2; sel[q * 4 + 2] = fw; sel[q * 4 + 3] = nbin; }
;       }
;       __syncthreads();
; #pragma unroll
;       for (int q = 0; q < 4; ++q) {
;         if (!few[q]) {
;           pref[q] = (pref[q] << (pass < 2 ? 10 : 12)) | (unsigned)sel[q * 4 + 0];
;           chi[q] = sel[q * 4 + 1];
;           nb[q] = sel[q * 4 + 3];
;           if (pass == 0) few[q] = sel[q * 4 + 2] != 0;
;         }
;       }
.Ltk_scan_wr_6:
	v_mov_b32_e32 v4, s62
	v_mov_b32_e32 v5, s56
	v_mov_b32_e32 v0, 0x200
	v_lshl_add_u32 v0, s2, 3, v0
	s_mov_b64 exec, 1
	ds_write_b64 v0, v[4:5]
	s_mov_b64 exec, -1
	s_branch .Ltk_scan_end_4
.Ltk_scan_idle_7:
	v_mov_b32_e32 v4, 0
	v_mov_b32_e32 v5, 0
	v_mov_b32_e32 v6, 0
	v_mov_b32_e32 v7, 0
	v_lshlrev_b32_e32 v0, 4, v100
	v_add_u32_e32 v0, 0x13000, v0
	ds_write_b128 v0, v[4:7]
	ds_write_b128 v0, v[4:7] offset:4096
	ds_write_b128 v0, v[4:7] offset:8192
	ds_write_b128 v0, v[4:7] offset:12288
	ds_write_b128 v0, v[4:7] offset:16384
	ds_write_b128 v0, v[4:7] offset:20480
	ds_write_b128 v0, v[4:7] offset:24576
	ds_write_b128 v0, v[4:7] offset:28672
	ds_write_b128 v0, v[4:7] offset:32768
	ds_write_b128 v0, v[4:7] offset:36864
	ds_write_b128 v0, v[4:7] offset:40960
	ds_write_b128 v0, v[4:7] offset:45056
	ds_write_b128 v0, v[4:7] offset:49152
	ds_write_b128 v0, v[4:7] offset:53248
	ds_write_b128 v0, v[4:7] offset:57344
	ds_write_b128 v0, v[4:7] offset:61440
.Ltk_scan_end_4:
	s_waitcnt lgkmcnt(0)
	s_barrier
	ds_read_b128 v[4:7], v3 offset:512
	ds_read_b128 v[8:11], v3 offset:528
	s_waitcnt lgkmcnt(0)
	v_readfirstlane_b32 s8, v4
	v_readfirstlane_b32 s9, v6
	v_readfirstlane_b32 s10, v8
	v_readfirstlane_b32 s11, v10
	s_add_i32 s28, s2, 1
	s_cmp_gt_u32 s28, s3
	s_cbranch_scc1 .Ltk_p1_done_9
	v_lshrrev_b32_e32 v0, 22, v208
	v_cmp_eq_u32_e32 vcc, s8, v0
	v_bfe_u32 v8, v208, 12, 10
	v_lshl_add_u32 v8, v8, 2, v25
	v_cndmask_b32_e32 v8, v75, v8, vcc
	ds_add_u32 v8, v20
	v_lshrrev_b32_e32 v1, 22, v175
	v_cmp_eq_u32_e32 vcc, s9, v1
	v_bfe_u32 v9, v175, 12, 10
	v_lshl_add_u32 v9, v9, 2, v26
	v_cndmask_b32_e32 v9, v75, v9, vcc
	ds_add_u32 v9, v20
	v_lshrrev_b32_e32 v4, 22, v161
	v_cmp_eq_u32_e32 vcc, s10, v4
	v_bfe_u32 v10, v161, 12, 10
	v_lshl_add_u32 v10, v10, 2, v27
	v_cndmask_b32_e32 v10, v75, v10, vcc
	ds_add_u32 v10, v20
	v_lshrrev_b32_e32 v5, 22, v138
	v_cmp_eq_u32_e32 vcc, s11, v5
	v_bfe_u32 v11, v138, 12, 10
	v_lshl_add_u32 v11, v11, 2, v28
	v_cndmask_b32_e32 v11, v75, v11, vcc
	ds_add_u32 v11, v20
	s_add_i32 s28, s28, 8
	s_cmp_gt_u32 s28, s3
	s_cbranch_scc1 .Ltk_p1_done_9
	v_lshrrev_b32_e32 v0, 22, v207
	v_cmp_eq_u32_e32 vcc, s8, v0
	v_bfe_u32 v8, v207, 12, 10
	v_lshl_add_u32 v8, v8, 2, v25
	v_cndmask_b32_e32 v8, v75, v8, vcc
	ds_add_u32 v8, v20
	v_lshrrev_b32_e32 v1, 22, v173
	v_cmp_eq_u32_e32 vcc, s9, v1
	v_bfe_u32 v9, v173, 12, 10
	v_lshl_add_u32 v9, v9, 2, v26
	v_cndmask_b32_e32 v9, v75, v9, vcc
	ds_add_u32 v9, v20
	v_lshrrev_b32_e32 v4, 22, v159
	v_cmp_eq_u32_e32 vcc, s10, v4
	v_bfe_u32 v10, v159, 12, 10
	v_lshl_add_u32 v10, v10, 2, v27
	v_cndmask_b32_e32 v10, v75, v10, vcc
	ds_add_u32 v10, v20
	v_lshrrev_b32_e32 v5, 22, v135
	v_cmp_eq_u32_e32 vcc, s11, v5
	v_bfe_u32 v11, v135, 12, 10
	v_lshl_add_u32 v11, v11, 2, v28
	v_cndmask_b32_e32 v11, v75, v11, vcc
	ds_add_u32 v11, v20
	s_add_i32 s28, s28, 8
	s_cmp_gt_u32 s28, s3
	s_cbranch_scc1 .Ltk_p1_done_9
	v_lshrrev_b32_e32 v0, 22, v187
	v_cmp_eq_u32_e32 vcc, s8, v0
	v_bfe_u32 v8, v187, 12, 10
	v_lshl_add_u32 v8, v8, 2, v25
	v_cndmask_b32_e32 v8, v75, v8, vcc
	ds_add_u32 v8, v20
	v_lshrrev_b32_e32 v1, 22, v172
	v_cmp_eq_u32_e32 vcc, s9, v1
	v_bfe_u32 v9, v172, 12, 10
	v_lshl_add_u32 v9, v9, 2, v26
	v_cndmask_b32_e32 v9, v75, v9, vcc
	ds_add_u32 v9, v20
	v_lshrrev_b32_e32 v4, 22, v158
	v_cmp_eq_u32_e32 vcc, s10, v4
	v_bfe_u32 v10, v158, 12, 10
	v_lshl_add_u32 v10, v10, 2, v27
	v_cndmask_b32_e32 v10, v75, v10, vcc
	ds_add_u32 v10, v20
	v_lshrrev_b32_e32 v5, 22, v133
	v_cmp_eq_u32_e32 vcc, s11, v5
	v_bfe_u32 v11, v133, 12, 10
	v_lshl_add_u32 v11, v11, 2, v28
	v_cndmask_b32_e32 v11, v75, v11, vcc
	ds_add_u32 v11, v20
	s_add_i32 s28, s28, 8
	s_cmp_gt_u32 s28, s3
	s_cbranch_scc1 .Ltk_p1_done_9
	v_lshrrev_b32_e32 v0, 22, v186
	v_cmp_eq_u32_e32 vcc, s8, v0
	v_bfe_u32 v8, v186, 12, 10
	v_lshl_add_u32 v8, v8, 2, v25
	v_cndmask_b32_e32 v8, v75, v8, vcc
	ds_add_u32 v8, v20
	v_lshrrev_b32_e32 v1, 22, v171
	v_cmp_eq_u32_e32 vcc, s9, v1
	v_bfe_u32 v9, v171, 12, 10
	v_lshl_add_u32 v9, v9, 2, v26
	v_cndmask_b32_e32 v9, v75, v9, vcc
	ds_add_u32 v9, v20
	v_lshrrev_b32_e32 v4, 22, v153
	v_cmp_eq_u32_e32 vcc, s10, v4
	v_bfe_u32 v10, v153, 12, 10
	v_lshl_add_u32 v10, v10, 2, v27
	v_cndmask_b32_e32 v10, v75, v10, vcc
	ds_add_u32 v10, v20
	v_lshrrev_b32_e32 v5, 22, v129
	v_cmp_eq_u32_e32 vcc, s11, v5
	v_bfe_u32 v11, v129, 12, 10
	v_lshl_add_u32 v11, v11, 2, v28
	v_cndmask_b32_e32 v11, v75, v11, vcc
	ds_add_u32 v11, v20
	s_add_i32 s28, s28, 8
	s_cmp_gt_u32 s28, s3
	s_cbranch_scc1 .Ltk_p1_done_9
	v_lshrrev_b32_e32 v0, 22, v185
	v_cmp_eq_u32_e32 vcc, s8, v0
	v_bfe_u32 v8, v185, 12, 10
	v_lshl_add_u32 v8, v8, 2, v25
	v_cndmask_b32_e32 v8, v75, v8, vcc
	ds_add_u32 v8, v20
	v_lshrrev_b32_e32 v1, 22, v170
	v_cmp_eq_u32_e32 vcc, s9, v1
	v_bfe_u32 v9, v170, 12, 10
	v_lshl_add_u32 v9, v9, 2, v26
	v_cndmask_b32_e32 v9, v75, v9, vcc
	ds_add_u32 v9, v20
	v_lshrrev_b32_e32 v4, 22, v150
	v_cmp_eq_u32_e32 vcc, s10, v4
	v_bfe_u32 v10, v150, 12, 10
	v_lshl_add_u32 v10, v10, 2, v27
	v_cndmask_b32_e32 v10, v75, v10, vcc
	ds_add_u32 v10, v20
	v_lshrrev_b32_e32 v5, 22, v127
	v_cmp_eq_u32_e32 vcc, s11, v5
	v_bfe_u32 v11, v127, 12, 10
	v_lshl_add_u32 v11, v11, 2, v28
	v_cndmask_b32_e32 v11, v75, v11, vcc
	ds_add_u32 v11, v20
	s_add_i32 s28, s28, 8
	s_cmp_gt_u32 s28, s3
	s_cbranch_scc1 .Ltk_p1_done_9
; DI void topk_job(const Params& p, int b, int t0, char* lds) {
;     ...
; #pragma unroll
;       for (int i = 0; i < 17; ++i) {
; #pragma unroll
;         for (int q = 0; q < 4; ++q) {
;           const unsigned u = sc[i][q];
;           bool part; unsigned bin;
;           if (pass == 0) { part = (u != 0u); bin = (u >> 22) + (lane & 3) * 1024; }
;           else if (pass == 1) { part = (u != 0u) && ((u >> 22) == pref[q]) && !few[q]; bin = ((u >> 12) & 1023u) + (lane & 3) * 1024; }
;           else { part = (u != 0u) && ((u >> 12) == pref[q]) && !few[q]; bin = u & 4095u; }
;           if (part) atomicAdd(hist + q * 4096 + bin, 1u);
;         }
;       }
	v_lshrrev_b32_e32 v0, 22, v184
	v_cmp_eq_u32_e32 vcc, s8, v0
	v_bfe_u32 v8, v184, 12, 10
	v_lshl_add_u32 v8, v8, 2, v25
	v_cndmask_b32_e32 v8, v75, v8, vcc
	ds_add_u32 v8, v20
	v_lshrrev_b32_e32 v1, 22, v168
	v_cmp_eq_u32_e32 vcc, s9, v1
	v_bfe_u32 v9, v168, 12, 10
	v_lshl_add_u32 v9, v9, 2, v26
	v_cndmask_b32_e32 v9, v75, v9, vcc
	ds_add_u32 v9, v20
	v_lshrrev_b32_e32 v4, 22, v149
	v_cmp_eq_u32_e32 vcc, s10, v4
	v_bfe_u32 v10, v149, 12, 10
	v_lshl_add_u32 v10, v10, 2, v27
	v_cndmask_b32_e32 v10, v75, v10, vcc
	ds_add_u32 v10, v20
	v_lshrrev_b32_e32 v5, 22, v125
	v_cmp_eq_u32_e32 vcc, s11, v5
	v_bfe_u32 v11, v125, 12, 10
	v_lshl_add_u32 v11, v11, 2, v28
	v_cndmask_b32_e32 v11, v75, v11, vcc
	ds_add_u32 v11, v20
	s_add_i32 s28, s28, 8
	s_cmp_gt_u32 s28, s3
	s_cbranch_scc1 .Ltk_p1_done_9
	v_lshrrev_b32_e32 v0, 22, v183
	v_cmp_eq_u32_e32 vcc, s8, v0
	v_bfe_u32 v8, v183, 12, 10
	v_lshl_add_u32 v8, v8, 2, v25
	v_cndmask_b32_e32 v8, v75, v8, vcc
	ds_add_u32 v8, v20
	v_lshrrev_b32_e32 v1, 22, v167
	v_cmp_eq_u32_e32 vcc, s9, v1
	v_bfe_u32 v9, v167, 12, 10
	v_lshl_add_u32 v9, v9, 2, v26
	v_cndmask_b32_e32 v9, v75, v9, vcc
	ds_add_u32 v9, v20
	v_lshrrev_b32_e32 v4, 22, v147
	v_cmp_eq_u32_e32 vcc, s10, v4
	v_bfe_u32 v10, v147, 12, 10
	v_lshl_add_u32 v10, v10, 2, v27
	v_cndmask_b32_e32 v10, v75, v10, vcc
	ds_add_u32 v10, v20
	v_lshrrev_b32_e32 v5, 22, v123
	v_cmp_eq_u32_e32 vcc, s11, v5
	v_bfe_u32 v11, v123, 12, 10
	v_lshl_add_u32 v11, v11, 2, v28
	v_cndmask_b32_e32 v11, v75, v11, vcc
	ds_add_u32 v11, v20
	s_add_i32 s28, s28, 8
	s_cmp_gt_u32 s28, s3
	s_cbranch_scc1 .Ltk_p1_done_9
	v_lshrrev_b32_e32 v0, 22, v182
	v_cmp_eq_u32_e32 vcc, s8, v0
	v_bfe_u32 v8, v182, 12, 10
	v_lshl_add_u32 v8, v8, 2, v25
	v_cndmask_b32_e32 v8, v75, v8, vcc
	ds_add_u32 v8, v20
	v_lshrrev_b32_e32 v1, 22, v166
	v_cmp_eq_u32_e32 vcc, s9, v1
	v_bfe_u32 v9, v166, 12, 10
	v_lshl_add_u32 v9, v9, 2, v26
	v_cndmask_b32_e32 v9, v75, v9, vcc
	ds_add_u32 v9, v20
	v_lshrrev_b32_e32 v4, 22, v146
	v_cmp_eq_u32_e32 vcc, s10, v4
	v_bfe_u32 v10, v146, 12, 10
	v_lshl_add_u32 v10, v10, 2, v27
	v_cndmask_b32_e32 v10, v75, v10, vcc
	ds_add_u32 v10, v20
	v_lshrrev_b32_e32 v5, 22, v121
	v_cmp_eq_u32_e32 vcc, s11, v5
	v_bfe_u32 v11, v121, 12, 10
	v_lshl_add_u32 v11, v11, 2, v28
	v_cndmask_b32_e32 v11, v75, v11, vcc
	ds_add_u32 v11, v20
	s_add_i32 s28, s28, 8
	s_cmp_gt_u32 s28, s3
	s_cbranch_scc1 .Ltk_p1_done_9
	v_lshrrev_b32_e32 v0, 22, v181
	v_cmp_eq_u32_e32 vcc, s8, v0
	v_bfe_u32 v8, v181, 12, 10
	v_lshl_add_u32 v8, v8, 2, v25
	v_cndmask_b32_e32 v8, v75, v8, vcc
	ds_add_u32 v8, v20
	v_lshrrev_b32_e32 v1, 22, v165
	v_cmp_eq_u32_e32 vcc, s9, v1
	v_bfe_u32 v9, v165, 12, 10
	v_lshl_add_u32 v9, v9, 2, v26
	v_cndmask_b32_e32 v9, v75, v9, vcc
	ds_add_u32 v9, v20
	v_lshrrev_b32_e32 v4, 22, v145
	v_cmp_eq_u32_e32 vcc, s10, v4
	v_bfe_u32 v10, v145, 12, 10
	v_lshl_add_u32 v10, v10, 2, v27
	v_cndmask_b32_e32 v10, v75, v10, vcc
	ds_add_u32 v10, v20
	v_lshrrev_b32_e32 v5, 22, v119
	v_cmp_eq_u32_e32 vcc, s11, v5
	v_bfe_u32 v11, v119, 12, 10
	v_lshl_add_u32 v11, v11, 2, v28
	v_cndmask_b32_e32 v11, v75, v11, vcc
	ds_add_u32 v11, v20
	s_add_i32 s28, s28, 8
	s_cmp_gt_u32 s28, s3
	s_cbranch_scc1 .Ltk_p1_done_9
	v_lshrrev_b32_e32 v0, 22, v180
	v_cmp_eq_u32_e32 vcc, s8, v0
	v_bfe_u32 v8, v180, 12, 10
	v_lshl_add_u32 v8, v8, 2, v25
	v_cndmask_b32_e32 v8, v75, v8, vcc
	ds_add_u32 v8, v20
	v_lshrrev_b32_e32 v1, 22, v164
	v_cmp_eq_u32_e32 vcc, s9, v1
	v_bfe_u32 v9, v164, 12, 10
	v_lshl_add_u32 v9, v9, 2, v26
	v_cndmask_b32_e32 v9, v75, v9, vcc
	ds_add_u32 v9, v20
	v_lshrrev_b32_e32 v4, 22, v143
	v_cmp_eq_u32_e32 vcc, s10, v4
	v_bfe_u32 v10, v143, 12, 10
	v_lshl_add_u32 v10, v10, 2, v27
	v_cndmask_b32_e32 v10, v75, v10, vcc
	ds_add_u32 v10, v20
	v_lshrrev_b32_e32 v5, 22, v115
	v_cmp_eq_u32_e32 vcc, s11, v5
	v_bfe_u32 v11, v115, 12, 10
	v_lshl_add_u32 v11, v11, 2, v28
	v_cndmask_b32_e32 v11, v75, v11, vcc
	ds_add_u32 v11, v20
	s_add_i32 s28, s28, 8
	s_cmp_gt_u32 s28, s3
	s_cbranch_scc1 .Ltk_p1_done_9
	v_lshrrev_b32_e32 v0, 22, v179
	v_cmp_eq_u32_e32 vcc, s8, v0
	v_bfe_u32 v8, v179, 12, 10
	v_lshl_add_u32 v8, v8, 2, v25
	v_cndmask_b32_e32 v8, v75, v8, vcc
	ds_add_u32 v8, v20
	v_lshrrev_b32_e32 v1, 22, v163
	v_cmp_eq_u32_e32 vcc, s9, v1
	v_bfe_u32 v9, v163, 12, 10
	v_lshl_add_u32 v9, v9, 2, v26
	v_cndmask_b32_e32 v9, v75, v9, vcc
	ds_add_u32 v9, v20
	v_lshrrev_b32_e32 v4, 22, v142
	v_cmp_eq_u32_e32 vcc, s10, v4
	v_bfe_u32 v10, v142, 12, 10
	v_lshl_add_u32 v10, v10, 2, v27
	v_cndmask_b32_e32 v10, v75, v10, vcc
	ds_add_u32 v10, v20
	v_lshrrev_b32_e32 v5, 22, v113
	v_cmp_eq_u32_e32 vcc, s11, v5
	v_bfe_u32 v11, v113, 12, 10
	v_lshl_add_u32 v11, v11, 2, v28
	v_cndmask_b32_e32 v11, v75, v11, vcc
	ds_add_u32 v11, v20
	s_add_i32 s28, s28, 8
	s_cmp_gt_u32 s28, s3
	s_cbranch_scc1 .Ltk_p1_done_9
	v_lshrrev_b32_e32 v0, 22, v178
	v_cmp_eq_u32_e32 vcc, s8, v0
	v_bfe_u32 v8, v178, 12, 10
	v_lshl_add_u32 v8, v8, 2, v25
	v_cndmask_b32_e32 v8, v75, v8, vcc
	ds_add_u32 v8, v20
	v_lshrrev_b32_e32 v1, 22, v162
	v_cmp_eq_u32_e32 vcc, s9, v1
	v_bfe_u32 v9, v162, 12, 10
	v_lshl_add_u32 v9, v9, 2, v26
	v_cndmask_b32_e32 v9, v75, v9, vcc
	ds_add_u32 v9, v20
	v_lshrrev_b32_e32 v4, 22, v141
	v_cmp_eq_u32_e32 vcc, s10, v4
	v_bfe_u32 v10, v141, 12, 10
	v_lshl_add_u32 v10, v10, 2, v27
	v_cndmask_b32_e32 v10, v75, v10, vcc
	ds_add_u32 v10, v20
	v_lshrrev_b32_e32 v5, 22, v111
	v_cmp_eq_u32_e32 vcc, s11, v5
	v_bfe_u32 v11, v111, 12, 10
	v_lshl_add_u32 v11, v11, 2, v28
	v_cndmask_b32_e32 v11, v75, v11, vcc
	ds_add_u32 v11, v20
	s_add_i32 s28, s28, 8
	s_cmp_gt_u32 s28, s3
	s_cbranch_scc1 .Ltk_p1_done_9
; DI void topk_job(const Params& p, int b, int t0, char* lds) {
;     ...
; #pragma unroll
;       for (int i = 0; i < 17; ++i) {
; #pragma unroll
;         for (int q = 0; q < 4; ++q) {
;           const unsigned u = sc[i][q];
;           bool part; unsigned bin;
;           if (pass == 0) { part = (u != 0u); bin = (u >> 22) + (lane & 3) * 1024; }
;           else if (pass == 1) { part = (u != 0u) && ((u >> 22) == pref[q]) && !few[q]; bin = ((u >> 12) & 1023u) + (lane & 3) * 1024; }
;           else { part = (u != 0u) && ((u >> 12) == pref[q]) && !few[q]; bin = u & 4095u; }
;           if (part) atomicAdd(hist + q * 4096 + bin, 1u);
;         }
;       }
	v_lshrrev_b32_e32 v0, 22, v177
	v_cmp_eq_u32_e32 vcc, s8, v0
	v_bfe_u32 v8, v177, 12, 10
	v_lshl_add_u32 v8, v8, 2, v25
	v_cndmask_b32_e32 v8, v75, v8, vcc
	ds_add_u32 v8, v20
	v_lshrrev_b32_e32 v1, 22, v160
	v_cmp_eq_u32_e32 vcc, s9, v1
	v_bfe_u32 v9, v160, 12, 10
	v_lshl_add_u32 v9, v9, 2, v26
	v_cndmask_b32_e32 v9, v75, v9, vcc
	ds_add_u32 v9, v20
	v_lshrrev_b32_e32 v4, 22, v140
	v_cmp_eq_u32_e32 vcc, s10, v4
	v_bfe_u32 v10, v140, 12, 10
	v_lshl_add_u32 v10, v10, 2, v27
	v_cndmask_b32_e32 v10, v75, v10, vcc
	ds_add_u32 v10, v20
	v_lshrrev_b32_e32 v5, 22, v109
	v_cmp_eq_u32_e32 vcc, s11, v5
	v_bfe_u32 v11, v109, 12, 10
	v_lshl_add_u32 v11, v11, 2, v28
	v_cndmask_b32_e32 v11, v75, v11, vcc
	ds_add_u32 v11, v20
	s_add_i32 s28, s28, 8
	s_cmp_gt_u32 s28, s3
	s_cbranch_scc1 .Ltk_p1_done_9
	v_lshrrev_b32_e32 v0, 22, v176
	v_cmp_eq_u32_e32 vcc, s8, v0
	v_bfe_u32 v8, v176, 12, 10
	v_lshl_add_u32 v8, v8, 2, v25
	v_cndmask_b32_e32 v8, v75, v8, vcc
	ds_add_u32 v8, v20
	v_lshrrev_b32_e32 v1, 22, v151
	v_cmp_eq_u32_e32 vcc, s9, v1
	v_bfe_u32 v9, v151, 12, 10
	v_lshl_add_u32 v9, v9, 2, v26
	v_cndmask_b32_e32 v9, v75, v9, vcc
	ds_add_u32 v9, v20
	v_lshrrev_b32_e32 v4, 22, v139
	v_cmp_eq_u32_e32 vcc, s10, v4
	v_bfe_u32 v10, v139, 12, 10
	v_lshl_add_u32 v10, v10, 2, v27
	v_cndmask_b32_e32 v10, v75, v10, vcc
	ds_add_u32 v10, v20
	v_lshrrev_b32_e32 v5, 22, v107
	v_cmp_eq_u32_e32 vcc, s11, v5
	v_bfe_u32 v11, v107, 12, 10
	v_lshl_add_u32 v11, v11, 2, v28
	v_cndmask_b32_e32 v11, v75, v11, vcc
	ds_add_u32 v11, v20
	s_add_i32 s28, s28, 8
	s_cmp_gt_u32 s28, s3
	s_cbranch_scc1 .Ltk_p1_done_9
	v_lshrrev_b32_e32 v0, 22, v174
	v_cmp_eq_u32_e32 vcc, s8, v0
	v_bfe_u32 v8, v174, 12, 10
	v_lshl_add_u32 v8, v8, 2, v25
	v_cndmask_b32_e32 v8, v75, v8, vcc
	ds_add_u32 v8, v20
	v_lshrrev_b32_e32 v1, 22, v148
	v_cmp_eq_u32_e32 vcc, s9, v1
	v_bfe_u32 v9, v148, 12, 10
	v_lshl_add_u32 v9, v9, 2, v26
	v_cndmask_b32_e32 v9, v75, v9, vcc
	ds_add_u32 v9, v20
	v_lshrrev_b32_e32 v4, 22, v131
	v_cmp_eq_u32_e32 vcc, s10, v4
	v_bfe_u32 v10, v131, 12, 10
	v_lshl_add_u32 v10, v10, 2, v27
	v_cndmask_b32_e32 v10, v75, v10, vcc
	ds_add_u32 v10, v20
	v_lshrrev_b32_e32 v5, 22, v105
	v_cmp_eq_u32_e32 vcc, s11, v5
	v_bfe_u32 v11, v105, 12, 10
	v_lshl_add_u32 v11, v11, 2, v28
	v_cndmask_b32_e32 v11, v75, v11, vcc
	ds_add_u32 v11, v20
	s_add_i32 s28, s28, 8
	s_cmp_gt_u32 s28, s3
	s_cbranch_scc1 .Ltk_p1_done_9
	v_lshrrev_b32_e32 v0, 22, v169
	v_cmp_eq_u32_e32 vcc, s8, v0
	v_bfe_u32 v8, v169, 12, 10
	v_lshl_add_u32 v8, v8, 2, v25
	v_cndmask_b32_e32 v8, v75, v8, vcc
	ds_add_u32 v8, v20
	v_lshrrev_b32_e32 v1, 22, v144
	v_cmp_eq_u32_e32 vcc, s9, v1
	v_bfe_u32 v9, v144, 12, 10
	v_lshl_add_u32 v9, v9, 2, v26
	v_cndmask_b32_e32 v9, v75, v9, vcc
	ds_add_u32 v9, v20
	v_lshrrev_b32_e32 v4, 22, v117
	v_cmp_eq_u32_e32 vcc, s10, v4
	v_bfe_u32 v10, v117, 12, 10
	v_lshl_add_u32 v10, v10, 2, v27
	v_cndmask_b32_e32 v10, v75, v10, vcc
	ds_add_u32 v10, v20
	v_lshrrev_b32_e32 v5, 22, v103
	v_cmp_eq_u32_e32 vcc, s11, v5
	v_bfe_u32 v11, v103, 12, 10
	v_lshl_add_u32 v11, v11, 2, v28
	v_cndmask_b32_e32 v11, v75, v11, vcc
	ds_add_u32 v11, v20
	s_add_i32 s28, s28, 8
	s_cmp_gt_u32 s28, s3
	s_cbranch_scc1 .Ltk_p1_done_9
	v_lshrrev_b32_e32 v0, 22, v19
	v_cmp_eq_u32_e32 vcc, s8, v0
	v_bfe_u32 v8, v19, 12, 10
	v_lshl_add_u32 v8, v8, 2, v25
	v_cndmask_b32_e32 v8, v75, v8, vcc
	ds_add_u32 v8, v20
	v_lshrrev_b32_e32 v1, 22, v18
	v_cmp_eq_u32_e32 vcc, s9, v1
	v_bfe_u32 v9, v18, 12, 10
	v_lshl_add_u32 v9, v9, 2, v26
	v_cndmask_b32_e32 v9, v75, v9, vcc
	ds_add_u32 v9, v20
	v_lshrrev_b32_e32 v4, 22, v17
	v_cmp_eq_u32_e32 vcc, s10, v4
	v_bfe_u32 v10, v17, 12, 10
	v_lshl_add_u32 v10, v10, 2, v27
	v_cndmask_b32_e32 v10, v75, v10, vcc
	ds_add_u32 v10, v20
	v_lshrrev_b32_e32 v5, 22, v16
	v_cmp_eq_u32_e32 vcc, s11, v5
	v_bfe_u32 v11, v16, 12, 10
	v_lshl_add_u32 v11, v11, 2, v28
	v_cndmask_b32_e32 v11, v75, v11, vcc
	ds_add_u32 v11, v20
; DI void topk_job(const Params& p, int b, int t0, char* lds) {
;     ...
;       __syncthreads();
;       if (w < 4) {
;         const int q = w;
;         const unsigned* hq = hist + q * 4096;
;         const int need = 256 - chi[q];
;         int G = 0;
;         if (pass < 2) {
; #pragma unroll
;           for (int rep = 0; rep < 4; ++rep)
; #pragma unroll
;             for (int j = 0; j < 16; ++j) G += (int)hq[rep * 1024 + 16 * lane + ((j + lane) & 15)];
;         } else {
; #pragma unroll 8
;           for (int j = 0; j < 64; ++j) G += (int)hq[64 * lane + ((j + lane) & 63)];
;         }
;         int S = G;
;         { int tt; S = wscan<false>(S, lane, tt); }
;         const unsigned long long mk = __ballot(S >= need);
.Ltk_p1_done_9:
	s_waitcnt lgkmcnt(0)
	s_barrier
	s_cmp_gt_u32 s2, 3
	s_cbranch_scc1 .Ltk_scan_idle_13
	s_lshl_b32 s84, s2, 14
	s_add_i32 s84, s84, 0x14000
	s_cmp_eq_u32 s56, 1
	s_cbranch_scc1 .Ltk_scan_few_11
	v_lshlrev_b32_e32 v33, 6, v101
	v_add_u32_e32 v33, s84, v33
	v_mov_b32_e32 v66, 0
	v_lshrrev_b32_e32 v1, 2, v101
	v_add_u32_e32 v0, 0, v1
	v_and_b32_e32 v0, 3, v0
	v_lshl_add_u32 v34, v0, 4, v33
	v_add_u32_e32 v0, 1, v1
	v_and_b32_e32 v0, 3, v0
	v_lshl_add_u32 v35, v0, 4, v33
	v_add_u32_e32 v0, 2, v1
	v_and_b32_e32 v0, 3, v0
	v_lshl_add_u32 v36, v0, 4, v33
	v_add_u32_e32 v0, 3, v1
	v_and_b32_e32 v0, 3, v0
	v_lshl_add_u32 v37, v0, 4, v33
	ds_read_b128 v[50:53], v34
	ds_read_b128 v[54:57], v35
	ds_read_b128 v[58:61], v36
	ds_read_b128 v[62:65], v37
	s_waitcnt lgkmcnt(0)
	v_add3_u32 v66, v66, v50, v51
	v_add3_u32 v66, v66, v52, v53
	v_add3_u32 v66, v66, v54, v55
	v_add3_u32 v66, v66, v56, v57
	v_add3_u32 v66, v66, v58, v59
	v_add3_u32 v66, v66, v60, v61
	v_add3_u32 v66, v66, v62, v63
	v_add3_u32 v66, v66, v64, v65
	ds_read_b128 v[50:53], v34 offset:4096
	ds_read_b128 v[54:57], v35 offset:4096
	ds_read_b128 v[58:61], v36 offset:4096
	ds_read_b128 v[62:65], v37 offset:4096
	s_waitcnt lgkmcnt(0)
	v_add3_u32 v66, v66, v50, v51
	v_add3_u32 v66, v66, v52, v53
	v_add3_u32 v66, v66, v54, v55
	v_add3_u32 v66, v66, v56, v57
	v_add3_u32 v66, v66, v58, v59
	v_add3_u32 v66, v66, v60, v61
	v_add3_u32 v66, v66, v62, v63
	v_add3_u32 v66, v66, v64, v65
	ds_read_b128 v[50:53], v34 offset:8192
	ds_read_b128 v[54:57], v35 offset:8192
	ds_read_b128 v[58:61], v36 offset:8192
	ds_read_b128 v[62:65], v37 offset:8192
	s_waitcnt lgkmcnt(0)
	v_add3_u32 v66, v66, v50, v51
	v_add3_u32 v66, v66, v52, v53
	v_add3_u32 v66, v66, v54, v55
	v_add3_u32 v66, v66, v56, v57
	v_add3_u32 v66, v66, v58, v59
	v_add3_u32 v66, v66, v60, v61
	v_add3_u32 v66, v66, v62, v63
	v_add3_u32 v66, v66, v64, v65
	ds_read_b128 v[50:53], v34 offset:12288
	ds_read_b128 v[54:57], v35 offset:12288
	ds_read_b128 v[58:61], v36 offset:12288
	ds_read_b128 v[62:65], v37 offset:12288
	s_waitcnt lgkmcnt(0)
	v_add3_u32 v66, v66, v50, v51
	v_add3_u32 v66, v66, v52, v53
	v_add3_u32 v66, v66, v54, v55
	v_add3_u32 v66, v66, v56, v57
	v_add3_u32 v66, v66, v58, v59
	v_add3_u32 v66, v66, v60, v61
	v_add3_u32 v66, v66, v62, v63
	v_add3_u32 v66, v66, v64, v65
	s_nop 1
	v_add_u32_dpp v68, v66, v66 quad_perm:[1,0,3,2] row_mask:0xf bank_mask:0xf bound_ctrl:1
	v_cndmask_b32_e64 v67, v66, v68, s[16:17]
	s_nop 1
	v_mov_b32_dpp v69, v68 quad_perm:[2,3,0,1] row_mask:0xf bank_mask:0xf bound_ctrl:1
	v_add_u32_e32 v68, v68, v69
	v_cndmask_b32_e64 v70, 0, v69, s[18:19]
	v_add_u32_e32 v67, v67, v70
	s_nop 0
	v_mov_b32_dpp v69, v68 row_half_mirror row_mask:0xf bank_mask:0xf bound_ctrl:1
	v_add_u32_e32 v68, v68, v69
	v_cndmask_b32_e64 v70, 0, v69, s[20:21]
	v_add_u32_e32 v67, v67, v70
	s_nop 0
	v_mov_b32_dpp v69, v68 row_mirror row_mask:0xf bank_mask:0xf bound_ctrl:1
	v_add_u32_e32 v68, v68, v69
	v_cndmask_b32_e64 v70, 0, v69, s[22:23]
	v_add_u32_e32 v67, v67, v70
	v_mov_b32_e32 v71, v68
	v_mov_b32_e32 v72, v68
	s_nop 1
	v_permlane16_swap_b32_e32 v71, v72
	v_cndmask_b32_e64 v69, v71, v72, s[24:25]
	v_add_u32_e32 v68, v68, v69
	v_cndmask_b32_e64 v70, 0, v69, s[24:25]
	v_add_u32_e32 v67, v67, v70
	v_mov_b32_e32 v71, v68
	v_mov_b32_e32 v72, v68
	s_nop 1
	v_permlane32_swap_b32_e32 v71, v72
	v_cndmask_b32_e64 v69, v71, v72, s[26:27]
	v_cndmask_b32_e64 v70, 0, v69, s[26:27]
	v_add_u32_e32 v67, v67, v70
	v_cmp_le_u32_e64 s[30:31], s85, v67
	s_cmp_eq_u64 s[30:31], 0
	s_cbranch_scc1 .Ltk_scan_few_11
	s_flbit_i32_b64 s88, s[30:31]
	s_sub_i32 s88, 63, s88
	s_mov_b32 s90, 0
	s_cmp_eq_u32 s88, 63
	s_cbranch_scc1 .Ltk_noabove_14
	s_add_i32 s4, s88, 1
	s_nop 0
	v_readlane_b32 s90, v67, s4

; DI void topk_job(const Params& p, int b, int t0, char* lds) {
;     ...
;       {
;         const u32x4 z = {0u, 0u, 0u, 0u};
; #pragma unroll
;         for (int j = 0; j < 8; ++j) ((u32x4*)hist)[tid + 512 * j] = z;
;       }
;       __syncthreads();
.Ltk_scan_idle_13:
	v_mov_b32_e32 v4, 0
	v_mov_b32_e32 v5, 0
	v_mov_b32_e32 v6, 0
	v_mov_b32_e32 v7, 0
	v_lshlrev_b32_e32 v0, 4, v100
	v_add_u32_e32 v0, 0x3000, v0
	ds_write_b128 v0, v[4:7]
	ds_write_b128 v0, v[4:7] offset:4096
	ds_write_b128 v0, v[4:7] offset:8192
	ds_write_b128 v0, v[4:7] offset:12288
	ds_write_b128 v0, v[4:7] offset:16384
	ds_write_b128 v0, v[4:7] offset:20480
	ds_write_b128 v0, v[4:7] offset:24576
	ds_write_b128 v0, v[4:7] offset:28672
	ds_write_b128 v0, v[4:7] offset:32768
	ds_write_b128 v0, v[4:7] offset:36864
	ds_write_b128 v0, v[4:7] offset:40960
	ds_write_b128 v0, v[4:7] offset:45056
	ds_write_b128 v0, v[4:7] offset:49152
	ds_write_b128 v0, v[4:7] offset:53248
	ds_write_b128 v0, v[4:7] offset:57344
	ds_write_b128 v0, v[4:7] offset:61440

; DI void topk_job(const Params& p, int b, int t0, char* lds) {
;     ...
;       __syncthreads();
;       if (w < 4) {
;         const int q = w;
;         const unsigned* hq = hist + q * 4096;
;         const int need = 256 - chi[q];
;         int G = 0;
;         if (pass < 2) {
; #pragma unroll
;           for (int rep = 0; rep < 4; ++rep)
; #pragma unroll
;             for (int j = 0; j < 16; ++j) G += (int)hq[rep * 1024 + 16 * lane + ((j + lane) & 15)];
;         } else {
; #pragma unroll 8
;           for (int j = 0; j < 64; ++j) G += (int)hq[64 * lane + ((j + lane) & 63)];
;         }
;         int S = G;
;         { int tt; S = wscan<false>(S, lane, tt); }
;         const unsigned long long mk = __ballot(S >= need);
.Ltk_p2s_83:
.Ltk_p2_done_15:
	s_waitcnt lgkmcnt(0)
	s_barrier
	s_cmp_gt_u32 s2, 3
	s_cbranch_scc1 .Ltk_scan_end_84
	s_lshl_b32 s84, s2, 14
	s_add_i32 s84, s84, 0x4000
	s_cmp_eq_u32 s56, 1
	s_cbranch_scc1 .Ltk_scan_few_85
	v_lshlrev_b32_e32 v33, 8, v101
	v_add_u32_e32 v33, s84, v33
	v_mov_b32_e32 v66, 0
	v_add_u32_e32 v0, 0, v101
	v_and_b32_e32 v0, 15, v0
	v_lshl_add_u32 v34, v0, 4, v33
	v_add_u32_e32 v0, 1, v101
	v_and_b32_e32 v0, 15, v0
	v_lshl_add_u32 v35, v0, 4, v33
	v_add_u32_e32 v0, 2, v101
	v_and_b32_e32 v0, 15, v0
	v_lshl_add_u32 v36, v0, 4, v33
	v_add_u32_e32 v0, 3, v101
	v_and_b32_e32 v0, 15, v0
	v_lshl_add_u32 v37, v0, 4, v33
	v_add_u32_e32 v0, 4, v101
	v_and_b32_e32 v0, 15, v0
	v_lshl_add_u32 v38, v0, 4, v33
	v_add_u32_e32 v0, 5, v101
	v_and_b32_e32 v0, 15, v0
	v_lshl_add_u32 v39, v0, 4, v33
	v_add_u32_e32 v0, 6, v101
	v_and_b32_e32 v0, 15, v0
	v_lshl_add_u32 v40, v0, 4, v33
	v_add_u32_e32 v0, 7, v101
	v_and_b32_e32 v0, 15, v0
	v_lshl_add_u32 v41, v0, 4, v33
	v_add_u32_e32 v0, 8, v101
	v_and_b32_e32 v0, 15, v0
	v_lshl_add_u32 v42, v0, 4, v33
	v_add_u32_e32 v0, 9, v101
	v_and_b32_e32 v0, 15, v0
	v_lshl_add_u32 v43, v0, 4, v33
	v_add_u32_e32 v0, 10, v101
	v_and_b32_e32 v0, 15, v0
	v_lshl_add_u32 v44, v0, 4, v33
	v_add_u32_e32 v0, 11, v101
	v_and_b32_e32 v0, 15, v0
	v_lshl_add_u32 v45, v0, 4, v33
	v_add_u32_e32 v0, 12, v101
	v_and_b32_e32 v0, 15, v0
	v_lshl_add_u32 v46, v0, 4, v33
	v_add_u32_e32 v0, 13, v101
	v_and_b32_e32 v0, 15, v0
	v_lshl_add_u32 v47, v0, 4, v33
	v_add_u32_e32 v0, 14, v101
	v_and_b32_e32 v0, 15, v0
	v_lshl_add_u32 v48, v0, 4, v33
	v_add_u32_e32 v0, 15, v101
	v_and_b32_e32 v0, 15, v0
	v_lshl_add_u32 v49, v0, 4, v33
	ds_read_b128 v[50:53], v34
	ds_read_b128 v[54:57], v35
	ds_read_b128 v[58:61], v36
	ds_read_b128 v[62:65], v37
	s_waitcnt lgkmcnt(0)
	v_add3_u32 v66, v66, v50, v51
	v_add3_u32 v66, v66, v52, v53
	v_add3_u32 v66, v66, v54, v55
	v_add3_u32 v66, v66, v56, v57
	v_add3_u32 v66, v66, v58, v59
	v_add3_u32 v66, v66, v60, v61
	v_add3_u32 v66, v66, v62, v63
	v_add3_u32 v66, v66, v64, v65
	ds_read_b128 v[50:53], v38
	ds_read_b128 v[54:57], v39
	ds_read_b128 v[58:61], v40
	ds_read_b128 v[62:65], v41
	s_waitcnt lgkmcnt(0)
	v_add3_u32 v66, v66, v50, v51
	v_add3_u32 v66, v66, v52, v53
	v_add3_u32 v66, v66, v54, v55
	v_add3_u32 v66, v66, v56, v57
	v_add3_u32 v66, v66, v58, v59
	v_add3_u32 v66, v66, v60, v61
	v_add3_u32 v66, v66, v62, v63
	v_add3_u32 v66, v66, v64, v65
	ds_read_b128 v[50:53], v42
	ds_read_b128 v[54:57], v43
	ds_read_b128 v[58:61], v44
	ds_read_b128 v[62:65], v45
	s_waitcnt lgkmcnt(0)
	v_add3_u32 v66, v66, v50, v51
	v_add3_u32 v66, v66, v52, v53
	v_add3_u32 v66, v66, v54, v55
	v_add3_u32 v66, v66, v56, v57
	v_add3_u32 v66, v66, v58, v59
	v_add3_u32 v66, v66, v60, v61
	v_add3_u32 v66, v66, v62, v63
	v_add3_u32 v66, v66, v64, v65
	ds_read_b128 v[50:53], v46
	ds_read_b128 v[54:57], v47
	ds_read_b128 v[58:61], v48
	ds_read_b128 v[62:65], v49
	s_waitcnt lgkmcnt(0)
	v_add3_u32 v66, v66, v50, v51
	v_add3_u32 v66, v66, v52, v53
	v_add3_u32 v66, v66, v54, v55
	v_add3_u32 v66, v66, v56, v57
	v_add3_u32 v66, v66, v58, v59
	v_add3_u32 v66, v66, v60, v61
	v_add3_u32 v66, v66, v62, v63
	v_add3_u32 v66, v66, v64, v65
	s_nop 1
	v_add_u32_dpp v68, v66, v66 quad_perm:[1,0,3,2] row_mask:0xf bank_mask:0xf bound_ctrl:1
	v_cndmask_b32_e64 v67, v66, v68, s[16:17]
	s_nop 1
	v_mov_b32_dpp v69, v68 quad_perm:[2,3,0,1] row_mask:0xf bank_mask:0xf bound_ctrl:1
	v_add_u32_e32 v68, v68, v69
	v_cndmask_b32_e64 v70, 0, v69, s[18:19]
	v_add_u32_e32 v67, v67, v70
	s_nop 0
	v_mov_b32_dpp v69, v68 row_half_mirror row_mask:0xf bank_mask:0xf bound_ctrl:1
	v_add_u32_e32 v68, v68, v69
	v_cndmask_b32_e64 v70, 0, v69, s[20:21]
	v_add_u32_e32 v67, v67, v70
	s_nop 0
	v_mov_b32_dpp v69, v68 row_mirror row_mask:0xf bank_mask:0xf bound_ctrl:1
	v_add_u32_e32 v68, v68, v69
	v_cndmask_b32_e64 v70, 0, v69, s[22:23]
	v_add_u32_e32 v67, v67, v70
	v_mov_b32_e32 v71, v68
	v_mov_b32_e32 v72, v68
	s_nop 1
	v_permlane16_swap_b32_e32 v71, v72
	v_cndmask_b32_e64 v69, v71, v72, s[24:25]
	v_add_u32_e32 v68, v68, v69
	v_cndmask_b32_e64 v70, 0, v69, s[24:25]
	v_add_u32_e32 v67, v67, v70
	v_mov_b32_e32 v71, v68
	v_mov_b32_e32 v72, v68
	s_nop 1
	v_permlane32_swap_b32_e32 v71, v72
	v_cndmask_b32_e64 v69, v71, v72, s[26:27]
	v_cndmask_b32_e64 v70, 0, v69, s[26:27]
	v_add_u32_e32 v67, v67, v70
	v_cmp_le_u32_e64 s[30:31], s85, v67
	s_cmp_eq_u64 s[30:31], 0
	s_cbranch_scc1 .Ltk_scan_few_85
	s_flbit_i32_b64 s88, s[30:31]
	s_sub_i32 s88, 63, s88
	s_mov_b32 s90, 0
	s_cmp_eq_u32 s88, 63
	s_cbranch_scc1 .Ltk_noabove_88
	s_add_i32 s4, s88, 1
	s_nop 0
	v_readlane_b32 s90, v67, s4

; __global__ void __launch_bounds__(NTHREADS) mega(Params p) {
;   extern __shared__ __attribute__((aligned(16))) char lds[];
;   cg::grid_group grid = cg::this_grid();
	.amdhsa_kernel _Z4mega6Params
		.amdhsa_group_segment_fixed_size 0
		.amdhsa_private_segment_fixed_size 0
		.amdhsa_kernarg_size 568
		.amdhsa_user_sgpr_count 2
		.amdhsa_user_sgpr_dispatch_ptr 0
		.amdhsa_user_sgpr_queue_ptr 0
		.amdhsa_user_sgpr_kernarg_segment_ptr 1
		.amdhsa_user_sgpr_dispatch_id 0
		.amdhsa_user_sgpr_kernarg_preload_length 0
		.amdhsa_user_sgpr_kernarg_preload_offset 0
		.amdhsa_user_sgpr_private_segment_size 0
		.amdhsa_uses_dynamic_stack 0
		.amdhsa_enable_private_segment 0
		.amdhsa_system_sgpr_workgroup_id_x 1
		.amdhsa_system_sgpr_workgroup_id_y 0
		.amdhsa_system_sgpr_workgroup_id_z 0
		.amdhsa_system_sgpr_workgroup_info 0
		.amdhsa_system_vgpr_workitem_id 2
		.amdhsa_next_free_vgpr 244
		.amdhsa_next_free_sgpr 102
		.amdhsa_accum_offset 244
		.amdhsa_reserve_vcc 1
		.amdhsa_float_round_mode_32 0
		.amdhsa_float_round_mode_16_64 0
		.amdhsa_float_denorm_mode_32 3
		.amdhsa_float_denorm_mode_16_64 3
		.amdhsa_dx10_clamp 1
		.amdhsa_ieee_mode 1
		.amdhsa_fp16_overflow 0
		.amdhsa_tg_split 0
		.amdhsa_exception_fp_ieee_invalid_op 0
		.amdhsa_exception_fp_denorm_src 0
		.amdhsa_exception_fp_ieee_div_zero 0
		.amdhsa_exception_fp_ieee_overflow 0
		.amdhsa_exception_fp_ieee_underflow 0
		.amdhsa_exception_fp_ieee_inexact 0
		.amdhsa_exception_int_div_zero 0
	.end_amdhsa_kernel

; __global__ void __launch_bounds__(NTHREADS) mega(Params p) {
;   extern __shared__ __attribute__((aligned(16))) char lds[];
;   cg::grid_group grid = cg::this_grid();
amdhsa.kernels:
  - .agpr_count:     0
    .args:
      - .offset:         0
        .size:           312
        .value_kind:     by_value
      - .offset:         312
        .size:           4
        .value_kind:     hidden_block_count_x
      - .offset:         316
        .size:           4
        .value_kind:     hidden_block_count_y
      - .offset:         320
        .size:           4
        .value_kind:     hidden_block_count_z
      - .offset:         324
        .size:           2
        .value_kind:     hidden_group_size_x
      - .offset:         326
        .size:           2
        .value_kind:     hidden_group_size_y
      - .offset:         328
        .size:           2
        .value_kind:     hidden_group_size_z
      - .offset:         330
        .size:           2
        .value_kind:     hidden_remainder_x
      - .offset:         332
        .size:           2
        .value_kind:     hidden_remainder_y
      - .offset:         334
        .size:           2
        .value_kind:     hidden_remainder_z
      - .offset:         352
        .size:           8
        .value_kind:     hidden_global_offset_x
      - .offset:         360
        .size:           8
        .value_kind:     hidden_global_offset_y
      - .offset:         368
        .size:           8
        .value_kind:     hidden_global_offset_z
      - .offset:         376
        .size:           2
        .value_kind:     hidden_grid_dims
      - .offset:         400
        .size:           8
        .value_kind:     hidden_multigrid_sync_arg
      - .offset:         432
        .size:           4
        .value_kind:     hidden_dynamic_lds_size
    .group_segment_fixed_size: 0
    .kernarg_segment_align: 8
    .kernarg_segment_size: 568
    .language:       OpenCL C
    .language_version:
      - 2
      - 0
    .max_flat_workgroup_size: 512
    .name:           _Z4mega6Params
    .private_segment_fixed_size: 0
    .sgpr_count:     108
    .sgpr_spill_count: 393
    .symbol:         _Z4mega6Params.kd
    .uniform_work_group_size: 1
    .uses_dynamic_stack: false
    .vgpr_count:     244
    .vgpr_spill_count: 0
    .wavefront_size: 64
